# speedup vs baseline: 1.0567x; 1.0029x over previous
; #define WAIT_V(n) asm volatile("s_waitcnt vmcnt(" #n ")" ::: "memory")
; #define BAR __builtin_amdgcn_s_barrier()
;     ...
;   const int wid = tx >> 6, lane = tx & 63, wr = wid >> 2, wc = wid & 3, fr = lane & 15, fq = lane >> 4;
;   f32x4 acc[2][2][4][2] = {};
;   bf16x8 At[4][2], B0[2][2], B1[2][2];
;   const int nt = K / BK;
;   unsigned soff0, soff1;
;   { int _r, _c; stage_rc(tx * 16, _r, _c); soff0 = (unsigned)(_r * K + _c) * 2u;
;     stage_rc(tx * 16 + 8192, _r, _c); soff1 = (unsigned)(_r * K + _c) * 2u; }
;   STAGE(SB(0, 0), Bt, bcol, 0); STAGE(SA(0, 0), A, brow, 0);
;   STAGE(SB(0, 1), Bt, bcol1, 0); STAGE(SA(0, 1), A, brow + HALF, 0);
;   if (wr == 1) BAR;
;   WAIT_V(4); BAR;
;   STAGE(SB(1, 0), Bt, bcol, 1); STAGE(SA(1, 0), A, brow, 1); STAGE(SB(1, 1), Bt, bcol1, 1);
;   WAIT_V(6); BAR;
.LBB0_68:
	s_or_b64 exec, exec, s[12:13]
	v_add_u32_e32 v155, s54, v18
	v_add_u32_e32 v156, 0x2000, v155
	v_readfirstlane_b32 s12, v155
	v_lshl_add_u64 v[10:11], v[10:11], 0, s[24:25]
	s_mov_b32 m0, s12
	v_readfirstlane_b32 s12, v156
	v_add_u32_e32 v157, 0x8000, v147
	s_waitcnt vmcnt(4)
	s_barrier
	global_load_lds_dwordx4 v[10:11], off
	v_lshl_add_u64 v[8:9], v[8:9], 0, s[24:25]
	s_mov_b32 m0, s12
	v_readfirstlane_b32 s12, v157
	v_add_u32_e32 v158, 0xa000, v147
	global_load_lds_dwordx4 v[8:9], off
	v_lshl_add_u64 v[6:7], v[6:7], 0, s[24:25]
	s_mov_b32 m0, s12
	v_readfirstlane_b32 s12, v158
	v_add_u32_e32 v159, s55, v18
	global_load_lds_dwordx4 v[6:7], off
	v_lshl_add_u64 v[4:5], v[4:5], 0, s[24:25]
	s_mov_b32 m0, s12
	v_readfirstlane_b32 s12, v159
	v_add_u32_e32 v160, 0x2000, v159
	global_load_lds_dwordx4 v[4:5], off
	v_lshl_add_u64 v[2:3], v[2:3], 0, s[24:25]
	s_mov_b32 m0, s12
	v_readfirstlane_b32 s12, v160
	global_load_lds_dwordx4 v[2:3], off
	v_lshl_add_u64 v[0:1], v[0:1], 0, s[24:25]
	s_mov_b32 m0, s12
	v_and_b32_e32 v239, 15, v142
	global_load_lds_dwordx4 v[0:1], off
	v_lshlrev_b32_e32 v1, 2, v142
	v_and_b32_e32 v237, 48, v142
	v_lshlrev_b32_e32 v0, 6, v239
	v_and_b32_e32 v1, 32, v1
	v_bitop3_b32 v0, v0, v1, v237 bitop3:0x36
	v_add_u32_e32 v5, s33, v0
	v_add_u32_e32 v6, s53, v0
	v_add_u32_e32 v7, s54, v0
	v_add_u32_e32 v8, s55, v0
	v_add_u32_e32 v10, 0, v0
	v_lshlrev_b32_e32 v0, 6, v142
	v_and_or_b32 v0, v0, s56, v237
	v_xad_u32 v11, v0, v1, 0
	v_lshlrev_b32_e32 v0, 16, v12
	v_lshlrev_b32_e32 v2, 16, v14
	v_and_b32_e32 v0, 0xfffe0000, v0
	v_and_b32_e32 v2, 0xfffe0000, v2
	v_lshl_add_u32 v0, v13, 13, v0
	v_and_b32_e32 v1, 1, v12
	v_lshl_add_u32 v2, v16, 13, v2
	v_and_b32_e32 v3, 1, v14
	v_lshl_or_b32 v0, v1, 6, v0
	s_add_u32 s8, s20, s8
	v_lshl_or_b32 v2, v3, 6, v2
	v_lshl_add_u32 v0, v15, 1, v0
	v_mov_b32_e32 v1, v185
	s_addc_u32 s9, s21, s9
	v_lshl_add_u32 v2, v17, 1, v2
	v_mov_b32_e32 v3, v185
	v_lshl_add_u64 v[130:131], s[8:9], 0, v[0:1]
	v_lshl_add_u64 v[132:133], s[8:9], 0, v[2:3]
	s_add_u32 s8, s18, s10
	v_bfe_u32 v236, v143, 6, 2
	s_waitcnt vmcnt(6)
	v_lshlrev_b32_e32 v9, 13, v238
	s_addc_u32 s9, s19, s11
	v_lshlrev_b32_e32 v4, 12, v236
	v_or_b32_e32 v18, 0x800, v9
	v_or_b32_e32 v19, 0x1000, v9
	v_or_b32_e32 v20, 0x1800, v9
	v_lshl_add_u64 v[134:135], s[8:9], 0, v[0:1]
	v_mov_b32_e32 v0, 0
	v_lshlrev_b32_e32 v138, 6, v238
	v_lshl_add_u64 v[136:137], s[8:9], 0, v[2:3]
	s_mov_b32 s10, -2
	s_mov_b64 s[8:9], 0
	v_add_u32_e32 v162, v5, v4
	v_add_u32_e32 v144, v10, v9
	v_add_u32_e32 v141, v11, v18
	v_add_u32_e32 v140, v11, v19
	v_add_u32_e32 v139, v11, v20
	v_add_u32_e32 v161, v6, v4
	v_add_u32_e32 v152, v7, v4
	v_add_u32_e32 v148, v8, v4
	v_mov_b32_e32 v1, v0
	v_mov_b32_e32 v2, v0
	v_mov_b32_e32 v3, v0
	v_mov_b32_e32 v4, v0
	v_mov_b32_e32 v5, v0
	v_mov_b32_e32 v6, v0
	v_mov_b32_e32 v7, v0
	v_mov_b32_e32 v8, v0
	v_mov_b32_e32 v9, v0
	v_mov_b32_e32 v10, v0
	v_mov_b32_e32 v11, v0
	v_mov_b32_e32 v12, v0
	v_mov_b32_e32 v13, v0
	v_mov_b32_e32 v14, v0
	v_mov_b32_e32 v15, v0
	v_mov_b32_e32 v16, v0
	v_mov_b32_e32 v17, v0
	v_mov_b32_e32 v18, v0
	v_mov_b32_e32 v19, v0
	v_mov_b32_e32 v20, v0
	v_mov_b32_e32 v21, v0
	v_mov_b32_e32 v22, v0
	v_mov_b32_e32 v23, v0
	v_mov_b32_e32 v24, v0
	v_mov_b32_e32 v25, v0
	v_mov_b32_e32 v26, v0
	v_mov_b32_e32 v27, v0
	v_mov_b32_e32 v28, v0
	v_mov_b32_e32 v29, v0
	v_mov_b32_e32 v30, v0
	v_mov_b32_e32 v31, v0
	v_mov_b32_e32 v32, v0
	v_mov_b32_e32 v33, v0
	v_mov_b32_e32 v34, v0
	v_mov_b32_e32 v35, v0
	v_mov_b32_e32 v36, v0
	v_mov_b32_e32 v37, v0
	v_mov_b32_e32 v38, v0
	v_mov_b32_e32 v39, v0
	v_mov_b32_e32 v40, v0
	v_mov_b32_e32 v41, v0
	v_mov_b32_e32 v42, v0
	v_mov_b32_e32 v43, v0
	v_mov_b32_e32 v44, v0
	v_mov_b32_e32 v45, v0
	v_mov_b32_e32 v46, v0
	v_mov_b32_e32 v47, v0
	v_mov_b32_e32 v48, v0
	v_mov_b32_e32 v49, v0
	v_mov_b32_e32 v50, v0
	v_mov_b32_e32 v51, v0
	v_mov_b32_e32 v52, v0
	v_mov_b32_e32 v53, v0
	v_mov_b32_e32 v54, v0
	v_mov_b32_e32 v55, v0
	v_mov_b32_e32 v56, v0
	v_mov_b32_e32 v57, v0
	v_mov_b32_e32 v58, v0
	v_mov_b32_e32 v59, v0
	v_mov_b32_e32 v60, v0
	v_mov_b32_e32 v61, v0
	v_mov_b32_e32 v62, v0
	v_mov_b32_e32 v63, v0
	v_mov_b32_e32 v64, v0
	v_mov_b32_e32 v65, v0
	v_mov_b32_e32 v66, v0
	v_mov_b32_e32 v67, v0
	v_mov_b32_e32 v68, v0
	v_mov_b32_e32 v69, v0
	v_mov_b32_e32 v70, v0
	v_mov_b32_e32 v71, v0
	v_mov_b32_e32 v72, v0
	v_mov_b32_e32 v73, v0
	v_mov_b32_e32 v74, v0
	v_mov_b32_e32 v75, v0
	v_mov_b32_e32 v76, v0
	v_mov_b32_e32 v77, v0
	v_mov_b32_e32 v78, v0
	v_mov_b32_e32 v79, v0
	v_mov_b32_e32 v80, v0
	v_mov_b32_e32 v81, v0
	v_mov_b32_e32 v82, v0
	v_mov_b32_e32 v83, v0
	v_mov_b32_e32 v84, v0
	v_mov_b32_e32 v85, v0
	v_mov_b32_e32 v86, v0
	v_mov_b32_e32 v87, v0
	v_mov_b32_e32 v88, v0
	v_mov_b32_e32 v89, v0
	v_mov_b32_e32 v90, v0
	v_mov_b32_e32 v91, v0
	v_mov_b32_e32 v92, v0
	v_mov_b32_e32 v93, v0
	v_mov_b32_e32 v94, v0
	v_mov_b32_e32 v95, v0
	v_mov_b32_e32 v96, v0
	v_mov_b32_e32 v97, v0
	v_mov_b32_e32 v98, v0
	v_mov_b32_e32 v99, v0
	v_mov_b32_e32 v100, v0
	v_mov_b32_e32 v101, v0
	v_mov_b32_e32 v102, v0
	v_mov_b32_e32 v103, v0
	v_mov_b32_e32 v104, v0
	v_mov_b32_e32 v105, v0
	v_mov_b32_e32 v106, v0
	v_mov_b32_e32 v107, v0
	v_mov_b32_e32 v108, v0
	v_mov_b32_e32 v109, v0
	v_mov_b32_e32 v110, v0
	v_mov_b32_e32 v111, v0
	v_mov_b32_e32 v112, v0
	v_mov_b32_e32 v113, v0
	v_mov_b32_e32 v114, v0
	v_mov_b32_e32 v115, v0
	v_mov_b32_e32 v116, v0
	v_mov_b32_e32 v117, v0
	v_mov_b32_e32 v118, v0
	v_mov_b32_e32 v119, v0
	v_mov_b32_e32 v120, v0
	v_mov_b32_e32 v121, v0
	v_mov_b32_e32 v122, v0
	v_mov_b32_e32 v123, v0
	v_mov_b32_e32 v124, v0
	v_mov_b32_e32 v125, v0
	v_mov_b32_e32 v126, v0
	v_mov_b32_e32 v127, v0
	v_or_b32_e32 v235, v138, v239
	s_barrier
; #define WAIT_L(n) asm volatile("s_waitcnt lgkmcnt(" #n ")" ::: "memory")
; #define BAR __builtin_amdgcn_s_barrier()
; #define SCHED __builtin_amdgcn_sched_barrier(0)
;     ...
;   for (int t = 0; t < nt - 2; t += 2) {
;     LDB(B0, 0, 0); SCHED; LDA(At, 0, 0); STAGE(SA(1, 1), A, brow + HALF, t + 1);
;     WAIT_L(8); BAR; WAIT_L(0); MMA(0, 0, At, B0); BAR; SCHED;
	v_readfirstlane_b32 s11, v147
	v_writelane_b32 v254, s64, 0
	v_writelane_b32 v254, s65, 1
	v_writelane_b32 v254, s66, 2
	v_writelane_b32 v254, s67, 3
	v_writelane_b32 v254, s68, 4
	v_writelane_b32 v254, s69, 5
	v_writelane_b32 v254, s70, 6
	v_writelane_b32 v254, s71, 7
	v_writelane_b32 v254, s72, 8
	v_writelane_b32 v254, s73, 9
	v_writelane_b32 v254, s74, 10
	v_writelane_b32 v254, s75, 11
	v_writelane_b32 v254, s76, 12
	v_writelane_b32 v254, s77, 13
	v_writelane_b32 v254, s78, 14
	v_writelane_b32 v254, s79, 15
	v_writelane_b32 v254, s80, 16
	v_writelane_b32 v254, s81, 17
	v_writelane_b32 v254, s82, 18
	v_writelane_b32 v254, s83, 19
	v_writelane_b32 v254, s84, 20
	v_writelane_b32 v254, s85, 21
	v_writelane_b32 v254, s86, 22
	v_writelane_b32 v254, s87, 23
	v_writelane_b32 v254, s88, 24
	v_writelane_b32 v254, s89, 25
	v_writelane_b32 v254, s90, 26
	v_writelane_b32 v254, s91, 27
	v_writelane_b32 v254, s92, 28
	v_writelane_b32 v254, s93, 29
	v_writelane_b32 v254, s94, 30
	v_writelane_b32 v254, s95, 31
	v_readfirstlane_b32 s64, v134
	v_readfirstlane_b32 s65, v135
	v_readfirstlane_b32 s66, v136
	v_readfirstlane_b32 s67, v137
	v_readfirstlane_b32 s68, v130
	v_readfirstlane_b32 s69, v131
	v_readfirstlane_b32 s70, v132
	v_readfirstlane_b32 s71, v133
	v_readfirstlane_b32 s72, v134
	v_readfirstlane_b32 s73, v135
	v_readfirstlane_b32 s74, v136
	v_readfirstlane_b32 s75, v137
	v_readfirstlane_b32 s76, v130
	v_readfirstlane_b32 s77, v131
	v_readfirstlane_b32 s78, v132
	v_readfirstlane_b32 s79, v133
	v_readfirstlane_b32 s80, v134
	v_readfirstlane_b32 s81, v135
	v_readfirstlane_b32 s82, v136
	v_readfirstlane_b32 s83, v137
	v_readfirstlane_b32 s84, v130
	v_readfirstlane_b32 s85, v131
	v_readfirstlane_b32 s86, v132
	v_readfirstlane_b32 s87, v133
	v_readfirstlane_b32 s88, v134
	v_readfirstlane_b32 s89, v135
	v_readfirstlane_b32 s90, v136
	v_readfirstlane_b32 s91, v137
	v_readfirstlane_b32 s92, v130
	v_readfirstlane_b32 s93, v131
	v_readfirstlane_b32 s94, v132
	v_readfirstlane_b32 s95, v133
	s_nop 3
	v_subrev_u32_e32 v151, s64, v134
	v_subrev_u32_e32 v153, s66, v136
	v_subrev_u32_e32 v149, s68, v130
	v_subrev_u32_e32 v150, s70, v132
	s_add_u32 s64, s64, s8
	s_addc_u32 s65, s65, s9
	s_add_u32 s64, s64, s26
	s_addc_u32 s65, s65, s27
	s_add_u32 s66, s66, s8
	s_addc_u32 s67, s67, s9
	s_add_u32 s66, s66, s26
	s_addc_u32 s67, s67, s27
	s_add_u32 s68, s68, s8
	s_addc_u32 s69, s69, s9
	s_add_u32 s68, s68, s28
	s_addc_u32 s69, s69, s29
	s_add_u32 s70, s70, s8
	s_addc_u32 s71, s71, s9
	s_add_u32 s70, s70, s28
	s_addc_u32 s71, s71, s29
	s_add_u32 s72, s72, s8
	s_addc_u32 s73, s73, s9
	s_add_u32 s72, s72, s28
	s_addc_u32 s73, s73, s29
	s_add_u32 s74, s74, s8
	s_addc_u32 s75, s75, s9
	s_add_u32 s74, s74, s28
	s_addc_u32 s75, s75, s29
	s_add_u32 s76, s76, s8
	s_addc_u32 s77, s77, s9
	s_add_u32 s76, s76, s30
	s_addc_u32 s77, s77, s31
	s_add_u32 s78, s78, s8
	s_addc_u32 s79, s79, s9
	s_add_u32 s78, s78, s30
	s_addc_u32 s79, s79, s31
	s_add_u32 s80, s80, s8
	s_addc_u32 s81, s81, s9
	s_add_u32 s80, s80, s30
	s_addc_u32 s81, s81, s31
	s_add_u32 s82, s82, s8
	s_addc_u32 s83, s83, s9
	s_add_u32 s82, s82, s30
	s_addc_u32 s83, s83, s31
	s_add_u32 s84, s84, s8
	s_addc_u32 s85, s85, s9
	s_add_u32 s84, s84, s34
	s_addc_u32 s85, s85, s35
	s_add_u32 s86, s86, s8
	s_addc_u32 s87, s87, s9
	s_add_u32 s86, s86, s34
	s_addc_u32 s87, s87, s35
	s_add_u32 s88, s88, s8
	s_addc_u32 s89, s89, s9
	s_add_u32 s88, s88, s34
	s_addc_u32 s89, s89, s35
	s_add_u32 s90, s90, s8
	s_addc_u32 s91, s91, s9
	s_add_u32 s90, s90, s34
	s_addc_u32 s91, s91, s35
	s_add_u32 s92, s92, s8
	s_addc_u32 s93, s93, s9
	s_add_u32 s92, s92, s36
	s_addc_u32 s93, s93, s37
	s_add_u32 s94, s94, s8
	s_addc_u32 s95, s95, s9
	s_add_u32 s94, s94, s36
	s_addc_u32 s95, s95, s37
	v_add_u32_e32 v163, 0xc000, v147
	v_add_u32_e32 v164, 0xe000, v147
.LBB0_69:
	ds_read_b128 v[166:169], v162
	ds_read_b128 v[170:173], v162 offset:1024
	ds_read_b128 v[174:177], v162 offset:2048
	ds_read_b128 v[178:181], v162 offset:3072
	s_add_u32 m0, s11, 0xc000
	ds_read_b128 v[186:189], v144
	ds_read_b128 v[190:193], v144 offset:1024
	ds_read_b128 v[194:197], v141
	ds_read_b128 v[198:201], v141 offset:1024
	ds_read_b128 v[202:205], v140
	ds_read_b128 v[206:209], v140 offset:1024
	ds_read_b128 v[210:213], v139
	ds_read_b128 v[214:217], v139 offset:1024
	global_load_lds_dwordx4 v151, s[64:65]
	s_add_u32 s64, s64, 0x100
	s_addc_u32 s65, s65, 0
	s_add_u32 m0, s11, 0xe000
	s_nop 0
	global_load_lds_dwordx4 v153, s[66:67]
	s_add_u32 s66, s66, 0x100
	s_addc_u32 s67, s67, 0
	s_waitcnt lgkmcnt(8)
	s_barrier
	s_waitcnt lgkmcnt(0)
	v_mfma_f32_16x16x32_bf16 v[124:127], v[166:169], v[186:189], v[124:127]
	v_mfma_f32_16x16x32_bf16 v[120:123], v[174:177], v[186:189], v[120:123]
	v_mfma_f32_16x16x32_bf16 v[116:119], v[166:169], v[194:197], v[116:119]
	v_mfma_f32_16x16x32_bf16 v[112:115], v[174:177], v[194:197], v[112:115]
	v_mfma_f32_16x16x32_bf16 v[108:111], v[166:169], v[202:205], v[108:111]
	v_mfma_f32_16x16x32_bf16 v[104:107], v[174:177], v[202:205], v[104:107]
	v_mfma_f32_16x16x32_bf16 v[100:103], v[166:169], v[210:213], v[100:103]
	v_mfma_f32_16x16x32_bf16 v[96:99], v[174:177], v[210:213], v[96:99]
	v_mfma_f32_16x16x32_bf16 v[124:127], v[170:173], v[190:193], v[124:127]
	v_mfma_f32_16x16x32_bf16 v[120:123], v[178:181], v[190:193], v[120:123]
	v_mfma_f32_16x16x32_bf16 v[116:119], v[170:173], v[198:201], v[116:119]
	v_mfma_f32_16x16x32_bf16 v[112:115], v[178:181], v[198:201], v[112:115]
	v_mfma_f32_16x16x32_bf16 v[108:111], v[170:173], v[206:209], v[108:111]
	v_mfma_f32_16x16x32_bf16 v[104:107], v[178:181], v[206:209], v[104:107]
	v_mfma_f32_16x16x32_bf16 v[100:103], v[170:173], v[214:217], v[100:103]
	v_mfma_f32_16x16x32_bf16 v[96:99], v[178:181], v[214:217], v[96:99]
	s_barrier
; #define WAIT_V(n) asm volatile("s_waitcnt vmcnt(" #n ")" ::: "memory")
; #define WAIT_L(n) asm volatile("s_waitcnt lgkmcnt(" #n ")" ::: "memory")
; #define BAR __builtin_amdgcn_s_barrier()
; #define SCHED __builtin_amdgcn_sched_barrier(0)
;     ...
;     LDB(B1, 0, 1); STAGE(SB(0, 0), Bt, bcol, t + 2);
;     BAR; WAIT_L(0); MMA(0, 1, At, B1); BAR;
;     LDA(At, 0, 1); STAGE(SA(0, 0), A, brow, t + 2);
;     BAR; WAIT_L(0); MMA(1, 0, At, B0); BAR; SCHED;
;     STAGE(SB(0, 1), Bt, bcol1, t + 2);
;     WAIT_V(6); BAR; MMA(1, 1, At, B1); BAR;
;     LDB(B0, 1, 0); SCHED; LDA(At, 1, 0); STAGE(SA(0, 1), A, brow + HALF, t + 2);
;     WAIT_L(8); BAR; WAIT_L(0); MMA(0, 0, At, B0); BAR; SCHED;
	s_add_u32 m0, s11, s33
	ds_read_b128 v[218:221], v161
	ds_read_b128 v[222:225], v161 offset:1024
	ds_read_b128 v[226:229], v161 offset:2048
	ds_read_b128 v[240:243], v161 offset:3072
	global_load_lds_dwordx4 v149, s[68:69]
	s_add_u32 s68, s68, 0x100
	s_addc_u32 s69, s69, 0
	s_add_u32 m0, s11, 0x2000
	s_add_u32 m0, m0, s33
	s_nop 0
	global_load_lds_dwordx4 v150, s[70:71]
	s_add_u32 s70, s70, 0x100
	s_addc_u32 s71, s71, 0
	s_barrier
	s_waitcnt lgkmcnt(0)
	v_mfma_f32_16x16x32_bf16 v[92:95], v[218:221], v[186:189], v[92:95]
	v_mfma_f32_16x16x32_bf16 v[88:91], v[226:229], v[186:189], v[88:91]
	v_mfma_f32_16x16x32_bf16 v[84:87], v[218:221], v[194:197], v[84:87]
	v_mfma_f32_16x16x32_bf16 v[80:83], v[226:229], v[194:197], v[80:83]
	v_mfma_f32_16x16x32_bf16 v[76:79], v[218:221], v[202:205], v[76:79]
	v_mfma_f32_16x16x32_bf16 v[72:75], v[226:229], v[202:205], v[72:75]
	v_mfma_f32_16x16x32_bf16 v[68:71], v[218:221], v[210:213], v[68:71]
	v_mfma_f32_16x16x32_bf16 v[64:67], v[226:229], v[210:213], v[64:67]
	v_mfma_f32_16x16x32_bf16 v[92:95], v[222:225], v[190:193], v[92:95]
	v_mfma_f32_16x16x32_bf16 v[88:91], v[240:243], v[190:193], v[88:91]
	v_mfma_f32_16x16x32_bf16 v[84:87], v[222:225], v[198:201], v[84:87]
	v_mfma_f32_16x16x32_bf16 v[80:83], v[240:243], v[198:201], v[80:83]
	v_mfma_f32_16x16x32_bf16 v[76:79], v[222:225], v[206:209], v[76:79]
	v_mfma_f32_16x16x32_bf16 v[72:75], v[240:243], v[206:209], v[72:75]
	v_mfma_f32_16x16x32_bf16 v[68:71], v[222:225], v[214:217], v[68:71]
	v_mfma_f32_16x16x32_bf16 v[64:67], v[240:243], v[214:217], v[64:67]
	s_mov_b32 m0, s11
	s_barrier
	ds_read_b128 v[186:189], v144 offset:16384
	ds_read_b128 v[190:193], v144 offset:17408
	ds_read_b128 v[194:197], v141 offset:16384
	ds_read_b128 v[198:201], v141 offset:17408
	ds_read_b128 v[202:205], v140 offset:16384
	ds_read_b128 v[206:209], v140 offset:17408
	ds_read_b128 v[210:213], v139 offset:16384
	ds_read_b128 v[214:217], v139 offset:17408
	global_load_lds_dwordx4 v151, s[72:73]
	s_add_u32 s72, s72, 0x100
	s_addc_u32 s73, s73, 0
	s_add_u32 m0, s11, 0x2000
	s_nop 0
	global_load_lds_dwordx4 v153, s[74:75]
	s_add_u32 s74, s74, 0x100
	s_addc_u32 s75, s75, 0
	s_barrier
	s_waitcnt lgkmcnt(0)
	v_mfma_f32_16x16x32_bf16 v[60:63], v[166:169], v[186:189], v[60:63]
	v_mfma_f32_16x16x32_bf16 v[56:59], v[174:177], v[186:189], v[56:59]
	v_mfma_f32_16x16x32_bf16 v[52:55], v[166:169], v[194:197], v[52:55]
	v_mfma_f32_16x16x32_bf16 v[48:51], v[174:177], v[194:197], v[48:51]
	v_mfma_f32_16x16x32_bf16 v[44:47], v[166:169], v[202:205], v[44:47]
	v_mfma_f32_16x16x32_bf16 v[40:43], v[174:177], v[202:205], v[40:43]
	v_mfma_f32_16x16x32_bf16 v[36:39], v[166:169], v[210:213], v[36:39]
	v_mfma_f32_16x16x32_bf16 v[32:35], v[174:177], v[210:213], v[32:35]
	v_mfma_f32_16x16x32_bf16 v[60:63], v[170:173], v[190:193], v[60:63]
	v_mfma_f32_16x16x32_bf16 v[56:59], v[178:181], v[190:193], v[56:59]
	v_mfma_f32_16x16x32_bf16 v[52:55], v[170:173], v[198:201], v[52:55]
	v_mfma_f32_16x16x32_bf16 v[48:51], v[178:181], v[198:201], v[48:51]
	v_mfma_f32_16x16x32_bf16 v[44:47], v[170:173], v[206:209], v[44:47]
	v_mfma_f32_16x16x32_bf16 v[40:43], v[178:181], v[206:209], v[40:43]
	v_mfma_f32_16x16x32_bf16 v[36:39], v[170:173], v[214:217], v[36:39]
	v_mfma_f32_16x16x32_bf16 v[32:35], v[178:181], v[214:217], v[32:35]
	s_barrier
	s_add_u32 m0, s11, s53
	s_nop 0
	global_load_lds_dwordx4 v149, s[76:77]
	s_add_u32 s76, s76, 0x100
	s_addc_u32 s77, s77, 0
	s_add_u32 m0, s11, 0x2000
	s_add_u32 m0, m0, s53
	s_nop 0
	global_load_lds_dwordx4 v150, s[78:79]
	s_add_u32 s78, s78, 0x100
	s_addc_u32 s79, s79, 0
	s_waitcnt vmcnt(6)
	s_barrier
	v_mfma_f32_16x16x32_bf16 v[28:31], v[218:221], v[186:189], v[28:31]
	v_mfma_f32_16x16x32_bf16 v[24:27], v[226:229], v[186:189], v[24:27]
	v_mfma_f32_16x16x32_bf16 v[20:23], v[218:221], v[194:197], v[20:23]
	v_mfma_f32_16x16x32_bf16 v[16:19], v[226:229], v[194:197], v[16:19]
	v_mfma_f32_16x16x32_bf16 v[12:15], v[218:221], v[202:205], v[12:15]
	v_mfma_f32_16x16x32_bf16 v[8:11], v[226:229], v[202:205], v[8:11]
	v_mfma_f32_16x16x32_bf16 v[4:7], v[218:221], v[210:213], v[4:7]
	v_mfma_f32_16x16x32_bf16 v[0:3], v[226:229], v[210:213], v[0:3]
	v_mfma_f32_16x16x32_bf16 v[28:31], v[222:225], v[190:193], v[28:31]
	v_mfma_f32_16x16x32_bf16 v[24:27], v[240:243], v[190:193], v[24:27]
	v_mfma_f32_16x16x32_bf16 v[20:23], v[222:225], v[198:201], v[20:23]
	v_mfma_f32_16x16x32_bf16 v[16:19], v[240:243], v[198:201], v[16:19]
	v_mfma_f32_16x16x32_bf16 v[12:15], v[222:225], v[206:209], v[12:15]
	v_mfma_f32_16x16x32_bf16 v[8:11], v[240:243], v[206:209], v[8:11]
	v_mfma_f32_16x16x32_bf16 v[4:7], v[222:225], v[214:217], v[4:7]
	v_mfma_f32_16x16x32_bf16 v[0:3], v[240:243], v[214:217], v[0:3]
	s_barrier
	ds_read_b128 v[166:169], v152
	ds_read_b128 v[170:173], v152 offset:1024
	ds_read_b128 v[174:177], v152 offset:2048
	ds_read_b128 v[178:181], v152 offset:3072
	s_add_u32 m0, s11, 0x4000
	ds_read_b128 v[186:189], v144 offset:32768
	ds_read_b128 v[190:193], v144 offset:33792
	ds_read_b128 v[194:197], v141 offset:32768
	ds_read_b128 v[198:201], v141 offset:33792
	ds_read_b128 v[202:205], v140 offset:32768
	ds_read_b128 v[206:209], v140 offset:33792
	ds_read_b128 v[210:213], v139 offset:32768
	ds_read_b128 v[214:217], v139 offset:33792
	global_load_lds_dwordx4 v151, s[80:81]
	s_add_u32 s80, s80, 0x100
	s_addc_u32 s81, s81, 0
	s_add_u32 m0, s11, 0x6000
	s_nop 0
	global_load_lds_dwordx4 v153, s[82:83]
	s_add_u32 s82, s82, 0x100
	s_addc_u32 s83, s83, 0
	s_waitcnt lgkmcnt(8)
	s_barrier
; #define WAIT_V(n) asm volatile("s_waitcnt vmcnt(" #n ")" ::: "memory")
; #define WAIT_L(n) asm volatile("s_waitcnt lgkmcnt(" #n ")" ::: "memory")
; #define BAR __builtin_amdgcn_s_barrier()
; #define SCHED __builtin_amdgcn_sched_barrier(0)
;     ...
;     WAIT_L(8); BAR; WAIT_L(0); MMA(0, 0, At, B0); BAR; SCHED;
;     LDB(B1, 1, 1); STAGE(SB(1, 0), Bt, bcol, t + 3);
;     BAR; WAIT_L(0); MMA(0, 1, At, B1); BAR;
;     LDA(At, 1, 1); STAGE(SA(1, 0), A, brow, t + 3);
;     BAR; WAIT_L(0); MMA(1, 0, At, B0); BAR; SCHED;
;     STAGE(SB(1, 1), Bt, bcol1, t + 3);
;     WAIT_V(6); BAR; MMA(1, 1, At, B1); BAR;
	s_waitcnt lgkmcnt(0)
	v_mfma_f32_16x16x32_bf16 v[124:127], v[166:169], v[186:189], v[124:127]
	v_mfma_f32_16x16x32_bf16 v[120:123], v[174:177], v[186:189], v[120:123]
	v_mfma_f32_16x16x32_bf16 v[116:119], v[166:169], v[194:197], v[116:119]
	v_mfma_f32_16x16x32_bf16 v[112:115], v[174:177], v[194:197], v[112:115]
	v_mfma_f32_16x16x32_bf16 v[108:111], v[166:169], v[202:205], v[108:111]
	v_mfma_f32_16x16x32_bf16 v[104:107], v[174:177], v[202:205], v[104:107]
	v_mfma_f32_16x16x32_bf16 v[100:103], v[166:169], v[210:213], v[100:103]
	v_mfma_f32_16x16x32_bf16 v[96:99], v[174:177], v[210:213], v[96:99]
	v_mfma_f32_16x16x32_bf16 v[124:127], v[170:173], v[190:193], v[124:127]
	v_mfma_f32_16x16x32_bf16 v[120:123], v[178:181], v[190:193], v[120:123]
	v_mfma_f32_16x16x32_bf16 v[116:119], v[170:173], v[198:201], v[116:119]
	v_mfma_f32_16x16x32_bf16 v[112:115], v[178:181], v[198:201], v[112:115]
	v_mfma_f32_16x16x32_bf16 v[108:111], v[170:173], v[206:209], v[108:111]
	v_mfma_f32_16x16x32_bf16 v[104:107], v[178:181], v[206:209], v[104:107]
	v_mfma_f32_16x16x32_bf16 v[100:103], v[170:173], v[214:217], v[100:103]
	v_mfma_f32_16x16x32_bf16 v[96:99], v[178:181], v[214:217], v[96:99]
	s_barrier
	s_add_u32 m0, s11, s54
	ds_read_b128 v[218:221], v148
	ds_read_b128 v[222:225], v148 offset:1024
	ds_read_b128 v[226:229], v148 offset:2048
	ds_read_b128 v[240:243], v148 offset:3072
	global_load_lds_dwordx4 v149, s[84:85]
	s_add_u32 s84, s84, 0x100
	s_addc_u32 s85, s85, 0
	s_add_u32 m0, s11, 0x2000
	s_add_u32 m0, m0, s54
	s_nop 0
	global_load_lds_dwordx4 v150, s[86:87]
	s_add_u32 s86, s86, 0x100
	s_addc_u32 s87, s87, 0
	s_barrier
	s_waitcnt lgkmcnt(0)
	v_mfma_f32_16x16x32_bf16 v[92:95], v[218:221], v[186:189], v[92:95]
	v_mfma_f32_16x16x32_bf16 v[88:91], v[226:229], v[186:189], v[88:91]
	v_mfma_f32_16x16x32_bf16 v[84:87], v[218:221], v[194:197], v[84:87]
	v_mfma_f32_16x16x32_bf16 v[80:83], v[226:229], v[194:197], v[80:83]
	v_mfma_f32_16x16x32_bf16 v[76:79], v[218:221], v[202:205], v[76:79]
	v_mfma_f32_16x16x32_bf16 v[72:75], v[226:229], v[202:205], v[72:75]
	v_mfma_f32_16x16x32_bf16 v[68:71], v[218:221], v[210:213], v[68:71]
	v_mfma_f32_16x16x32_bf16 v[64:67], v[226:229], v[210:213], v[64:67]
	v_mfma_f32_16x16x32_bf16 v[92:95], v[222:225], v[190:193], v[92:95]
	v_mfma_f32_16x16x32_bf16 v[88:91], v[240:243], v[190:193], v[88:91]
	v_mfma_f32_16x16x32_bf16 v[84:87], v[222:225], v[198:201], v[84:87]
	v_mfma_f32_16x16x32_bf16 v[80:83], v[240:243], v[198:201], v[80:83]
	v_mfma_f32_16x16x32_bf16 v[76:79], v[222:225], v[206:209], v[76:79]
	v_mfma_f32_16x16x32_bf16 v[72:75], v[240:243], v[206:209], v[72:75]
	v_mfma_f32_16x16x32_bf16 v[68:71], v[222:225], v[214:217], v[68:71]
	v_mfma_f32_16x16x32_bf16 v[64:67], v[240:243], v[214:217], v[64:67]
	s_add_u32 m0, s11, 0x8000
	s_barrier
	ds_read_b128 v[186:189], v144 offset:49152
	ds_read_b128 v[190:193], v144 offset:50176
	ds_read_b128 v[194:197], v141 offset:49152
	ds_read_b128 v[198:201], v141 offset:50176
	ds_read_b128 v[202:205], v140 offset:49152
	ds_read_b128 v[206:209], v140 offset:50176
	ds_read_b128 v[210:213], v139 offset:49152
	ds_read_b128 v[214:217], v139 offset:50176
	global_load_lds_dwordx4 v151, s[88:89]
	s_add_u32 s88, s88, 0x100
	s_addc_u32 s89, s89, 0
	s_add_u32 m0, s11, 0xa000
	s_nop 0
	global_load_lds_dwordx4 v153, s[90:91]
	s_add_u32 s90, s90, 0x100
	s_addc_u32 s91, s91, 0
	s_barrier
	s_waitcnt lgkmcnt(0)
	v_mfma_f32_16x16x32_bf16 v[60:63], v[166:169], v[186:189], v[60:63]
	v_mfma_f32_16x16x32_bf16 v[56:59], v[174:177], v[186:189], v[56:59]
	v_mfma_f32_16x16x32_bf16 v[52:55], v[166:169], v[194:197], v[52:55]
	v_mfma_f32_16x16x32_bf16 v[48:51], v[174:177], v[194:197], v[48:51]
	v_mfma_f32_16x16x32_bf16 v[44:47], v[166:169], v[202:205], v[44:47]
	v_mfma_f32_16x16x32_bf16 v[40:43], v[174:177], v[202:205], v[40:43]
	v_mfma_f32_16x16x32_bf16 v[36:39], v[166:169], v[210:213], v[36:39]
	v_mfma_f32_16x16x32_bf16 v[32:35], v[174:177], v[210:213], v[32:35]
	v_mfma_f32_16x16x32_bf16 v[60:63], v[170:173], v[190:193], v[60:63]
	v_mfma_f32_16x16x32_bf16 v[56:59], v[178:181], v[190:193], v[56:59]
	v_mfma_f32_16x16x32_bf16 v[52:55], v[170:173], v[198:201], v[52:55]
	v_mfma_f32_16x16x32_bf16 v[48:51], v[178:181], v[198:201], v[48:51]
	v_mfma_f32_16x16x32_bf16 v[44:47], v[170:173], v[206:209], v[44:47]
	v_mfma_f32_16x16x32_bf16 v[40:43], v[178:181], v[206:209], v[40:43]
	v_mfma_f32_16x16x32_bf16 v[36:39], v[170:173], v[214:217], v[36:39]
	v_mfma_f32_16x16x32_bf16 v[32:35], v[178:181], v[214:217], v[32:35]
	s_barrier
	s_add_u32 m0, s11, s55
	s_nop 0
	global_load_lds_dwordx4 v149, s[92:93]
	s_add_u32 s92, s92, 0x100
	s_addc_u32 s93, s93, 0
	s_add_u32 m0, s11, 0x2000
	s_add_u32 m0, m0, s55
	s_nop 0
	global_load_lds_dwordx4 v150, s[94:95]
	s_add_u32 s94, s94, 0x100
	s_addc_u32 s95, s95, 0
	s_waitcnt vmcnt(6)
	s_barrier
	v_mfma_f32_16x16x32_bf16 v[28:31], v[218:221], v[186:189], v[28:31]
	v_mfma_f32_16x16x32_bf16 v[24:27], v[226:229], v[186:189], v[24:27]
	v_mfma_f32_16x16x32_bf16 v[20:23], v[218:221], v[194:197], v[20:23]
	v_mfma_f32_16x16x32_bf16 v[16:19], v[226:229], v[194:197], v[16:19]
	v_mfma_f32_16x16x32_bf16 v[12:15], v[218:221], v[202:205], v[12:15]
	v_mfma_f32_16x16x32_bf16 v[8:11], v[226:229], v[202:205], v[8:11]
	v_mfma_f32_16x16x32_bf16 v[4:7], v[218:221], v[210:213], v[4:7]
	v_mfma_f32_16x16x32_bf16 v[0:3], v[226:229], v[210:213], v[0:3]
	v_mfma_f32_16x16x32_bf16 v[28:31], v[222:225], v[190:193], v[28:31]
	v_mfma_f32_16x16x32_bf16 v[24:27], v[240:243], v[190:193], v[24:27]
	v_mfma_f32_16x16x32_bf16 v[20:23], v[222:225], v[198:201], v[20:23]
	v_mfma_f32_16x16x32_bf16 v[16:19], v[240:243], v[198:201], v[16:19]
	v_mfma_f32_16x16x32_bf16 v[12:15], v[222:225], v[206:209], v[12:15]
	v_mfma_f32_16x16x32_bf16 v[8:11], v[240:243], v[206:209], v[8:11]
	v_mfma_f32_16x16x32_bf16 v[4:7], v[222:225], v[214:217], v[4:7]
	v_mfma_f32_16x16x32_bf16 v[0:3], v[240:243], v[214:217], v[0:3]
	s_add_i32 s10, s10, 2
	s_add_u32 s8, s8, 0x100
	s_addc_u32 s9, s9, 0
	s_cmp_lt_u32 s10, 60
	s_barrier
; #define WAIT_V(n) asm volatile("s_waitcnt vmcnt(" #n ")" ::: "memory")
; #define WAIT_L(n) asm volatile("s_waitcnt lgkmcnt(" #n ")" ::: "memory")
; #define BAR __builtin_amdgcn_s_barrier()
;     ...
;   { LDB(B0, 0, 0); LDA(At, 0, 0); STAGE(SA(1, 1), A, brow + HALF, nt - 1);
;     BAR; WAIT_L(0); MMA(0, 0, At, B0); BAR;
;     LDB(B1, 0, 1); BAR; WAIT_L(0); MMA(0, 1, At, B1); BAR;
;     LDA(At, 0, 1); WAIT_V(4); BAR; WAIT_L(0); MMA(1, 0, At, B0); MMA(1, 1, At, B1); BAR; }
	s_cbranch_scc1 .LBB0_69
	v_readlane_b32 s64, v254, 0
	v_readlane_b32 s65, v254, 1
	v_readlane_b32 s66, v254, 2
	v_readlane_b32 s67, v254, 3
	v_readlane_b32 s68, v254, 4
	v_readlane_b32 s69, v254, 5
	v_readlane_b32 s70, v254, 6
	v_readlane_b32 s71, v254, 7
	v_readlane_b32 s72, v254, 8
	v_readlane_b32 s73, v254, 9
	v_readlane_b32 s74, v254, 10
	v_readlane_b32 s75, v254, 11
	v_readlane_b32 s76, v254, 12
	v_readlane_b32 s77, v254, 13
	v_readlane_b32 s78, v254, 14
	v_readlane_b32 s79, v254, 15
	v_readlane_b32 s80, v254, 16
	v_readlane_b32 s81, v254, 17
	v_readlane_b32 s82, v254, 18
	v_readlane_b32 s83, v254, 19
	v_readlane_b32 s84, v254, 20
	v_readlane_b32 s85, v254, 21
	v_readlane_b32 s86, v254, 22
	v_readlane_b32 s87, v254, 23
	v_readlane_b32 s88, v254, 24
	v_readlane_b32 s89, v254, 25
	v_readlane_b32 s90, v254, 26
	v_readlane_b32 s91, v254, 27
	v_readlane_b32 s92, v254, 28
	v_readlane_b32 s93, v254, 29
	v_readlane_b32 s94, v254, 30
	v_readlane_b32 s95, v254, 31
	s_nop 4
	s_add_u32 s4, s4, 0x1f80
	s_addc_u32 s5, s5, 0
	v_readfirstlane_b32 s8, v163
	v_lshl_add_u64 v[146:147], s[4:5], 0, v[184:185]
	s_mov_b32 m0, s8
	v_lshl_add_u64 v[128:129], s[4:5], 0, v[128:129]
	v_readfirstlane_b32 s4, v164
	ds_read_b128 v[130:133], v162
	ds_read_b128 v[134:137], v162 offset:1024
	ds_read_b128 v[154:157], v162 offset:2048
	ds_read_b128 v[166:169], v162 offset:3072
	ds_read_b128 v[170:173], v144
	ds_read_b128 v[174:177], v144 offset:1024
	ds_read_b128 v[178:181], v141
	ds_read_b128 v[186:189], v141 offset:1024
	ds_read_b128 v[190:193], v140
	ds_read_b128 v[194:197], v140 offset:1024
	ds_read_b128 v[198:201], v139
	ds_read_b128 v[202:205], v139 offset:1024
	global_load_lds_dwordx4 v[146:147], off
	s_mov_b32 m0, s4
	s_nop 0
	global_load_lds_dwordx4 v[128:129], off
	s_barrier
	s_waitcnt lgkmcnt(0)
	s_waitcnt lgkmcnt(0)
	v_mfma_f32_16x16x32_bf16 v[124:127], v[130:133], v[170:173], v[124:127]
	v_mfma_f32_16x16x32_bf16 v[120:123], v[154:157], v[170:173], v[120:123]
	v_mfma_f32_16x16x32_bf16 v[116:119], v[130:133], v[178:181], v[116:119]
	v_mfma_f32_16x16x32_bf16 v[108:111], v[130:133], v[190:193], v[108:111]
	v_mfma_f32_16x16x32_bf16 v[104:107], v[154:157], v[190:193], v[104:107]
	v_mfma_f32_16x16x32_bf16 v[124:127], v[134:137], v[174:177], v[124:127]
	v_mfma_f32_16x16x32_bf16 v[120:123], v[166:169], v[174:177], v[120:123]
	v_mfma_f32_16x16x32_bf16 v[116:119], v[134:137], v[186:189], v[116:119]
	v_mfma_f32_16x16x32_bf16 v[112:115], v[154:157], v[178:181], v[112:115]
	v_mfma_f32_16x16x32_bf16 v[108:111], v[134:137], v[194:197], v[108:111]
	v_mfma_f32_16x16x32_bf16 v[104:107], v[166:169], v[194:197], v[104:107]
	v_mfma_f32_16x16x32_bf16 v[100:103], v[130:133], v[198:201], v[100:103]
	v_mfma_f32_16x16x32_bf16 v[96:99], v[154:157], v[198:201], v[96:99]
	v_mfma_f32_16x16x32_bf16 v[162:165], v[166:169], v[186:189], v[112:115]
	v_mfma_f32_16x16x32_bf16 v[206:209], v[134:137], v[202:205], v[100:103]
	v_mfma_f32_16x16x32_bf16 v[210:213], v[166:169], v[202:205], v[96:99]
	s_barrier
	s_nop 2
	ds_read_b128 v[96:99], v161
	ds_read_b128 v[100:103], v161 offset:1024
	ds_read_b128 v[112:115], v161 offset:2048
	ds_read_b128 v[158:161], v161 offset:3072
	s_barrier
	s_waitcnt lgkmcnt(0)
	s_waitcnt lgkmcnt(0)
	v_mfma_f32_16x16x32_bf16 v[92:95], v[96:99], v[170:173], v[92:95]
	v_mfma_f32_16x16x32_bf16 v[88:91], v[112:115], v[170:173], v[88:91]
	v_mfma_f32_16x16x32_bf16 v[84:87], v[96:99], v[178:181], v[84:87]
	v_mfma_f32_16x16x32_bf16 v[76:79], v[96:99], v[190:193], v[76:79]
	v_mfma_f32_16x16x32_bf16 v[72:75], v[112:115], v[190:193], v[72:75]
	v_mfma_f32_16x16x32_bf16 v[92:95], v[100:103], v[174:177], v[92:95]
	v_mfma_f32_16x16x32_bf16 v[88:91], v[158:161], v[174:177], v[88:91]
	v_mfma_f32_16x16x32_bf16 v[84:87], v[100:103], v[186:189], v[84:87]
	v_mfma_f32_16x16x32_bf16 v[80:83], v[112:115], v[178:181], v[80:83]
	v_mfma_f32_16x16x32_bf16 v[76:79], v[100:103], v[194:197], v[76:79]
	v_mfma_f32_16x16x32_bf16 v[72:75], v[158:161], v[194:197], v[72:75]
	v_mfma_f32_16x16x32_bf16 v[68:71], v[96:99], v[198:201], v[68:71]
	v_mfma_f32_16x16x32_bf16 v[64:67], v[112:115], v[198:201], v[64:67]
	v_mfma_f32_16x16x32_bf16 v[170:173], v[158:161], v[186:189], v[80:83]
	v_mfma_f32_16x16x32_bf16 v[174:177], v[100:103], v[202:205], v[68:71]
	v_mfma_f32_16x16x32_bf16 v[178:181], v[158:161], v[202:205], v[64:67]
	s_barrier
	s_nop 2
	ds_read_b128 v[64:67], v144 offset:16384
	ds_read_b128 v[68:71], v144 offset:17408
	ds_read_b128 v[80:83], v141 offset:16384
	ds_read_b128 v[186:189], v141 offset:17408
	ds_read_b128 v[190:193], v140 offset:16384
	ds_read_b128 v[194:197], v140 offset:17408
	ds_read_b128 v[198:201], v139 offset:16384
	ds_read_b128 v[202:205], v139 offset:17408
	s_waitcnt vmcnt(4)
	s_barrier
; #define WAIT_V(n) asm volatile("s_waitcnt vmcnt(" #n ")" ::: "memory")
; #define WAIT_L(n) asm volatile("s_waitcnt lgkmcnt(" #n ")" ::: "memory")
; #define BAR __builtin_amdgcn_s_barrier()
;     ...
;     LDA(At, 0, 1); WAIT_V(4); BAR; WAIT_L(0); MMA(1, 0, At, B0); MMA(1, 1, At, B1); BAR; }
;   { LDB(B0, 1, 0); LDA(At, 1, 0); WAIT_V(2); BAR; WAIT_L(0); MMA(0, 0, At, B0); BAR;
	s_waitcnt lgkmcnt(0)
	s_waitcnt lgkmcnt(0)
	v_mfma_f32_16x16x32_bf16 v[60:63], v[130:133], v[64:67], v[60:63]
	v_mfma_f32_16x16x32_bf16 v[56:59], v[154:157], v[64:67], v[56:59]
	v_mfma_f32_16x16x32_bf16 v[52:55], v[130:133], v[80:83], v[52:55]
	v_mfma_f32_16x16x32_bf16 v[44:47], v[130:133], v[190:193], v[44:47]
	v_mfma_f32_16x16x32_bf16 v[40:43], v[154:157], v[190:193], v[40:43]
	v_mfma_f32_16x16x32_bf16 v[60:63], v[134:137], v[68:71], v[60:63]
	v_mfma_f32_16x16x32_bf16 v[56:59], v[166:169], v[68:71], v[56:59]
	v_mfma_f32_16x16x32_bf16 v[52:55], v[134:137], v[186:189], v[52:55]
	v_mfma_f32_16x16x32_bf16 v[48:51], v[154:157], v[80:83], v[48:51]
	v_mfma_f32_16x16x32_bf16 v[44:47], v[134:137], v[194:197], v[44:47]
	v_mfma_f32_16x16x32_bf16 v[40:43], v[166:169], v[194:197], v[40:43]
	v_mfma_f32_16x16x32_bf16 v[36:39], v[130:133], v[198:201], v[36:39]
	v_mfma_f32_16x16x32_bf16 v[32:35], v[154:157], v[198:201], v[32:35]
	v_mfma_f32_16x16x32_bf16 v[214:217], v[166:169], v[186:189], v[48:51]
	v_mfma_f32_16x16x32_bf16 v[128:131], v[134:137], v[202:205], v[36:39]
	v_mfma_f32_16x16x32_bf16 v[132:135], v[166:169], v[202:205], v[32:35]
	v_mfma_f32_16x16x32_bf16 v[28:31], v[96:99], v[64:67], v[28:31]
	v_mfma_f32_16x16x32_bf16 v[24:27], v[112:115], v[64:67], v[24:27]
	v_mfma_f32_16x16x32_bf16 v[20:23], v[96:99], v[80:83], v[20:23]
	v_mfma_f32_16x16x32_bf16 v[12:15], v[96:99], v[190:193], v[12:15]
	v_mfma_f32_16x16x32_bf16 v[8:11], v[112:115], v[190:193], v[8:11]
	v_mfma_f32_16x16x32_bf16 v[28:31], v[100:103], v[68:71], v[28:31]
	v_mfma_f32_16x16x32_bf16 v[24:27], v[158:161], v[68:71], v[24:27]
	v_mfma_f32_16x16x32_bf16 v[20:23], v[100:103], v[186:189], v[20:23]
	v_mfma_f32_16x16x32_bf16 v[16:19], v[112:115], v[80:83], v[16:19]
	v_mfma_f32_16x16x32_bf16 v[12:15], v[100:103], v[194:197], v[12:15]
	v_mfma_f32_16x16x32_bf16 v[8:11], v[158:161], v[194:197], v[8:11]
	v_mfma_f32_16x16x32_bf16 v[4:7], v[96:99], v[198:201], v[4:7]
	v_mfma_f32_16x16x32_bf16 v[0:3], v[112:115], v[198:201], v[0:3]
	v_mfma_f32_16x16x32_bf16 v[154:157], v[158:161], v[186:189], v[16:19]
	v_mfma_f32_16x16x32_bf16 v[166:169], v[100:103], v[202:205], v[4:7]
	v_mfma_f32_16x16x32_bf16 v[158:161], v[158:161], v[202:205], v[0:3]
	s_barrier
	s_nop 2
	ds_read_b128 v[0:3], v152
	ds_read_b128 v[4:7], v152 offset:1024
	ds_read_b128 v[16:19], v152 offset:2048
	ds_read_b128 v[150:153], v152 offset:3072
	ds_read_b128 v[32:35], v144 offset:32768
	ds_read_b128 v[36:39], v144 offset:33792
	ds_read_b128 v[48:51], v141 offset:32768
	ds_read_b128 v[68:71], v141 offset:33792
	ds_read_b128 v[186:189], v140 offset:32768
	ds_read_b128 v[190:193], v140 offset:33792
	ds_read_b128 v[194:197], v139 offset:32768
	ds_read_b128 v[198:201], v139 offset:33792
	s_waitcnt vmcnt(2)
	s_barrier
	s_waitcnt lgkmcnt(0)
	s_waitcnt lgkmcnt(0)
	v_mfma_f32_16x16x32_bf16 v[64:67], v[0:3], v[32:35], v[124:127]
	v_mfma_f32_16x16x32_bf16 v[112:115], v[4:7], v[36:39], v[64:67]
	v_mfma_f32_16x16x32_bf16 v[64:67], v[16:19], v[32:35], v[120:123]
	v_mfma_f32_16x16x32_bf16 v[96:99], v[150:153], v[36:39], v[64:67]
	v_mfma_f32_16x16x32_bf16 v[64:67], v[0:3], v[48:51], v[116:119]
	v_mfma_f32_16x16x32_bf16 v[116:119], v[4:7], v[68:71], v[64:67]
	v_mfma_f32_16x16x32_bf16 v[64:67], v[16:19], v[48:51], v[162:165]
	v_mfma_f32_16x16x32_bf16 v[100:103], v[150:153], v[68:71], v[64:67]
	v_mfma_f32_16x16x32_bf16 v[64:67], v[0:3], v[186:189], v[108:111]
	v_mfma_f32_16x16x32_bf16 v[120:123], v[4:7], v[190:193], v[64:67]
	v_mfma_f32_16x16x32_bf16 v[64:67], v[16:19], v[186:189], v[104:107]
	v_mfma_f32_16x16x32_bf16 v[104:107], v[150:153], v[190:193], v[64:67]
	v_mfma_f32_16x16x32_bf16 v[64:67], v[0:3], v[194:197], v[206:209]
	v_mfma_f32_16x16x32_bf16 v[124:127], v[4:7], v[198:201], v[64:67]
	v_mfma_f32_16x16x32_bf16 v[64:67], v[16:19], v[194:197], v[210:213]
	v_mfma_f32_16x16x32_bf16 v[108:111], v[150:153], v[198:201], v[64:67]
	s_barrier
; #define WAIT_V(n) asm volatile("s_waitcnt vmcnt(" #n ")" ::: "memory")
; #define WAIT_L(n) asm volatile("s_waitcnt lgkmcnt(" #n ")" ::: "memory")
; #define BAR __builtin_amdgcn_s_barrier()
;     ...
;   { LDB(B0, 1, 0); LDA(At, 1, 0); WAIT_V(2); BAR; WAIT_L(0); MMA(0, 0, At, B0); BAR;
;     LDB(B1, 1, 1); WAIT_V(0); BAR; WAIT_L(0); MMA(0, 1, At, B1); BAR;
;     LDA(At, 1, 1); BAR; WAIT_L(0); MMA(1, 0, At, B0); MMA(1, 1, At, B1); BAR; }
;   if (wr == 0) BAR;
	ds_read_b128 v[162:165], v148
	ds_read_b128 v[202:205], v148 offset:1024
	ds_read_b128 v[206:209], v148 offset:2048
	ds_read_b128 v[146:149], v148 offset:3072
	s_waitcnt vmcnt(0)
	s_barrier
	s_waitcnt lgkmcnt(0)
	s_waitcnt lgkmcnt(0)
	v_mfma_f32_16x16x32_bf16 v[64:67], v[162:165], v[32:35], v[92:95]
	v_mfma_f32_16x16x32_bf16 v[32:35], v[206:209], v[32:35], v[88:91]
	v_mfma_f32_16x16x32_bf16 v[80:83], v[202:205], v[36:39], v[64:67]
	v_mfma_f32_16x16x32_bf16 v[64:67], v[146:149], v[36:39], v[32:35]
	v_mfma_f32_16x16x32_bf16 v[32:35], v[162:165], v[48:51], v[84:87]
	v_mfma_f32_16x16x32_bf16 v[84:87], v[202:205], v[68:71], v[32:35]
	v_mfma_f32_16x16x32_bf16 v[32:35], v[206:209], v[48:51], v[170:173]
	v_mfma_f32_16x16x32_bf16 v[68:71], v[146:149], v[68:71], v[32:35]
	v_mfma_f32_16x16x32_bf16 v[32:35], v[162:165], v[186:189], v[76:79]
	v_mfma_f32_16x16x32_bf16 v[88:91], v[202:205], v[190:193], v[32:35]
	v_mfma_f32_16x16x32_bf16 v[32:35], v[206:209], v[186:189], v[72:75]
	v_mfma_f32_16x16x32_bf16 v[72:75], v[146:149], v[190:193], v[32:35]
	v_mfma_f32_16x16x32_bf16 v[32:35], v[162:165], v[194:197], v[174:177]
	v_mfma_f32_16x16x32_bf16 v[92:95], v[202:205], v[198:201], v[32:35]
	v_mfma_f32_16x16x32_bf16 v[32:35], v[206:209], v[194:197], v[178:181]
	v_mfma_f32_16x16x32_bf16 v[76:79], v[146:149], v[198:201], v[32:35]
	s_barrier
	ds_read_b128 v[170:173], v144 offset:49152
	ds_read_b128 v[174:177], v144 offset:50176
	ds_read_b128 v[178:181], v141 offset:49152
	ds_read_b128 v[186:189], v141 offset:50176
	ds_read_b128 v[190:193], v140 offset:49152
	ds_read_b128 v[194:197], v140 offset:50176
	ds_read_b128 v[198:201], v139 offset:49152
	ds_read_b128 v[210:213], v139 offset:50176
	s_barrier
	s_waitcnt lgkmcnt(0)
	s_waitcnt lgkmcnt(0)
	v_mfma_f32_16x16x32_bf16 v[32:35], v[0:3], v[170:173], v[60:63]
	v_mfma_f32_16x16x32_bf16 v[36:39], v[0:3], v[178:181], v[52:55]
	v_mfma_f32_16x16x32_bf16 v[44:47], v[0:3], v[190:193], v[44:47]
	v_mfma_f32_16x16x32_bf16 v[0:3], v[0:3], v[198:201], v[128:131]
	v_mfma_f32_16x16x32_bf16 v[48:51], v[4:7], v[174:177], v[32:35]
	v_mfma_f32_16x16x32_bf16 v[32:35], v[16:19], v[170:173], v[56:59]
	v_mfma_f32_16x16x32_bf16 v[52:55], v[4:7], v[186:189], v[36:39]
	v_mfma_f32_16x16x32_bf16 v[36:39], v[16:19], v[178:181], v[214:217]
	v_mfma_f32_16x16x32_bf16 v[40:43], v[16:19], v[190:193], v[40:43]
	v_mfma_f32_16x16x32_bf16 v[60:63], v[4:7], v[210:213], v[0:3]
	v_mfma_f32_16x16x32_bf16 v[0:3], v[16:19], v[198:201], v[132:135]
	v_mfma_f32_16x16x32_bf16 v[32:35], v[150:153], v[174:177], v[32:35]
	v_mfma_f32_16x16x32_bf16 v[36:39], v[150:153], v[186:189], v[36:39]
	v_mfma_f32_16x16x32_bf16 v[56:59], v[4:7], v[194:197], v[44:47]
	v_mfma_f32_16x16x32_bf16 v[40:43], v[150:153], v[194:197], v[40:43]
	v_mfma_f32_16x16x32_bf16 v[44:47], v[150:153], v[210:213], v[0:3]
	v_mfma_f32_16x16x32_bf16 v[0:3], v[162:165], v[170:173], v[28:31]
	v_mfma_f32_16x16x32_bf16 v[12:15], v[162:165], v[190:193], v[12:15]
	v_mfma_f32_16x16x32_bf16 v[16:19], v[202:205], v[174:177], v[0:3]
	v_mfma_f32_16x16x32_bf16 v[0:3], v[206:209], v[170:173], v[24:27]
	v_mfma_f32_16x16x32_bf16 v[4:7], v[162:165], v[178:181], v[20:23]
	v_mfma_f32_16x16x32_bf16 v[24:27], v[202:205], v[194:197], v[12:15]
	v_mfma_f32_16x16x32_bf16 v[12:15], v[162:165], v[198:201], v[166:169]
	v_mfma_f32_16x16x32_bf16 v[20:23], v[202:205], v[186:189], v[4:7]
	v_mfma_f32_16x16x32_bf16 v[4:7], v[206:209], v[178:181], v[154:157]
	v_mfma_f32_16x16x32_bf16 v[8:11], v[206:209], v[190:193], v[8:11]
	v_mfma_f32_16x16x32_bf16 v[28:31], v[202:205], v[210:213], v[12:15]
	v_mfma_f32_16x16x32_bf16 v[12:15], v[206:209], v[198:201], v[158:161]
	v_mfma_f32_16x16x32_bf16 v[0:3], v[146:149], v[174:177], v[0:3]
	v_mfma_f32_16x16x32_bf16 v[4:7], v[146:149], v[186:189], v[4:7]
	v_mfma_f32_16x16x32_bf16 v[8:11], v[146:149], v[194:197], v[8:11]
	v_mfma_f32_16x16x32_bf16 v[12:15], v[146:149], v[210:213], v[12:15]
	v_cmp_gt_u32_e32 vcc, s57, v143
	s_barrier
	s_and_saveexec_b64 s[4:5], vcc
	s_cbranch_execz .LBB0_72
	s_barrier

; #define WAIT_V(n) asm volatile("s_waitcnt vmcnt(" #n ")" ::: "memory")
; #define BAR __builtin_amdgcn_s_barrier()
;     ...
;   const int wid = tx >> 6, lane = tx & 63, wr = wid >> 2, wc = wid & 3, fr = lane & 15, fq = lane >> 4;
;   f32x4 acc[2][2][4][2] = {};
;   bf16x8 At[4][2], B0[2][2], B1[2][2];
;   const int nt = K / BK;
;   unsigned soff0, soff1;
;   { int _r, _c; stage_rc(tx * 16, _r, _c); soff0 = (unsigned)(_r * K + _c) * 2u;
;     stage_rc(tx * 16 + 8192, _r, _c); soff1 = (unsigned)(_r * K + _c) * 2u; }
;   STAGE(SB(0, 0), Bt, bcol, 0); STAGE(SA(0, 0), A, brow, 0);
;   STAGE(SB(0, 1), Bt, bcol1, 0); STAGE(SA(0, 1), A, brow + HALF, 0);
;   if (wr == 1) BAR;
;   WAIT_V(4); BAR;
;   STAGE(SB(1, 0), Bt, bcol, 1); STAGE(SA(1, 0), A, brow, 1); STAGE(SB(1, 1), Bt, bcol1, 1);
;   WAIT_V(6); BAR;
.LBB0_1141:
	s_or_b64 exec, exec, s[34:35]
	v_add_u32_e32 v162, s38, v18
	v_add_u32_e32 v163, 0x2000, v162
	v_readfirstlane_b32 s25, v162
	v_lshl_add_u64 v[10:11], v[10:11], 0, s[12:13]
	s_mov_b32 m0, s25
	v_readfirstlane_b32 s25, v163
	v_add_u32_e32 v164, 0x8000, v154
	s_waitcnt vmcnt(4)
	s_barrier
	global_load_lds_dwordx4 v[10:11], off
	v_lshl_add_u64 v[8:9], v[8:9], 0, s[12:13]
	s_mov_b32 m0, s25
	v_readfirstlane_b32 s25, v164
	v_add_u32_e32 v165, 0xa000, v154
	global_load_lds_dwordx4 v[8:9], off
	v_lshl_add_u64 v[6:7], v[6:7], 0, s[12:13]
	s_mov_b32 m0, s25
	v_readfirstlane_b32 s25, v165
	v_add_u32_e32 v166, s39, v18
	global_load_lds_dwordx4 v[6:7], off
	v_lshl_add_u64 v[4:5], v[4:5], 0, s[12:13]
	s_mov_b32 m0, s25
	v_readfirstlane_b32 s25, v166
	v_add_u32_e32 v167, 0x2000, v166
	global_load_lds_dwordx4 v[4:5], off
	v_lshl_add_u64 v[2:3], v[2:3], 0, s[12:13]
	s_mov_b32 m0, s25
	v_readfirstlane_b32 s25, v167
	global_load_lds_dwordx4 v[2:3], off
	v_lshl_add_u64 v[0:1], v[0:1], 0, s[12:13]
	s_mov_b32 m0, s25
	v_and_b32_e32 v142, 15, v140
	global_load_lds_dwordx4 v[0:1], off
	v_lshlrev_b32_e32 v2, 2, v140
	v_and_b32_e32 v0, 48, v140
	v_lshlrev_b32_e32 v1, 6, v142
	v_and_b32_e32 v2, 32, v2
	v_bitop3_b32 v1, v1, v2, v0 bitop3:0x36
	v_add_u32_e32 v5, s36, v1
	v_add_u32_e32 v6, s37, v1
	v_add_u32_e32 v7, s38, v1
	v_add_u32_e32 v8, s39, v1
	v_add_u32_e32 v10, 0, v1
	v_lshlrev_b32_e32 v1, 6, v140
	v_and_or_b32 v0, v1, s40, v0
	v_xad_u32 v11, v0, v2, 0
	v_lshlrev_b32_e32 v0, 16, v12
	v_lshlrev_b32_e32 v2, 16, v14
	v_and_b32_e32 v0, 0xfffe0000, v0
	v_and_b32_e32 v2, 0xfffe0000, v2
	v_lshl_add_u32 v0, v13, 13, v0
	v_and_b32_e32 v1, 1, v12
	v_lshl_add_u32 v2, v16, 13, v2
	v_and_b32_e32 v3, 1, v14
	v_lshl_or_b32 v0, v1, 6, v0
	s_add_u32 s30, s8, s30
	v_lshl_or_b32 v2, v3, 6, v2
	v_lshl_add_u32 v0, v15, 1, v0
	v_mov_b32_e32 v1, v137
	s_addc_u32 s31, s9, s31
	v_lshl_add_u32 v2, v17, 1, v2
	v_mov_b32_e32 v3, v137
	v_lshl_add_u64 v[130:131], s[30:31], 0, v[0:1]
	v_lshl_add_u64 v[132:133], s[30:31], 0, v[2:3]
	s_add_i32 s30, s46, s47
	s_ashr_i32 s31, s30, 31
	s_lshl_b64 s[30:31], s[30:31], 13
	s_add_u32 s30, s4, s30
	v_bfe_u32 v141, v150, 6, 2
	s_waitcnt vmcnt(6)
	v_lshlrev_b32_e32 v9, 13, v19
	s_addc_u32 s31, s5, s31
	v_lshlrev_b32_e32 v4, 12, v141
	v_lshlrev_b32_e32 v143, 6, v19
	v_or_b32_e32 v18, 0x800, v9
	v_or_b32_e32 v19, 0x1000, v9
	v_or_b32_e32 v20, 0x1800, v9
	v_lshl_add_u64 v[134:135], s[30:31], 0, v[0:1]
	v_mov_b32_e32 v0, 0
	v_or_b32_e32 v151, v143, v142
	v_lshl_add_u64 v[138:139], s[30:31], 0, v[2:3]
	s_mov_b32 s25, -2
	s_mov_b64 s[30:31], 0
	v_add_u32_e32 v169, v5, v4
	v_add_u32_e32 v147, v10, v9
	v_add_u32_e32 v146, v11, v18
	v_add_u32_e32 v145, v11, v19
	v_add_u32_e32 v144, v11, v20
	v_add_u32_e32 v168, v6, v4
	v_add_u32_e32 v160, v7, v4
	v_add_u32_e32 v155, v8, v4
	v_mov_b32_e32 v1, v0
	v_mov_b32_e32 v2, v0
	v_mov_b32_e32 v3, v0
	v_mov_b32_e32 v4, v0
	v_mov_b32_e32 v5, v0
	v_mov_b32_e32 v6, v0
	v_mov_b32_e32 v7, v0
	v_mov_b32_e32 v8, v0
	v_mov_b32_e32 v9, v0
	v_mov_b32_e32 v10, v0
	v_mov_b32_e32 v11, v0
	v_mov_b32_e32 v12, v0
	v_mov_b32_e32 v13, v0
	v_mov_b32_e32 v14, v0
	v_mov_b32_e32 v15, v0
	v_mov_b32_e32 v16, v0
	v_mov_b32_e32 v17, v0
	v_mov_b32_e32 v18, v0
	v_mov_b32_e32 v19, v0
	v_mov_b32_e32 v20, v0
	v_mov_b32_e32 v21, v0
	v_mov_b32_e32 v22, v0
	v_mov_b32_e32 v23, v0
	v_mov_b32_e32 v24, v0
	v_mov_b32_e32 v25, v0
	v_mov_b32_e32 v26, v0
	v_mov_b32_e32 v27, v0
	v_mov_b32_e32 v28, v0
	v_mov_b32_e32 v29, v0
	v_mov_b32_e32 v30, v0
	v_mov_b32_e32 v31, v0
	v_mov_b32_e32 v32, v0
	v_mov_b32_e32 v33, v0
	v_mov_b32_e32 v34, v0
	v_mov_b32_e32 v35, v0
	v_mov_b32_e32 v36, v0
	v_mov_b32_e32 v37, v0
	v_mov_b32_e32 v38, v0
	v_mov_b32_e32 v39, v0
	v_mov_b32_e32 v40, v0
	v_mov_b32_e32 v41, v0
	v_mov_b32_e32 v42, v0
	v_mov_b32_e32 v43, v0
	v_mov_b32_e32 v44, v0
	v_mov_b32_e32 v45, v0
	v_mov_b32_e32 v46, v0
	v_mov_b32_e32 v47, v0
	v_mov_b32_e32 v48, v0
	v_mov_b32_e32 v49, v0
	v_mov_b32_e32 v50, v0
	v_mov_b32_e32 v51, v0
	v_mov_b32_e32 v52, v0
	v_mov_b32_e32 v53, v0
	v_mov_b32_e32 v54, v0
	v_mov_b32_e32 v55, v0
	v_mov_b32_e32 v56, v0
	v_mov_b32_e32 v57, v0
	v_mov_b32_e32 v58, v0
	v_mov_b32_e32 v59, v0
	v_mov_b32_e32 v60, v0
	v_mov_b32_e32 v61, v0
	v_mov_b32_e32 v62, v0
	v_mov_b32_e32 v63, v0
	v_mov_b32_e32 v64, v0
	v_mov_b32_e32 v65, v0
	v_mov_b32_e32 v66, v0
	v_mov_b32_e32 v67, v0
	v_mov_b32_e32 v68, v0
	v_mov_b32_e32 v69, v0
	v_mov_b32_e32 v70, v0
	v_mov_b32_e32 v71, v0
	v_mov_b32_e32 v72, v0
	v_mov_b32_e32 v73, v0
	v_mov_b32_e32 v74, v0
	v_mov_b32_e32 v75, v0
	v_mov_b32_e32 v76, v0
	v_mov_b32_e32 v77, v0
	v_mov_b32_e32 v78, v0
	v_mov_b32_e32 v79, v0
	v_mov_b32_e32 v80, v0
	v_mov_b32_e32 v81, v0
	v_mov_b32_e32 v82, v0
	v_mov_b32_e32 v83, v0
	v_mov_b32_e32 v84, v0
	v_mov_b32_e32 v85, v0
	v_mov_b32_e32 v86, v0
	v_mov_b32_e32 v87, v0
	v_mov_b32_e32 v88, v0
	v_mov_b32_e32 v89, v0
	v_mov_b32_e32 v90, v0
	v_mov_b32_e32 v91, v0
	v_mov_b32_e32 v92, v0
	v_mov_b32_e32 v93, v0
	v_mov_b32_e32 v94, v0
	v_mov_b32_e32 v95, v0
	v_mov_b32_e32 v96, v0
	v_mov_b32_e32 v97, v0
	v_mov_b32_e32 v98, v0
	v_mov_b32_e32 v99, v0
	v_mov_b32_e32 v100, v0
	v_mov_b32_e32 v101, v0
	v_mov_b32_e32 v102, v0
	v_mov_b32_e32 v103, v0
	v_mov_b32_e32 v104, v0
	v_mov_b32_e32 v105, v0
	v_mov_b32_e32 v106, v0
	v_mov_b32_e32 v107, v0
	v_mov_b32_e32 v108, v0
	v_mov_b32_e32 v109, v0
	v_mov_b32_e32 v110, v0
	v_mov_b32_e32 v111, v0
	v_mov_b32_e32 v112, v0
	v_mov_b32_e32 v113, v0
	v_mov_b32_e32 v114, v0
	v_mov_b32_e32 v115, v0
	v_mov_b32_e32 v116, v0
	v_mov_b32_e32 v117, v0
	v_mov_b32_e32 v118, v0
	v_mov_b32_e32 v119, v0
	v_mov_b32_e32 v120, v0
	v_mov_b32_e32 v121, v0
	v_mov_b32_e32 v122, v0
	v_mov_b32_e32 v123, v0
	v_mov_b32_e32 v124, v0
	v_mov_b32_e32 v125, v0
	v_mov_b32_e32 v126, v0
	v_mov_b32_e32 v127, v0
	s_barrier
; #define WAIT_L(n) asm volatile("s_waitcnt lgkmcnt(" #n ")" ::: "memory")
; #define BAR __builtin_amdgcn_s_barrier()
; #define SCHED __builtin_amdgcn_sched_barrier(0)
;     ...
;   for (int t = 0; t < nt - 2; t += 2) {
;     LDB(B0, 0, 0); SCHED; LDA(At, 0, 0); STAGE(SA(1, 1), A, brow + HALF, t + 1);
;     WAIT_L(8); BAR; WAIT_L(0); MMA(0, 0, At, B0); BAR; SCHED;
	v_readfirstlane_b32 s27, v154
	v_writelane_b32 v254, s64, 0
	v_writelane_b32 v254, s65, 1
	v_writelane_b32 v254, s66, 2
	v_writelane_b32 v254, s67, 3
	v_writelane_b32 v254, s68, 4
	v_writelane_b32 v254, s69, 5
	v_writelane_b32 v254, s70, 6
	v_writelane_b32 v254, s71, 7
	v_writelane_b32 v254, s72, 8
	v_writelane_b32 v254, s73, 9
	v_writelane_b32 v254, s74, 10
	v_writelane_b32 v254, s75, 11
	v_writelane_b32 v254, s76, 12
	v_writelane_b32 v254, s77, 13
	v_writelane_b32 v254, s78, 14
	v_writelane_b32 v254, s79, 15
	v_writelane_b32 v254, s80, 16
	v_writelane_b32 v254, s81, 17
	v_writelane_b32 v254, s82, 18
	v_writelane_b32 v254, s83, 19
	v_writelane_b32 v254, s84, 20
	v_writelane_b32 v254, s85, 21
	v_writelane_b32 v254, s86, 22
	v_writelane_b32 v254, s87, 23
	v_writelane_b32 v254, s88, 24
	v_writelane_b32 v254, s89, 25
	v_writelane_b32 v254, s90, 26
	v_writelane_b32 v254, s91, 27
	v_writelane_b32 v254, s92, 28
	v_writelane_b32 v254, s93, 29
	v_writelane_b32 v254, s94, 30
	v_writelane_b32 v254, s95, 31
	v_readfirstlane_b32 s64, v134
	v_readfirstlane_b32 s65, v135
	v_readfirstlane_b32 s66, v138
	v_readfirstlane_b32 s67, v139
	v_readfirstlane_b32 s68, v130
	v_readfirstlane_b32 s69, v131
	v_readfirstlane_b32 s70, v132
	v_readfirstlane_b32 s71, v133
	v_readfirstlane_b32 s72, v134
	v_readfirstlane_b32 s73, v135
	v_readfirstlane_b32 s74, v138
	v_readfirstlane_b32 s75, v139
	v_readfirstlane_b32 s76, v130
	v_readfirstlane_b32 s77, v131
	v_readfirstlane_b32 s78, v132
	v_readfirstlane_b32 s79, v133
	v_readfirstlane_b32 s80, v134
	v_readfirstlane_b32 s81, v135
	v_readfirstlane_b32 s82, v138
	v_readfirstlane_b32 s83, v139
	v_readfirstlane_b32 s84, v130
	v_readfirstlane_b32 s85, v131
	v_readfirstlane_b32 s86, v132
	v_readfirstlane_b32 s87, v133
	v_readfirstlane_b32 s88, v134
	v_readfirstlane_b32 s89, v135
	v_readfirstlane_b32 s90, v138
	v_readfirstlane_b32 s91, v139
	v_readfirstlane_b32 s92, v130
	v_readfirstlane_b32 s93, v131
	v_readfirstlane_b32 s94, v132
	v_readfirstlane_b32 s95, v133
	s_nop 3
	v_subrev_u32_e32 v158, s64, v134
	v_subrev_u32_e32 v159, s66, v138
	v_subrev_u32_e32 v156, s68, v130
	v_subrev_u32_e32 v157, s70, v132
	s_add_u32 s64, s64, s30
	s_addc_u32 s65, s65, s31
	s_add_u32 s64, s64, s14
	s_addc_u32 s65, s65, s15
	s_add_u32 s66, s66, s30
	s_addc_u32 s67, s67, s31
	s_add_u32 s66, s66, s14
	s_addc_u32 s67, s67, s15
	s_add_u32 s68, s68, s30
	s_addc_u32 s69, s69, s31
	s_add_u32 s68, s68, s16
	s_addc_u32 s69, s69, s17
	s_add_u32 s70, s70, s30
	s_addc_u32 s71, s71, s31
	s_add_u32 s70, s70, s16
	s_addc_u32 s71, s71, s17
	s_add_u32 s72, s72, s30
	s_addc_u32 s73, s73, s31
	s_add_u32 s72, s72, s16
	s_addc_u32 s73, s73, s17
	s_add_u32 s74, s74, s30
	s_addc_u32 s75, s75, s31
	s_add_u32 s74, s74, s16
	s_addc_u32 s75, s75, s17
	s_add_u32 s76, s76, s30
	s_addc_u32 s77, s77, s31
	s_add_u32 s76, s76, s18
	s_addc_u32 s77, s77, s19
	s_add_u32 s78, s78, s30
	s_addc_u32 s79, s79, s31
	s_add_u32 s78, s78, s18
	s_addc_u32 s79, s79, s19
	s_add_u32 s80, s80, s30
	s_addc_u32 s81, s81, s31
	s_add_u32 s80, s80, s18
	s_addc_u32 s81, s81, s19
	s_add_u32 s82, s82, s30
	s_addc_u32 s83, s83, s31
	s_add_u32 s82, s82, s18
	s_addc_u32 s83, s83, s19
	s_add_u32 s84, s84, s30
	s_addc_u32 s85, s85, s31
	s_add_u32 s84, s84, s20
	s_addc_u32 s85, s85, s21
	s_add_u32 s86, s86, s30
	s_addc_u32 s87, s87, s31
	s_add_u32 s86, s86, s20
	s_addc_u32 s87, s87, s21
	s_add_u32 s88, s88, s30
	s_addc_u32 s89, s89, s31
	s_add_u32 s88, s88, s20
	s_addc_u32 s89, s89, s21
	s_add_u32 s90, s90, s30
	s_addc_u32 s91, s91, s31
	s_add_u32 s90, s90, s20
	s_addc_u32 s91, s91, s21
	s_add_u32 s92, s92, s30
	s_addc_u32 s93, s93, s31
	s_add_u32 s92, s92, s22
	s_addc_u32 s93, s93, s23
	s_add_u32 s94, s94, s30
	s_addc_u32 s95, s95, s31
	s_add_u32 s94, s94, s22
	s_addc_u32 s95, s95, s23
	v_add_u32_e32 v170, 0xc000, v154
	v_add_u32_e32 v171, 0xe000, v154
.LBB0_1142:
	ds_read_b128 v[172:175], v169
	ds_read_b128 v[176:179], v169 offset:1024
	ds_read_b128 v[180:183], v169 offset:2048
	ds_read_b128 v[184:187], v169 offset:3072
	s_add_u32 m0, s27, 0xc000
	ds_read_b128 v[188:191], v147
	ds_read_b128 v[192:195], v147 offset:1024
	ds_read_b128 v[196:199], v146
	ds_read_b128 v[200:203], v146 offset:1024
	ds_read_b128 v[204:207], v145
	ds_read_b128 v[208:211], v145 offset:1024
	ds_read_b128 v[212:215], v144
	ds_read_b128 v[216:219], v144 offset:1024
	global_load_lds_dwordx4 v158, s[64:65]
	s_add_u32 s64, s64, 0x100
	s_addc_u32 s65, s65, 0
	s_add_u32 m0, s27, 0xe000
	s_nop 0
	global_load_lds_dwordx4 v159, s[66:67]
	s_add_u32 s66, s66, 0x100
	s_addc_u32 s67, s67, 0
	s_waitcnt lgkmcnt(8)
	s_barrier
	s_waitcnt lgkmcnt(0)
	v_mfma_f32_16x16x32_bf16 v[124:127], v[172:175], v[188:191], v[124:127]
	v_mfma_f32_16x16x32_bf16 v[120:123], v[180:183], v[188:191], v[120:123]
	v_mfma_f32_16x16x32_bf16 v[116:119], v[172:175], v[196:199], v[116:119]
	v_mfma_f32_16x16x32_bf16 v[112:115], v[180:183], v[196:199], v[112:115]
	v_mfma_f32_16x16x32_bf16 v[108:111], v[172:175], v[204:207], v[108:111]
	v_mfma_f32_16x16x32_bf16 v[104:107], v[180:183], v[204:207], v[104:107]
	v_mfma_f32_16x16x32_bf16 v[100:103], v[172:175], v[212:215], v[100:103]
	v_mfma_f32_16x16x32_bf16 v[96:99], v[180:183], v[212:215], v[96:99]
	v_mfma_f32_16x16x32_bf16 v[124:127], v[176:179], v[192:195], v[124:127]
	v_mfma_f32_16x16x32_bf16 v[120:123], v[184:187], v[192:195], v[120:123]
	v_mfma_f32_16x16x32_bf16 v[116:119], v[176:179], v[200:203], v[116:119]
	v_mfma_f32_16x16x32_bf16 v[112:115], v[184:187], v[200:203], v[112:115]
	v_mfma_f32_16x16x32_bf16 v[108:111], v[176:179], v[208:211], v[108:111]
	v_mfma_f32_16x16x32_bf16 v[104:107], v[184:187], v[208:211], v[104:107]
	v_mfma_f32_16x16x32_bf16 v[100:103], v[176:179], v[216:219], v[100:103]
	v_mfma_f32_16x16x32_bf16 v[96:99], v[184:187], v[216:219], v[96:99]
	s_barrier
; #define WAIT_V(n) asm volatile("s_waitcnt vmcnt(" #n ")" ::: "memory")
; #define WAIT_L(n) asm volatile("s_waitcnt lgkmcnt(" #n ")" ::: "memory")
; #define BAR __builtin_amdgcn_s_barrier()
; #define SCHED __builtin_amdgcn_sched_barrier(0)
;     ...
;     LDB(B1, 0, 1); STAGE(SB(0, 0), Bt, bcol, t + 2);
;     BAR; WAIT_L(0); MMA(0, 1, At, B1); BAR;
;     LDA(At, 0, 1); STAGE(SA(0, 0), A, brow, t + 2);
;     BAR; WAIT_L(0); MMA(1, 0, At, B0); BAR; SCHED;
;     STAGE(SB(0, 1), Bt, bcol1, t + 2);
;     WAIT_V(6); BAR; MMA(1, 1, At, B1); BAR;
;     LDB(B0, 1, 0); SCHED; LDA(At, 1, 0); STAGE(SA(0, 1), A, brow + HALF, t + 2);
;     WAIT_L(8); BAR; WAIT_L(0); MMA(0, 0, At, B0); BAR; SCHED;
	s_add_u32 m0, s27, s36
	ds_read_b128 v[220:223], v168
	ds_read_b128 v[224:227], v168 offset:1024
	ds_read_b128 v[228:231], v168 offset:2048
	ds_read_b128 v[232:235], v168 offset:3072
	global_load_lds_dwordx4 v156, s[68:69]
	s_add_u32 s68, s68, 0x100
	s_addc_u32 s69, s69, 0
	s_add_u32 m0, s27, 0x2000
	s_add_u32 m0, m0, s36
	s_nop 0
	global_load_lds_dwordx4 v157, s[70:71]
	s_add_u32 s70, s70, 0x100
	s_addc_u32 s71, s71, 0
	s_barrier
	s_waitcnt lgkmcnt(0)
	v_mfma_f32_16x16x32_bf16 v[92:95], v[220:223], v[188:191], v[92:95]
	v_mfma_f32_16x16x32_bf16 v[88:91], v[228:231], v[188:191], v[88:91]
	v_mfma_f32_16x16x32_bf16 v[84:87], v[220:223], v[196:199], v[84:87]
	v_mfma_f32_16x16x32_bf16 v[80:83], v[228:231], v[196:199], v[80:83]
	v_mfma_f32_16x16x32_bf16 v[76:79], v[220:223], v[204:207], v[76:79]
	v_mfma_f32_16x16x32_bf16 v[72:75], v[228:231], v[204:207], v[72:75]
	v_mfma_f32_16x16x32_bf16 v[68:71], v[220:223], v[212:215], v[68:71]
	v_mfma_f32_16x16x32_bf16 v[64:67], v[228:231], v[212:215], v[64:67]
	v_mfma_f32_16x16x32_bf16 v[92:95], v[224:227], v[192:195], v[92:95]
	v_mfma_f32_16x16x32_bf16 v[88:91], v[232:235], v[192:195], v[88:91]
	v_mfma_f32_16x16x32_bf16 v[84:87], v[224:227], v[200:203], v[84:87]
	v_mfma_f32_16x16x32_bf16 v[80:83], v[232:235], v[200:203], v[80:83]
	v_mfma_f32_16x16x32_bf16 v[76:79], v[224:227], v[208:211], v[76:79]
	v_mfma_f32_16x16x32_bf16 v[72:75], v[232:235], v[208:211], v[72:75]
	v_mfma_f32_16x16x32_bf16 v[68:71], v[224:227], v[216:219], v[68:71]
	v_mfma_f32_16x16x32_bf16 v[64:67], v[232:235], v[216:219], v[64:67]
	s_mov_b32 m0, s27
	s_barrier
	ds_read_b128 v[188:191], v147 offset:16384
	ds_read_b128 v[192:195], v147 offset:17408
	ds_read_b128 v[196:199], v146 offset:16384
	ds_read_b128 v[200:203], v146 offset:17408
	ds_read_b128 v[204:207], v145 offset:16384
	ds_read_b128 v[208:211], v145 offset:17408
	ds_read_b128 v[212:215], v144 offset:16384
	ds_read_b128 v[216:219], v144 offset:17408
	global_load_lds_dwordx4 v158, s[72:73]
	s_add_u32 s72, s72, 0x100
	s_addc_u32 s73, s73, 0
	s_add_u32 m0, s27, 0x2000
	s_nop 0
	global_load_lds_dwordx4 v159, s[74:75]
	s_add_u32 s74, s74, 0x100
	s_addc_u32 s75, s75, 0
	s_barrier
	s_waitcnt lgkmcnt(0)
	v_mfma_f32_16x16x32_bf16 v[60:63], v[172:175], v[188:191], v[60:63]
	v_mfma_f32_16x16x32_bf16 v[56:59], v[180:183], v[188:191], v[56:59]
	v_mfma_f32_16x16x32_bf16 v[52:55], v[172:175], v[196:199], v[52:55]
	v_mfma_f32_16x16x32_bf16 v[48:51], v[180:183], v[196:199], v[48:51]
	v_mfma_f32_16x16x32_bf16 v[44:47], v[172:175], v[204:207], v[44:47]
	v_mfma_f32_16x16x32_bf16 v[40:43], v[180:183], v[204:207], v[40:43]
	v_mfma_f32_16x16x32_bf16 v[36:39], v[172:175], v[212:215], v[36:39]
	v_mfma_f32_16x16x32_bf16 v[32:35], v[180:183], v[212:215], v[32:35]
	v_mfma_f32_16x16x32_bf16 v[60:63], v[176:179], v[192:195], v[60:63]
	v_mfma_f32_16x16x32_bf16 v[56:59], v[184:187], v[192:195], v[56:59]
	v_mfma_f32_16x16x32_bf16 v[52:55], v[176:179], v[200:203], v[52:55]
	v_mfma_f32_16x16x32_bf16 v[48:51], v[184:187], v[200:203], v[48:51]
	v_mfma_f32_16x16x32_bf16 v[44:47], v[176:179], v[208:211], v[44:47]
	v_mfma_f32_16x16x32_bf16 v[40:43], v[184:187], v[208:211], v[40:43]
	v_mfma_f32_16x16x32_bf16 v[36:39], v[176:179], v[216:219], v[36:39]
	v_mfma_f32_16x16x32_bf16 v[32:35], v[184:187], v[216:219], v[32:35]
	s_barrier
	s_add_u32 m0, s27, s37
	s_nop 0
	global_load_lds_dwordx4 v156, s[76:77]
	s_add_u32 s76, s76, 0x100
	s_addc_u32 s77, s77, 0
	s_add_u32 m0, s27, 0x2000
	s_add_u32 m0, m0, s37
	s_nop 0
	global_load_lds_dwordx4 v157, s[78:79]
	s_add_u32 s78, s78, 0x100
	s_addc_u32 s79, s79, 0
	s_waitcnt vmcnt(6)
	s_barrier
	v_mfma_f32_16x16x32_bf16 v[28:31], v[220:223], v[188:191], v[28:31]
	v_mfma_f32_16x16x32_bf16 v[24:27], v[228:231], v[188:191], v[24:27]
	v_mfma_f32_16x16x32_bf16 v[20:23], v[220:223], v[196:199], v[20:23]
	v_mfma_f32_16x16x32_bf16 v[16:19], v[228:231], v[196:199], v[16:19]
	v_mfma_f32_16x16x32_bf16 v[12:15], v[220:223], v[204:207], v[12:15]
	v_mfma_f32_16x16x32_bf16 v[8:11], v[228:231], v[204:207], v[8:11]
	v_mfma_f32_16x16x32_bf16 v[4:7], v[220:223], v[212:215], v[4:7]
	v_mfma_f32_16x16x32_bf16 v[0:3], v[228:231], v[212:215], v[0:3]
	v_mfma_f32_16x16x32_bf16 v[28:31], v[224:227], v[192:195], v[28:31]
	v_mfma_f32_16x16x32_bf16 v[24:27], v[232:235], v[192:195], v[24:27]
	v_mfma_f32_16x16x32_bf16 v[20:23], v[224:227], v[200:203], v[20:23]
	v_mfma_f32_16x16x32_bf16 v[16:19], v[232:235], v[200:203], v[16:19]
	v_mfma_f32_16x16x32_bf16 v[12:15], v[224:227], v[208:211], v[12:15]
	v_mfma_f32_16x16x32_bf16 v[8:11], v[232:235], v[208:211], v[8:11]
	v_mfma_f32_16x16x32_bf16 v[4:7], v[224:227], v[216:219], v[4:7]
	v_mfma_f32_16x16x32_bf16 v[0:3], v[232:235], v[216:219], v[0:3]
	s_barrier
	ds_read_b128 v[172:175], v160
	ds_read_b128 v[176:179], v160 offset:1024
	ds_read_b128 v[180:183], v160 offset:2048
	ds_read_b128 v[184:187], v160 offset:3072
	s_add_u32 m0, s27, 0x4000
	ds_read_b128 v[188:191], v147 offset:32768
	ds_read_b128 v[192:195], v147 offset:33792
	ds_read_b128 v[196:199], v146 offset:32768
	ds_read_b128 v[200:203], v146 offset:33792
	ds_read_b128 v[204:207], v145 offset:32768
	ds_read_b128 v[208:211], v145 offset:33792
	ds_read_b128 v[212:215], v144 offset:32768
	ds_read_b128 v[216:219], v144 offset:33792
	global_load_lds_dwordx4 v158, s[80:81]
	s_add_u32 s80, s80, 0x100
	s_addc_u32 s81, s81, 0
	s_add_u32 m0, s27, 0x6000
	s_nop 0
	global_load_lds_dwordx4 v159, s[82:83]
	s_add_u32 s82, s82, 0x100
	s_addc_u32 s83, s83, 0
	s_waitcnt lgkmcnt(8)
	s_barrier
; #define WAIT_V(n) asm volatile("s_waitcnt vmcnt(" #n ")" ::: "memory")
; #define WAIT_L(n) asm volatile("s_waitcnt lgkmcnt(" #n ")" ::: "memory")
; #define BAR __builtin_amdgcn_s_barrier()
; #define SCHED __builtin_amdgcn_sched_barrier(0)
;     ...
;     WAIT_L(8); BAR; WAIT_L(0); MMA(0, 0, At, B0); BAR; SCHED;
;     LDB(B1, 1, 1); STAGE(SB(1, 0), Bt, bcol, t + 3);
;     BAR; WAIT_L(0); MMA(0, 1, At, B1); BAR;
;     LDA(At, 1, 1); STAGE(SA(1, 0), A, brow, t + 3);
;     BAR; WAIT_L(0); MMA(1, 0, At, B0); BAR; SCHED;
;     STAGE(SB(1, 1), Bt, bcol1, t + 3);
;     WAIT_V(6); BAR; MMA(1, 1, At, B1); BAR;
	s_waitcnt lgkmcnt(0)
	v_mfma_f32_16x16x32_bf16 v[124:127], v[172:175], v[188:191], v[124:127]
	v_mfma_f32_16x16x32_bf16 v[120:123], v[180:183], v[188:191], v[120:123]
	v_mfma_f32_16x16x32_bf16 v[116:119], v[172:175], v[196:199], v[116:119]
	v_mfma_f32_16x16x32_bf16 v[112:115], v[180:183], v[196:199], v[112:115]
	v_mfma_f32_16x16x32_bf16 v[108:111], v[172:175], v[204:207], v[108:111]
	v_mfma_f32_16x16x32_bf16 v[104:107], v[180:183], v[204:207], v[104:107]
	v_mfma_f32_16x16x32_bf16 v[100:103], v[172:175], v[212:215], v[100:103]
	v_mfma_f32_16x16x32_bf16 v[96:99], v[180:183], v[212:215], v[96:99]
	v_mfma_f32_16x16x32_bf16 v[124:127], v[176:179], v[192:195], v[124:127]
	v_mfma_f32_16x16x32_bf16 v[120:123], v[184:187], v[192:195], v[120:123]
	v_mfma_f32_16x16x32_bf16 v[116:119], v[176:179], v[200:203], v[116:119]
	v_mfma_f32_16x16x32_bf16 v[112:115], v[184:187], v[200:203], v[112:115]
	v_mfma_f32_16x16x32_bf16 v[108:111], v[176:179], v[208:211], v[108:111]
	v_mfma_f32_16x16x32_bf16 v[104:107], v[184:187], v[208:211], v[104:107]
	v_mfma_f32_16x16x32_bf16 v[100:103], v[176:179], v[216:219], v[100:103]
	v_mfma_f32_16x16x32_bf16 v[96:99], v[184:187], v[216:219], v[96:99]
	s_barrier
	s_add_u32 m0, s27, s38
	ds_read_b128 v[220:223], v155
	ds_read_b128 v[224:227], v155 offset:1024
	ds_read_b128 v[228:231], v155 offset:2048
	ds_read_b128 v[232:235], v155 offset:3072
	global_load_lds_dwordx4 v156, s[84:85]
	s_add_u32 s84, s84, 0x100
	s_addc_u32 s85, s85, 0
	s_add_u32 m0, s27, 0x2000
	s_add_u32 m0, m0, s38
	s_nop 0
	global_load_lds_dwordx4 v157, s[86:87]
	s_add_u32 s86, s86, 0x100
	s_addc_u32 s87, s87, 0
	s_barrier
	s_waitcnt lgkmcnt(0)
	v_mfma_f32_16x16x32_bf16 v[92:95], v[220:223], v[188:191], v[92:95]
	v_mfma_f32_16x16x32_bf16 v[88:91], v[228:231], v[188:191], v[88:91]
	v_mfma_f32_16x16x32_bf16 v[84:87], v[220:223], v[196:199], v[84:87]
	v_mfma_f32_16x16x32_bf16 v[80:83], v[228:231], v[196:199], v[80:83]
	v_mfma_f32_16x16x32_bf16 v[76:79], v[220:223], v[204:207], v[76:79]
	v_mfma_f32_16x16x32_bf16 v[72:75], v[228:231], v[204:207], v[72:75]
	v_mfma_f32_16x16x32_bf16 v[68:71], v[220:223], v[212:215], v[68:71]
	v_mfma_f32_16x16x32_bf16 v[64:67], v[228:231], v[212:215], v[64:67]
	v_mfma_f32_16x16x32_bf16 v[92:95], v[224:227], v[192:195], v[92:95]
	v_mfma_f32_16x16x32_bf16 v[88:91], v[232:235], v[192:195], v[88:91]
	v_mfma_f32_16x16x32_bf16 v[84:87], v[224:227], v[200:203], v[84:87]
	v_mfma_f32_16x16x32_bf16 v[80:83], v[232:235], v[200:203], v[80:83]
	v_mfma_f32_16x16x32_bf16 v[76:79], v[224:227], v[208:211], v[76:79]
	v_mfma_f32_16x16x32_bf16 v[72:75], v[232:235], v[208:211], v[72:75]
	v_mfma_f32_16x16x32_bf16 v[68:71], v[224:227], v[216:219], v[68:71]
	v_mfma_f32_16x16x32_bf16 v[64:67], v[232:235], v[216:219], v[64:67]
	s_add_u32 m0, s27, 0x8000
	s_barrier
	ds_read_b128 v[188:191], v147 offset:49152
	ds_read_b128 v[192:195], v147 offset:50176
	ds_read_b128 v[196:199], v146 offset:49152
	ds_read_b128 v[200:203], v146 offset:50176
	ds_read_b128 v[204:207], v145 offset:49152
	ds_read_b128 v[208:211], v145 offset:50176
	ds_read_b128 v[212:215], v144 offset:49152
	ds_read_b128 v[216:219], v144 offset:50176
	global_load_lds_dwordx4 v158, s[88:89]
	s_add_u32 s88, s88, 0x100
	s_addc_u32 s89, s89, 0
	s_add_u32 m0, s27, 0xa000
	s_nop 0
	global_load_lds_dwordx4 v159, s[90:91]
	s_add_u32 s90, s90, 0x100
	s_addc_u32 s91, s91, 0
	s_barrier
	s_waitcnt lgkmcnt(0)
	v_mfma_f32_16x16x32_bf16 v[60:63], v[172:175], v[188:191], v[60:63]
	v_mfma_f32_16x16x32_bf16 v[56:59], v[180:183], v[188:191], v[56:59]
	v_mfma_f32_16x16x32_bf16 v[52:55], v[172:175], v[196:199], v[52:55]
	v_mfma_f32_16x16x32_bf16 v[48:51], v[180:183], v[196:199], v[48:51]
	v_mfma_f32_16x16x32_bf16 v[44:47], v[172:175], v[204:207], v[44:47]
	v_mfma_f32_16x16x32_bf16 v[40:43], v[180:183], v[204:207], v[40:43]
	v_mfma_f32_16x16x32_bf16 v[36:39], v[172:175], v[212:215], v[36:39]
	v_mfma_f32_16x16x32_bf16 v[32:35], v[180:183], v[212:215], v[32:35]
	v_mfma_f32_16x16x32_bf16 v[60:63], v[176:179], v[192:195], v[60:63]
	v_mfma_f32_16x16x32_bf16 v[56:59], v[184:187], v[192:195], v[56:59]
	v_mfma_f32_16x16x32_bf16 v[52:55], v[176:179], v[200:203], v[52:55]
	v_mfma_f32_16x16x32_bf16 v[48:51], v[184:187], v[200:203], v[48:51]
	v_mfma_f32_16x16x32_bf16 v[44:47], v[176:179], v[208:211], v[44:47]
	v_mfma_f32_16x16x32_bf16 v[40:43], v[184:187], v[208:211], v[40:43]
	v_mfma_f32_16x16x32_bf16 v[36:39], v[176:179], v[216:219], v[36:39]
	v_mfma_f32_16x16x32_bf16 v[32:35], v[184:187], v[216:219], v[32:35]
	s_barrier
	s_add_u32 m0, s27, s39
	s_nop 0
	global_load_lds_dwordx4 v156, s[92:93]
	s_add_u32 s92, s92, 0x100
	s_addc_u32 s93, s93, 0
	s_add_u32 m0, s27, 0x2000
	s_add_u32 m0, m0, s39
	s_nop 0
	global_load_lds_dwordx4 v157, s[94:95]
	s_add_u32 s94, s94, 0x100
	s_addc_u32 s95, s95, 0
	s_waitcnt vmcnt(6)
	s_barrier
	v_mfma_f32_16x16x32_bf16 v[28:31], v[220:223], v[188:191], v[28:31]
	v_mfma_f32_16x16x32_bf16 v[24:27], v[228:231], v[188:191], v[24:27]
	v_mfma_f32_16x16x32_bf16 v[20:23], v[220:223], v[196:199], v[20:23]
	v_mfma_f32_16x16x32_bf16 v[16:19], v[228:231], v[196:199], v[16:19]
	v_mfma_f32_16x16x32_bf16 v[12:15], v[220:223], v[204:207], v[12:15]
	v_mfma_f32_16x16x32_bf16 v[8:11], v[228:231], v[204:207], v[8:11]
	v_mfma_f32_16x16x32_bf16 v[4:7], v[220:223], v[212:215], v[4:7]
	v_mfma_f32_16x16x32_bf16 v[0:3], v[228:231], v[212:215], v[0:3]
	v_mfma_f32_16x16x32_bf16 v[28:31], v[224:227], v[192:195], v[28:31]
	v_mfma_f32_16x16x32_bf16 v[24:27], v[232:235], v[192:195], v[24:27]
	v_mfma_f32_16x16x32_bf16 v[20:23], v[224:227], v[200:203], v[20:23]
	v_mfma_f32_16x16x32_bf16 v[16:19], v[232:235], v[200:203], v[16:19]
	v_mfma_f32_16x16x32_bf16 v[12:15], v[224:227], v[208:211], v[12:15]
	v_mfma_f32_16x16x32_bf16 v[8:11], v[232:235], v[208:211], v[8:11]
	v_mfma_f32_16x16x32_bf16 v[4:7], v[224:227], v[216:219], v[4:7]
	v_mfma_f32_16x16x32_bf16 v[0:3], v[232:235], v[216:219], v[0:3]
	s_add_i32 s25, s25, 2
	s_add_u32 s30, s30, 0x100
	s_addc_u32 s31, s31, 0
	s_cmp_lt_u32 s25, 60
	s_barrier
; #define WAIT_V(n) asm volatile("s_waitcnt vmcnt(" #n ")" ::: "memory")
; #define WAIT_L(n) asm volatile("s_waitcnt lgkmcnt(" #n ")" ::: "memory")
; #define BAR __builtin_amdgcn_s_barrier()
;     ...
;   { LDB(B0, 0, 0); LDA(At, 0, 0); STAGE(SA(1, 1), A, brow + HALF, nt - 1);
;     BAR; WAIT_L(0); MMA(0, 0, At, B0); BAR;
;     LDB(B1, 0, 1); BAR; WAIT_L(0); MMA(0, 1, At, B1); BAR;
;     LDA(At, 0, 1); WAIT_V(4); BAR; WAIT_L(0); MMA(1, 0, At, B0); MMA(1, 1, At, B1); BAR; }
	s_cbranch_scc1 .LBB0_1142
	v_readlane_b32 s64, v254, 0
	v_readlane_b32 s65, v254, 1
	v_readlane_b32 s66, v254, 2
	v_readlane_b32 s67, v254, 3
	v_readlane_b32 s68, v254, 4
	v_readlane_b32 s69, v254, 5
	v_readlane_b32 s70, v254, 6
	v_readlane_b32 s71, v254, 7
	v_readlane_b32 s72, v254, 8
	v_readlane_b32 s73, v254, 9
	v_readlane_b32 s74, v254, 10
	v_readlane_b32 s75, v254, 11
	v_readlane_b32 s76, v254, 12
	v_readlane_b32 s77, v254, 13
	v_readlane_b32 s78, v254, 14
	v_readlane_b32 s79, v254, 15
	v_readlane_b32 s80, v254, 16
	v_readlane_b32 s81, v254, 17
	v_readlane_b32 s82, v254, 18
	v_readlane_b32 s83, v254, 19
	v_readlane_b32 s84, v254, 20
	v_readlane_b32 s85, v254, 21
	v_readlane_b32 s86, v254, 22
	v_readlane_b32 s87, v254, 23
	v_readlane_b32 s88, v254, 24
	v_readlane_b32 s89, v254, 25
	v_readlane_b32 s90, v254, 26
	v_readlane_b32 s91, v254, 27
	v_readlane_b32 s92, v254, 28
	v_readlane_b32 s93, v254, 29
	v_readlane_b32 s94, v254, 30
	v_readlane_b32 s95, v254, 31
	s_nop 4
	s_add_u32 s28, s28, 0x1f80
	s_addc_u32 s29, s29, 0
	v_readfirstlane_b32 s25, v170
	v_lshl_add_u64 v[134:135], s[28:29], 0, v[136:137]
	s_mov_b32 m0, s25
	v_readfirstlane_b32 s25, v171
	ds_read_b128 v[130:133], v169
	ds_read_b128 v[156:159], v169 offset:1024
	ds_read_b128 v[162:165], v169 offset:2048
	ds_read_b128 v[172:175], v169 offset:3072
	ds_read_b128 v[176:179], v147
	ds_read_b128 v[180:183], v147 offset:1024
	ds_read_b128 v[184:187], v146
	ds_read_b128 v[188:191], v146 offset:1024
	ds_read_b128 v[192:195], v145
	ds_read_b128 v[196:199], v145 offset:1024
	ds_read_b128 v[200:203], v144
	ds_read_b128 v[204:207], v144 offset:1024
	global_load_lds_dwordx4 v[134:135], off
	v_lshl_add_u64 v[128:129], s[28:29], 0, v[128:129]
	s_mov_b32 m0, s25
	s_nop 0
	global_load_lds_dwordx4 v[128:129], off
	s_barrier
	s_waitcnt lgkmcnt(0)
	s_waitcnt lgkmcnt(0)
	v_mfma_f32_16x16x32_bf16 v[124:127], v[130:133], v[176:179], v[124:127]
	v_mfma_f32_16x16x32_bf16 v[120:123], v[162:165], v[176:179], v[120:123]
	v_mfma_f32_16x16x32_bf16 v[116:119], v[130:133], v[184:187], v[116:119]
	v_mfma_f32_16x16x32_bf16 v[112:115], v[162:165], v[184:187], v[112:115]
	v_mfma_f32_16x16x32_bf16 v[108:111], v[130:133], v[192:195], v[108:111]
	v_mfma_f32_16x16x32_bf16 v[104:107], v[162:165], v[192:195], v[104:107]
	v_mfma_f32_16x16x32_bf16 v[96:99], v[162:165], v[200:203], v[96:99]
	v_mfma_f32_16x16x32_bf16 v[124:127], v[156:159], v[180:183], v[124:127]
	v_mfma_f32_16x16x32_bf16 v[120:123], v[172:175], v[180:183], v[120:123]
	v_mfma_f32_16x16x32_bf16 v[116:119], v[156:159], v[188:191], v[116:119]
	v_mfma_f32_16x16x32_bf16 v[112:115], v[172:175], v[188:191], v[112:115]
	v_mfma_f32_16x16x32_bf16 v[108:111], v[156:159], v[196:199], v[108:111]
	v_mfma_f32_16x16x32_bf16 v[104:107], v[172:175], v[196:199], v[104:107]
	v_mfma_f32_16x16x32_bf16 v[100:103], v[130:133], v[200:203], v[100:103]
	v_mfma_f32_16x16x32_bf16 v[96:99], v[172:175], v[204:207], v[96:99]
	v_mfma_f32_16x16x32_bf16 v[100:103], v[156:159], v[204:207], v[100:103]
	s_barrier
	ds_read_b128 v[208:211], v168
	ds_read_b128 v[212:215], v168 offset:1024
	ds_read_b128 v[216:219], v168 offset:2048
	ds_read_b128 v[166:169], v168 offset:3072
	s_barrier
	s_waitcnt lgkmcnt(0)
	s_waitcnt lgkmcnt(0)
	v_mfma_f32_16x16x32_bf16 v[92:95], v[208:211], v[176:179], v[92:95]
	v_mfma_f32_16x16x32_bf16 v[88:91], v[216:219], v[176:179], v[88:91]
	v_mfma_f32_16x16x32_bf16 v[84:87], v[208:211], v[184:187], v[84:87]
	v_mfma_f32_16x16x32_bf16 v[80:83], v[216:219], v[184:187], v[80:83]
	v_mfma_f32_16x16x32_bf16 v[76:79], v[208:211], v[192:195], v[76:79]
	v_mfma_f32_16x16x32_bf16 v[72:75], v[216:219], v[192:195], v[72:75]
	v_mfma_f32_16x16x32_bf16 v[68:71], v[208:211], v[200:203], v[68:71]
	v_mfma_f32_16x16x32_bf16 v[92:95], v[212:215], v[180:183], v[92:95]
	v_mfma_f32_16x16x32_bf16 v[88:91], v[166:169], v[180:183], v[88:91]
	v_mfma_f32_16x16x32_bf16 v[84:87], v[212:215], v[188:191], v[84:87]
	v_mfma_f32_16x16x32_bf16 v[80:83], v[166:169], v[188:191], v[80:83]
	v_mfma_f32_16x16x32_bf16 v[76:79], v[212:215], v[196:199], v[76:79]
	v_mfma_f32_16x16x32_bf16 v[176:179], v[166:169], v[196:199], v[72:75]
	v_mfma_f32_16x16x32_bf16 v[68:71], v[212:215], v[204:207], v[68:71]
	v_mfma_f32_16x16x32_bf16 v[64:67], v[216:219], v[200:203], v[64:67]
	v_mfma_f32_16x16x32_bf16 v[180:183], v[166:169], v[204:207], v[64:67]
	s_barrier
	s_nop 4
	ds_read_b128 v[64:67], v147 offset:16384
	ds_read_b128 v[72:75], v147 offset:17408
	ds_read_b128 v[184:187], v146 offset:16384
	ds_read_b128 v[188:191], v146 offset:17408
	ds_read_b128 v[192:195], v145 offset:16384
	ds_read_b128 v[196:199], v145 offset:17408
	ds_read_b128 v[200:203], v144 offset:16384
	ds_read_b128 v[204:207], v144 offset:17408
	s_waitcnt vmcnt(4)
	s_barrier
; #define WAIT_V(n) asm volatile("s_waitcnt vmcnt(" #n ")" ::: "memory")
; #define WAIT_L(n) asm volatile("s_waitcnt lgkmcnt(" #n ")" ::: "memory")
; #define BAR __builtin_amdgcn_s_barrier()
;     ...
;     LDA(At, 0, 1); WAIT_V(4); BAR; WAIT_L(0); MMA(1, 0, At, B0); MMA(1, 1, At, B1); BAR; }
;   { LDB(B0, 1, 0); LDA(At, 1, 0); WAIT_V(2); BAR; WAIT_L(0); MMA(0, 0, At, B0); BAR;
	s_waitcnt lgkmcnt(0)
	s_waitcnt lgkmcnt(0)
	v_mfma_f32_16x16x32_bf16 v[60:63], v[130:133], v[64:67], v[60:63]
	v_mfma_f32_16x16x32_bf16 v[36:39], v[130:133], v[200:203], v[36:39]
	v_mfma_f32_16x16x32_bf16 v[32:35], v[162:165], v[200:203], v[32:35]
	v_mfma_f32_16x16x32_bf16 v[60:63], v[156:159], v[72:75], v[60:63]
	v_mfma_f32_16x16x32_bf16 v[56:59], v[162:165], v[64:67], v[56:59]
	v_mfma_f32_16x16x32_bf16 v[52:55], v[130:133], v[184:187], v[52:55]
	v_mfma_f32_16x16x32_bf16 v[48:51], v[162:165], v[184:187], v[48:51]
	v_mfma_f32_16x16x32_bf16 v[44:47], v[130:133], v[192:195], v[44:47]
	v_mfma_f32_16x16x32_bf16 v[40:43], v[162:165], v[192:195], v[40:43]
	v_mfma_f32_16x16x32_bf16 v[128:131], v[156:159], v[204:207], v[36:39]
	v_mfma_f32_16x16x32_bf16 v[132:135], v[172:175], v[204:207], v[32:35]
	v_mfma_f32_16x16x32_bf16 v[220:223], v[172:175], v[72:75], v[56:59]
	v_mfma_f32_16x16x32_bf16 v[224:227], v[156:159], v[188:191], v[52:55]
	v_mfma_f32_16x16x32_bf16 v[228:231], v[172:175], v[188:191], v[48:51]
	v_mfma_f32_16x16x32_bf16 v[232:235], v[156:159], v[196:199], v[44:47]
	v_mfma_f32_16x16x32_bf16 v[236:239], v[172:175], v[196:199], v[40:43]
	v_mfma_f32_16x16x32_bf16 v[28:31], v[208:211], v[64:67], v[28:31]
	v_mfma_f32_16x16x32_bf16 v[24:27], v[216:219], v[64:67], v[24:27]
	v_mfma_f32_16x16x32_bf16 v[20:23], v[208:211], v[184:187], v[20:23]
	v_mfma_f32_16x16x32_bf16 v[16:19], v[216:219], v[184:187], v[16:19]
	v_mfma_f32_16x16x32_bf16 v[12:15], v[208:211], v[192:195], v[12:15]
	v_mfma_f32_16x16x32_bf16 v[8:11], v[216:219], v[192:195], v[8:11]
	v_mfma_f32_16x16x32_bf16 v[4:7], v[208:211], v[200:203], v[4:7]
	v_mfma_f32_16x16x32_bf16 v[0:3], v[216:219], v[200:203], v[0:3]
	v_mfma_f32_16x16x32_bf16 v[156:159], v[212:215], v[72:75], v[28:31]
	v_mfma_f32_16x16x32_bf16 v[24:27], v[166:169], v[72:75], v[24:27]
	v_mfma_f32_16x16x32_bf16 v[162:165], v[212:215], v[188:191], v[20:23]
	v_mfma_f32_16x16x32_bf16 v[170:173], v[166:169], v[188:191], v[16:19]
	v_mfma_f32_16x16x32_bf16 v[12:15], v[212:215], v[196:199], v[12:15]
	v_mfma_f32_16x16x32_bf16 v[184:187], v[166:169], v[196:199], v[8:11]
	v_mfma_f32_16x16x32_bf16 v[188:191], v[212:215], v[204:207], v[4:7]
	v_mfma_f32_16x16x32_bf16 v[166:169], v[166:169], v[204:207], v[0:3]
	s_barrier
	ds_read_b128 v[192:195], v160
	ds_read_b128 v[196:199], v160 offset:1024
	ds_read_b128 v[200:203], v160 offset:2048
	ds_read_b128 v[204:207], v160 offset:3072
	ds_read_b128 v[32:35], v147 offset:32768
	ds_read_b128 v[48:51], v147 offset:33792
	ds_read_b128 v[52:55], v146 offset:32768
	ds_read_b128 v[64:67], v146 offset:33792
	ds_read_b128 v[208:211], v145 offset:32768
	ds_read_b128 v[212:215], v145 offset:33792
	ds_read_b128 v[216:219], v144 offset:32768
	ds_read_b128 v[240:243], v144 offset:33792
	s_waitcnt vmcnt(2)
	s_barrier
	s_waitcnt lgkmcnt(0)
	s_waitcnt lgkmcnt(0)
	v_mfma_f32_16x16x32_bf16 v[0:3], v[192:195], v[32:35], v[124:127]
	v_mfma_f32_16x16x32_bf16 v[4:7], v[200:203], v[32:35], v[120:123]
	v_mfma_f32_16x16x32_bf16 v[8:11], v[192:195], v[52:55], v[116:119]
	v_mfma_f32_16x16x32_bf16 v[16:19], v[200:203], v[52:55], v[112:115]
	v_mfma_f32_16x16x32_bf16 v[20:23], v[192:195], v[208:211], v[108:111]
	v_mfma_f32_16x16x32_bf16 v[28:31], v[200:203], v[208:211], v[104:107]
	v_mfma_f32_16x16x32_bf16 v[36:39], v[192:195], v[216:219], v[100:103]
	v_mfma_f32_16x16x32_bf16 v[40:43], v[200:203], v[216:219], v[96:99]
	v_mfma_f32_16x16x32_bf16 v[0:3], v[196:199], v[48:51], v[0:3]
	v_mfma_f32_16x16x32_bf16 v[4:7], v[204:207], v[48:51], v[4:7]
	v_mfma_f32_16x16x32_bf16 v[8:11], v[196:199], v[64:67], v[8:11]
	v_mfma_f32_16x16x32_bf16 v[16:19], v[204:207], v[64:67], v[16:19]
	v_mfma_f32_16x16x32_bf16 v[20:23], v[196:199], v[212:215], v[20:23]
	v_mfma_f32_16x16x32_bf16 v[28:31], v[204:207], v[212:215], v[28:31]
	v_mfma_f32_16x16x32_bf16 v[36:39], v[196:199], v[240:243], v[36:39]
	v_mfma_f32_16x16x32_bf16 v[44:47], v[204:207], v[240:243], v[40:43]
	s_barrier
; #define WAIT_V(n) asm volatile("s_waitcnt vmcnt(" #n ")" ::: "memory")
; #define WAIT_L(n) asm volatile("s_waitcnt lgkmcnt(" #n ")" ::: "memory")
; #define BAR __builtin_amdgcn_s_barrier()
;     ...
;   { LDB(B0, 1, 0); LDA(At, 1, 0); WAIT_V(2); BAR; WAIT_L(0); MMA(0, 0, At, B0); BAR;
;     LDB(B1, 1, 1); WAIT_V(0); BAR; WAIT_L(0); MMA(0, 1, At, B1); BAR;
;     LDA(At, 1, 1); BAR; WAIT_L(0); MMA(1, 0, At, B0); MMA(1, 1, At, B1); BAR; }
;   if (wr == 0) BAR;
	ds_read_b128 v[244:247], v155
	ds_read_b128 v[248:251], v155 offset:1024
	ds_read_b128 v[100:103], v155 offset:2048
	ds_read_b128 v[152:155], v155 offset:3072
	s_waitcnt vmcnt(0)
	s_barrier
	s_waitcnt lgkmcnt(0)
	s_waitcnt lgkmcnt(0)
	v_mfma_f32_16x16x32_bf16 v[40:43], v[244:247], v[32:35], v[92:95]
	v_mfma_f32_16x16x32_bf16 v[32:35], v[100:103], v[32:35], v[88:91]
	v_mfma_f32_16x16x32_bf16 v[40:43], v[248:251], v[48:51], v[40:43]
	v_mfma_f32_16x16x32_bf16 v[32:35], v[152:155], v[48:51], v[32:35]
	v_mfma_f32_16x16x32_bf16 v[48:51], v[244:247], v[52:55], v[84:87]
	v_mfma_f32_16x16x32_bf16 v[56:59], v[248:251], v[64:67], v[48:51]
	v_mfma_f32_16x16x32_bf16 v[48:51], v[100:103], v[52:55], v[80:83]
	v_mfma_f32_16x16x32_bf16 v[52:55], v[244:247], v[208:211], v[76:79]
	v_mfma_f32_16x16x32_bf16 v[72:75], v[248:251], v[212:215], v[52:55]
	v_mfma_f32_16x16x32_bf16 v[52:55], v[100:103], v[208:211], v[176:179]
	v_mfma_f32_16x16x32_bf16 v[48:51], v[152:155], v[64:67], v[48:51]
	v_mfma_f32_16x16x32_bf16 v[64:67], v[152:155], v[212:215], v[52:55]
	v_mfma_f32_16x16x32_bf16 v[52:55], v[244:247], v[216:219], v[68:71]
	v_mfma_f32_16x16x32_bf16 v[88:91], v[248:251], v[240:243], v[52:55]
	v_mfma_f32_16x16x32_bf16 v[52:55], v[100:103], v[216:219], v[180:183]
	v_mfma_f32_16x16x32_bf16 v[76:79], v[152:155], v[240:243], v[52:55]
	s_barrier
	ds_read_b128 v[96:99], v147 offset:49152
	ds_read_b128 v[108:111], v147 offset:50176
	ds_read_b128 v[120:123], v146 offset:49152
	ds_read_b128 v[124:127], v146 offset:50176
	ds_read_b128 v[178:181], v145 offset:49152
	ds_read_b128 v[208:211], v145 offset:50176
	ds_read_b128 v[212:215], v144 offset:49152
	ds_read_b128 v[144:147], v144 offset:50176
	s_barrier
	s_waitcnt lgkmcnt(0)
	s_waitcnt lgkmcnt(0)
	v_mfma_f32_16x16x32_bf16 v[104:107], v[192:195], v[212:215], v[128:131]
	v_mfma_f32_16x16x32_bf16 v[52:55], v[192:195], v[96:99], v[60:63]
	v_mfma_f32_16x16x32_bf16 v[60:63], v[200:203], v[96:99], v[220:223]
	v_mfma_f32_16x16x32_bf16 v[68:71], v[192:195], v[120:123], v[224:227]
	v_mfma_f32_16x16x32_bf16 v[80:83], v[200:203], v[120:123], v[228:231]
	v_mfma_f32_16x16x32_bf16 v[84:87], v[192:195], v[178:181], v[232:235]
	v_mfma_f32_16x16x32_bf16 v[92:95], v[200:203], v[178:181], v[236:239]
	v_mfma_f32_16x16x32_bf16 v[174:177], v[196:199], v[144:147], v[104:107]
	v_mfma_f32_16x16x32_bf16 v[104:107], v[200:203], v[212:215], v[132:135]
	v_mfma_f32_16x16x32_bf16 v[52:55], v[196:199], v[108:111], v[52:55]
	v_mfma_f32_16x16x32_bf16 v[60:63], v[204:207], v[108:111], v[60:63]
	v_mfma_f32_16x16x32_bf16 v[68:71], v[196:199], v[124:127], v[68:71]
	v_mfma_f32_16x16x32_bf16 v[80:83], v[204:207], v[124:127], v[80:83]
	v_mfma_f32_16x16x32_bf16 v[84:87], v[196:199], v[208:211], v[84:87]
	v_mfma_f32_16x16x32_bf16 v[92:95], v[204:207], v[208:211], v[92:95]
	v_mfma_f32_16x16x32_bf16 v[112:115], v[204:207], v[144:147], v[104:107]
	v_mfma_f32_16x16x32_bf16 v[24:27], v[100:103], v[96:99], v[24:27]
	v_mfma_f32_16x16x32_bf16 v[104:107], v[244:247], v[96:99], v[156:159]
	v_mfma_f32_16x16x32_bf16 v[96:99], v[152:155], v[108:111], v[24:27]
	v_mfma_f32_16x16x32_bf16 v[24:27], v[244:247], v[120:123], v[162:165]
	v_mfma_f32_16x16x32_bf16 v[116:119], v[248:251], v[124:127], v[24:27]
	v_mfma_f32_16x16x32_bf16 v[24:27], v[100:103], v[120:123], v[170:173]
	v_mfma_f32_16x16x32_bf16 v[12:15], v[244:247], v[178:181], v[12:15]
	v_mfma_f32_16x16x32_bf16 v[104:107], v[248:251], v[108:111], v[104:107]
	v_mfma_f32_16x16x32_bf16 v[108:111], v[152:155], v[124:127], v[24:27]
	v_mfma_f32_16x16x32_bf16 v[124:127], v[248:251], v[208:211], v[12:15]
	v_mfma_f32_16x16x32_bf16 v[12:15], v[100:103], v[178:181], v[184:187]
	v_mfma_f32_16x16x32_bf16 v[120:123], v[152:155], v[208:211], v[12:15]
	v_mfma_f32_16x16x32_bf16 v[12:15], v[244:247], v[212:215], v[188:191]
	v_mfma_f32_16x16x32_bf16 v[132:135], v[248:251], v[144:147], v[12:15]
	v_mfma_f32_16x16x32_bf16 v[12:15], v[100:103], v[212:215], v[166:169]
	v_mfma_f32_16x16x32_bf16 v[128:131], v[152:155], v[144:147], v[12:15]
	v_cmp_gt_u32_e32 vcc, s41, v150
	s_barrier
	s_and_saveexec_b64 s[28:29], vcc
	s_cbranch_execz .LBB0_1145
	s_barrier

; #define WAIT_V(n) asm volatile("s_waitcnt vmcnt(" #n ")" ::: "memory")
; #define BAR __builtin_amdgcn_s_barrier()
;     ...
;   const int wid = tx >> 6, lane = tx & 63, wr = wid >> 2, wc = wid & 3, fr = lane & 15, fq = lane >> 4;
;   f32x4 acc[2][2][4][2] = {};
;   bf16x8 At[4][2], B0[2][2], B1[2][2];
;   const int nt = K / BK;
;   unsigned soff0, soff1;
;   { int _r, _c; stage_rc(tx * 16, _r, _c); soff0 = (unsigned)(_r * K + _c) * 2u;
;     stage_rc(tx * 16 + 8192, _r, _c); soff1 = (unsigned)(_r * K + _c) * 2u; }
;   STAGE(SB(0, 0), Bt, bcol, 0); STAGE(SA(0, 0), A, brow, 0);
;   STAGE(SB(0, 1), Bt, bcol1, 0); STAGE(SA(0, 1), A, brow + HALF, 0);
;   if (wr == 1) BAR;
;   WAIT_V(4); BAR;
;   STAGE(SB(1, 0), Bt, bcol, 1); STAGE(SA(1, 0), A, brow, 1); STAGE(SB(1, 1), Bt, bcol1, 1);
;   WAIT_V(6); BAR;
.LBB0_1235:
	s_or_b64 exec, exec, s[44:45]
	v_add_u32_e32 v162, s59, v15
	v_add_u32_e32 v163, 0x2000, v162
	v_readfirstlane_b32 s4, v162
	v_lshl_add_u64 v[6:7], v[6:7], 0, s[22:23]
	s_mov_b32 m0, s4
	v_readfirstlane_b32 s4, v163
	v_add_u32_e32 v164, 0x8000, v154
	s_waitcnt vmcnt(4)
	s_barrier
	global_load_lds_dwordx4 v[6:7], off
	v_lshl_add_u64 v[4:5], v[4:5], 0, s[22:23]
	s_mov_b32 m0, s4
	v_readfirstlane_b32 s4, v164
	v_add_u32_e32 v165, 0xa000, v154
	global_load_lds_dwordx4 v[4:5], off
	v_lshl_add_u64 v[2:3], v[2:3], 0, s[22:23]
	s_mov_b32 m0, s4
	v_readfirstlane_b32 s4, v165
	global_load_lds_dwordx4 v[2:3], off
	s_mov_b32 m0, s4
	s_add_u32 s4, s7, 0x5600080
	v_add_u32_e32 v168, s60, v15
	v_lshl_add_u64 v[0:1], v[0:1], 0, s[22:23]
	s_addc_u32 s5, s47, 0
	v_readfirstlane_b32 s7, v168
	global_load_lds_dwordx4 v[0:1], off
	v_lshl_add_u64 v[0:1], s[4:5], 0, v[148:149]
	s_mov_b32 m0, s7
	v_add_u32_e32 v171, 0x2000, v168
	global_load_lds_dwordx4 v[0:1], off
	v_lshl_add_u64 v[0:1], s[4:5], 0, v[128:129]
	v_readfirstlane_b32 s4, v171
	s_mov_b32 m0, s4
	v_and_b32_e32 v169, 15, v9
	global_load_lds_dwordx4 v[0:1], off
	v_bfe_u32 v146, v9, 4, 2
	v_lshlrev_b32_e32 v1, 2, v9
	v_lshlrev_b32_e32 v147, 4, v146
	v_lshlrev_b32_e32 v0, 6, v169
	v_and_b32_e32 v1, 32, v1
	v_bitop3_b32 v0, v147, v1, v0 bitop3:0x36
	v_add_u32_e32 v5, s33, v0
	v_add_u32_e32 v6, s58, v0
	v_add_u32_e32 v7, s59, v0
	v_add_u32_e32 v15, s60, v0
	v_add_u32_e32 v17, 0, v0
	v_lshlrev_b32_e32 v0, 6, v9
	v_and_or_b32 v0, v0, s83, v147
	v_xad_u32 v9, v0, v1, 0
	v_lshlrev_b32_e32 v0, 16, v8
	v_lshlrev_b32_e32 v2, 16, v11
	v_and_b32_e32 v0, 0xfffe0000, v0
	v_and_b32_e32 v2, 0xfffe0000, v2
	v_lshl_add_u32 v0, v10, 13, v0
	v_and_b32_e32 v1, 1, v8
	v_lshl_add_u32 v2, v13, 13, v2
	v_and_b32_e32 v3, 1, v11
	v_lshl_or_b32 v0, v1, 6, v0
	s_add_u32 s4, s20, s12
	v_lshl_or_b32 v2, v3, 6, v2
	v_lshl_add_u32 v0, v12, 1, v0
	v_mov_b32_e32 v1, v149
	s_addc_u32 s5, s21, s13
	v_lshl_add_u32 v2, v14, 1, v2
	v_mov_b32_e32 v3, v149
	v_lshl_add_u64 v[130:131], s[4:5], 0, v[0:1]
	v_lshl_add_u64 v[132:133], s[4:5], 0, v[2:3]
	s_add_u32 s4, s18, s14
	s_addc_u32 s5, s19, s15
	v_lshl_add_u64 v[134:135], s[4:5], 0, v[0:1]
	v_lshl_add_u64 v[136:137], s[4:5], 0, v[2:3]
	s_add_u32 s4, s20, s42
	v_bfe_u32 v144, v145, 6, 2
	s_waitcnt vmcnt(6)
	v_lshlrev_b32_e32 v16, 13, v167
	s_addc_u32 s5, s21, s43
	v_lshlrev_b32_e32 v4, 12, v144
	v_or_b32_e32 v18, 0x800, v16
	v_or_b32_e32 v19, 0x1000, v16
	v_or_b32_e32 v20, 0x1800, v16
	v_lshl_add_u64 v[138:139], s[4:5], 0, v[0:1]
	v_mov_b32_e32 v0, 0
	v_lshlrev_b32_e32 v170, 6, v167
	v_lshl_add_u64 v[140:141], s[4:5], 0, v[2:3]
	s_mov_b32 s7, -2
	s_mov_b64 s[4:5], 0
	v_add_u32_e32 v173, v5, v4
	v_add_u32_e32 v153, v17, v16
	v_add_u32_e32 v152, v9, v18
	v_add_u32_e32 v151, v9, v19
	v_add_u32_e32 v150, v9, v20
	v_add_u32_e32 v172, v6, v4
	v_add_u32_e32 v161, v7, v4
	v_add_u32_e32 v156, v15, v4
	v_mov_b32_e32 v1, v0
	v_mov_b32_e32 v2, v0
	v_mov_b32_e32 v3, v0
	v_mov_b32_e32 v4, v0
	v_mov_b32_e32 v5, v0
	v_mov_b32_e32 v6, v0
	v_mov_b32_e32 v7, v0
	v_mov_b32_e32 v8, v0
	v_mov_b32_e32 v9, v0
	v_mov_b32_e32 v10, v0
	v_mov_b32_e32 v11, v0
	v_mov_b32_e32 v12, v0
	v_mov_b32_e32 v13, v0
	v_mov_b32_e32 v14, v0
	v_mov_b32_e32 v15, v0
	v_mov_b32_e32 v16, v0
	v_mov_b32_e32 v17, v0
	v_mov_b32_e32 v18, v0
	v_mov_b32_e32 v19, v0
	v_mov_b32_e32 v20, v0
	v_mov_b32_e32 v21, v0
	v_mov_b32_e32 v22, v0
	v_mov_b32_e32 v23, v0
	v_mov_b32_e32 v24, v0
	v_mov_b32_e32 v25, v0
	v_mov_b32_e32 v26, v0
	v_mov_b32_e32 v27, v0
	v_mov_b32_e32 v28, v0
	v_mov_b32_e32 v29, v0
	v_mov_b32_e32 v30, v0
	v_mov_b32_e32 v31, v0
	v_mov_b32_e32 v32, v0
	v_mov_b32_e32 v33, v0
	v_mov_b32_e32 v34, v0
	v_mov_b32_e32 v35, v0
	v_mov_b32_e32 v36, v0
	v_mov_b32_e32 v37, v0
	v_mov_b32_e32 v38, v0
	v_mov_b32_e32 v39, v0
	v_mov_b32_e32 v40, v0
	v_mov_b32_e32 v41, v0
	v_mov_b32_e32 v42, v0
	v_mov_b32_e32 v43, v0
	v_mov_b32_e32 v44, v0
	v_mov_b32_e32 v45, v0
	v_mov_b32_e32 v46, v0
	v_mov_b32_e32 v47, v0
	v_mov_b32_e32 v48, v0
	v_mov_b32_e32 v49, v0
	v_mov_b32_e32 v50, v0
	v_mov_b32_e32 v51, v0
	v_mov_b32_e32 v52, v0
	v_mov_b32_e32 v53, v0
	v_mov_b32_e32 v54, v0
	v_mov_b32_e32 v55, v0
	v_mov_b32_e32 v56, v0
	v_mov_b32_e32 v57, v0
	v_mov_b32_e32 v58, v0
	v_mov_b32_e32 v59, v0
	v_mov_b32_e32 v60, v0
	v_mov_b32_e32 v61, v0
	v_mov_b32_e32 v62, v0
	v_mov_b32_e32 v63, v0
	v_mov_b32_e32 v64, v0
	v_mov_b32_e32 v65, v0
	v_mov_b32_e32 v66, v0
	v_mov_b32_e32 v67, v0
	v_mov_b32_e32 v68, v0
	v_mov_b32_e32 v69, v0
	v_mov_b32_e32 v70, v0
	v_mov_b32_e32 v71, v0
	v_mov_b32_e32 v72, v0
	v_mov_b32_e32 v73, v0
	v_mov_b32_e32 v74, v0
	v_mov_b32_e32 v75, v0
	v_mov_b32_e32 v76, v0
	v_mov_b32_e32 v77, v0
	v_mov_b32_e32 v78, v0
	v_mov_b32_e32 v79, v0
	v_mov_b32_e32 v80, v0
	v_mov_b32_e32 v81, v0
	v_mov_b32_e32 v82, v0
	v_mov_b32_e32 v83, v0
	v_mov_b32_e32 v84, v0
	v_mov_b32_e32 v85, v0
	v_mov_b32_e32 v86, v0
	v_mov_b32_e32 v87, v0
	v_mov_b32_e32 v88, v0
	v_mov_b32_e32 v89, v0
	v_mov_b32_e32 v90, v0
	v_mov_b32_e32 v91, v0
	v_mov_b32_e32 v92, v0
	v_mov_b32_e32 v93, v0
	v_mov_b32_e32 v94, v0
	v_mov_b32_e32 v95, v0
	v_mov_b32_e32 v96, v0
	v_mov_b32_e32 v97, v0
	v_mov_b32_e32 v98, v0
	v_mov_b32_e32 v99, v0
	v_mov_b32_e32 v100, v0
	v_mov_b32_e32 v101, v0
	v_mov_b32_e32 v102, v0
	v_mov_b32_e32 v103, v0
	v_mov_b32_e32 v104, v0
	v_mov_b32_e32 v105, v0
	v_mov_b32_e32 v106, v0
	v_mov_b32_e32 v107, v0
	v_mov_b32_e32 v108, v0
	v_mov_b32_e32 v109, v0
	v_mov_b32_e32 v110, v0
	v_mov_b32_e32 v111, v0
	v_mov_b32_e32 v112, v0
	v_mov_b32_e32 v113, v0
	v_mov_b32_e32 v114, v0
	v_mov_b32_e32 v115, v0
	v_mov_b32_e32 v116, v0
	v_mov_b32_e32 v117, v0
	v_mov_b32_e32 v118, v0
	v_mov_b32_e32 v119, v0
	v_mov_b32_e32 v120, v0
	v_mov_b32_e32 v121, v0
	v_mov_b32_e32 v122, v0
	v_mov_b32_e32 v123, v0
	v_mov_b32_e32 v124, v0
	v_mov_b32_e32 v125, v0
	v_mov_b32_e32 v126, v0
	v_mov_b32_e32 v127, v0
	s_barrier
; #define WAIT_L(n) asm volatile("s_waitcnt lgkmcnt(" #n ")" ::: "memory")
; #define BAR __builtin_amdgcn_s_barrier()
; #define SCHED __builtin_amdgcn_sched_barrier(0)
;     ...
;   for (int t = 0; t < nt - 2; t += 2) {
;     LDB(B0, 0, 0); SCHED; LDA(At, 0, 0); STAGE(SA(1, 1), A, brow + HALF, t + 1);
;     WAIT_L(8); BAR; WAIT_L(0); MMA(0, 0, At, B0); BAR; SCHED;
	v_readfirstlane_b32 s12, v154
	v_writelane_b32 v254, s64, 0
	v_writelane_b32 v254, s65, 1
	v_writelane_b32 v254, s66, 2
	v_writelane_b32 v254, s67, 3
	v_writelane_b32 v254, s68, 4
	v_writelane_b32 v254, s69, 5
	v_writelane_b32 v254, s70, 6
	v_writelane_b32 v254, s71, 7
	v_writelane_b32 v254, s72, 8
	v_writelane_b32 v254, s73, 9
	v_writelane_b32 v254, s74, 10
	v_writelane_b32 v254, s75, 11
	v_writelane_b32 v254, s76, 12
	v_writelane_b32 v254, s77, 13
	v_writelane_b32 v254, s78, 14
	v_writelane_b32 v254, s79, 15
	v_writelane_b32 v254, s80, 16
	v_writelane_b32 v254, s81, 17
	v_writelane_b32 v254, s82, 18
	v_writelane_b32 v254, s83, 19
	v_writelane_b32 v254, s84, 20
	v_writelane_b32 v254, s85, 21
	v_writelane_b32 v254, s86, 22
	v_writelane_b32 v254, s87, 23
	v_writelane_b32 v254, s88, 24
	v_writelane_b32 v254, s89, 25
	v_writelane_b32 v254, s90, 26
	v_writelane_b32 v254, s91, 27
	v_writelane_b32 v254, s92, 28
	v_writelane_b32 v254, s93, 29
	v_writelane_b32 v254, s94, 30
	v_writelane_b32 v254, s95, 31
	v_readfirstlane_b32 s64, v134
	v_readfirstlane_b32 s65, v135
	v_readfirstlane_b32 s66, v136
	v_readfirstlane_b32 s67, v137
	v_readfirstlane_b32 s68, v130
	v_readfirstlane_b32 s69, v131
	v_readfirstlane_b32 s70, v132
	v_readfirstlane_b32 s71, v133
	v_readfirstlane_b32 s72, v134
	v_readfirstlane_b32 s73, v135
	v_readfirstlane_b32 s74, v136
	v_readfirstlane_b32 s75, v137
	v_readfirstlane_b32 s76, v138
	v_readfirstlane_b32 s77, v139
	v_readfirstlane_b32 s78, v140
	v_readfirstlane_b32 s79, v141
	v_readfirstlane_b32 s80, v134
	v_readfirstlane_b32 s81, v135
	v_readfirstlane_b32 s82, v136
	v_readfirstlane_b32 s83, v137
	v_readfirstlane_b32 s84, v130
	v_readfirstlane_b32 s85, v131
	v_readfirstlane_b32 s86, v132
	v_readfirstlane_b32 s87, v133
	v_readfirstlane_b32 s88, v134
	v_readfirstlane_b32 s89, v135
	v_readfirstlane_b32 s90, v136
	v_readfirstlane_b32 s91, v137
	v_readfirstlane_b32 s92, v138
	v_readfirstlane_b32 s93, v139
	v_readfirstlane_b32 s94, v140
	v_readfirstlane_b32 s95, v141
	s_nop 3
	v_subrev_u32_e32 v159, s64, v134
	v_subrev_u32_e32 v160, s66, v136
	v_subrev_u32_e32 v157, s68, v130
	v_subrev_u32_e32 v158, s70, v132
	v_subrev_u32_e32 v162, s76, v138
	v_subrev_u32_e32 v163, s78, v140
	s_add_u32 s64, s64, s4
	s_addc_u32 s65, s65, s5
	s_add_u32 s64, s64, s24
	s_addc_u32 s65, s65, s25
	s_add_u32 s66, s66, s4
	s_addc_u32 s67, s67, s5
	s_add_u32 s66, s66, s24
	s_addc_u32 s67, s67, s25
	s_add_u32 s68, s68, s4
	s_addc_u32 s69, s69, s5
	s_add_u32 s68, s68, s26
	s_addc_u32 s69, s69, s27
	s_add_u32 s70, s70, s4
	s_addc_u32 s71, s71, s5
	s_add_u32 s70, s70, s26
	s_addc_u32 s71, s71, s27
	s_add_u32 s72, s72, s4
	s_addc_u32 s73, s73, s5
	s_add_u32 s72, s72, s26
	s_addc_u32 s73, s73, s27
	s_add_u32 s74, s74, s4
	s_addc_u32 s75, s75, s5
	s_add_u32 s74, s74, s26
	s_addc_u32 s75, s75, s27
	s_add_u32 s76, s76, s4
	s_addc_u32 s77, s77, s5
	s_add_u32 s76, s76, s28
	s_addc_u32 s77, s77, s29
	s_add_u32 s78, s78, s4
	s_addc_u32 s79, s79, s5
	s_add_u32 s78, s78, s28
	s_addc_u32 s79, s79, s29
	s_add_u32 s80, s80, s4
	s_addc_u32 s81, s81, s5
	s_add_u32 s80, s80, s30
	s_addc_u32 s81, s81, s31
	s_add_u32 s82, s82, s4
	s_addc_u32 s83, s83, s5
	s_add_u32 s82, s82, s30
	s_addc_u32 s83, s83, s31
	s_add_u32 s84, s84, s4
	s_addc_u32 s85, s85, s5
	s_add_u32 s84, s84, s34
	s_addc_u32 s85, s85, s35
	s_add_u32 s86, s86, s4
	s_addc_u32 s87, s87, s5
	s_add_u32 s86, s86, s34
	s_addc_u32 s87, s87, s35
	s_add_u32 s88, s88, s4
	s_addc_u32 s89, s89, s5
	s_add_u32 s88, s88, s34
	s_addc_u32 s89, s89, s35
	s_add_u32 s90, s90, s4
	s_addc_u32 s91, s91, s5
	s_add_u32 s90, s90, s34
	s_addc_u32 s91, s91, s35
	s_add_u32 s92, s92, s4
	s_addc_u32 s93, s93, s5
	s_add_u32 s92, s92, s36
	s_addc_u32 s93, s93, s37
	s_add_u32 s94, s94, s4
	s_addc_u32 s95, s95, s5
	s_add_u32 s94, s94, s36
	s_addc_u32 s95, s95, s37
	v_add_u32_e32 v174, 0xc000, v154
	v_add_u32_e32 v175, 0xe000, v154
.LBB0_1236:
	ds_read_b128 v[176:179], v173
	ds_read_b128 v[180:183], v173 offset:1024
	ds_read_b128 v[184:187], v173 offset:2048
	ds_read_b128 v[188:191], v173 offset:3072
	s_add_u32 m0, s12, 0xc000
	ds_read_b128 v[192:195], v153
	ds_read_b128 v[196:199], v153 offset:1024
	ds_read_b128 v[200:203], v152
	ds_read_b128 v[204:207], v152 offset:1024
	ds_read_b128 v[208:211], v151
	ds_read_b128 v[212:215], v151 offset:1024
	ds_read_b128 v[216:219], v150
	ds_read_b128 v[220:223], v150 offset:1024
	global_load_lds_dwordx4 v159, s[64:65]
	s_add_u32 s64, s64, 0x100
	s_addc_u32 s65, s65, 0
	s_add_u32 m0, s12, 0xe000
	s_nop 0
	global_load_lds_dwordx4 v160, s[66:67]
	s_add_u32 s66, s66, 0x100
	s_addc_u32 s67, s67, 0
	s_waitcnt lgkmcnt(8)
	s_barrier
	s_waitcnt lgkmcnt(0)
	v_mfma_f32_16x16x32_bf16 v[124:127], v[176:179], v[192:195], v[124:127]
	v_mfma_f32_16x16x32_bf16 v[120:123], v[184:187], v[192:195], v[120:123]
	v_mfma_f32_16x16x32_bf16 v[116:119], v[176:179], v[200:203], v[116:119]
	v_mfma_f32_16x16x32_bf16 v[112:115], v[184:187], v[200:203], v[112:115]
	v_mfma_f32_16x16x32_bf16 v[108:111], v[176:179], v[208:211], v[108:111]
	v_mfma_f32_16x16x32_bf16 v[104:107], v[184:187], v[208:211], v[104:107]
	v_mfma_f32_16x16x32_bf16 v[100:103], v[176:179], v[216:219], v[100:103]
	v_mfma_f32_16x16x32_bf16 v[96:99], v[184:187], v[216:219], v[96:99]
	v_mfma_f32_16x16x32_bf16 v[124:127], v[180:183], v[196:199], v[124:127]
	v_mfma_f32_16x16x32_bf16 v[120:123], v[188:191], v[196:199], v[120:123]
	v_mfma_f32_16x16x32_bf16 v[116:119], v[180:183], v[204:207], v[116:119]
	v_mfma_f32_16x16x32_bf16 v[112:115], v[188:191], v[204:207], v[112:115]
	v_mfma_f32_16x16x32_bf16 v[108:111], v[180:183], v[212:215], v[108:111]
	v_mfma_f32_16x16x32_bf16 v[104:107], v[188:191], v[212:215], v[104:107]
	v_mfma_f32_16x16x32_bf16 v[100:103], v[180:183], v[220:223], v[100:103]
	v_mfma_f32_16x16x32_bf16 v[96:99], v[188:191], v[220:223], v[96:99]
	s_barrier
; #define WAIT_V(n) asm volatile("s_waitcnt vmcnt(" #n ")" ::: "memory")
; #define WAIT_L(n) asm volatile("s_waitcnt lgkmcnt(" #n ")" ::: "memory")
; #define BAR __builtin_amdgcn_s_barrier()
; #define SCHED __builtin_amdgcn_sched_barrier(0)
;     ...
;     LDB(B1, 0, 1); STAGE(SB(0, 0), Bt, bcol, t + 2);
;     BAR; WAIT_L(0); MMA(0, 1, At, B1); BAR;
;     LDA(At, 0, 1); STAGE(SA(0, 0), A, brow, t + 2);
;     BAR; WAIT_L(0); MMA(1, 0, At, B0); BAR; SCHED;
;     STAGE(SB(0, 1), Bt, bcol1, t + 2);
;     WAIT_V(6); BAR; MMA(1, 1, At, B1); BAR;
;     LDB(B0, 1, 0); SCHED; LDA(At, 1, 0); STAGE(SA(0, 1), A, brow + HALF, t + 2);
;     WAIT_L(8); BAR; WAIT_L(0); MMA(0, 0, At, B0); BAR; SCHED;
	s_add_u32 m0, s12, s33
	ds_read_b128 v[224:227], v172
	ds_read_b128 v[228:231], v172 offset:1024
	ds_read_b128 v[232:235], v172 offset:2048
	ds_read_b128 v[236:239], v172 offset:3072
	global_load_lds_dwordx4 v157, s[68:69]
	s_add_u32 s68, s68, 0x100
	s_addc_u32 s69, s69, 0
	s_add_u32 m0, s12, 0x2000
	s_add_u32 m0, m0, s33
	s_nop 0
	global_load_lds_dwordx4 v158, s[70:71]
	s_add_u32 s70, s70, 0x100
	s_addc_u32 s71, s71, 0
	s_barrier
	s_waitcnt lgkmcnt(0)
	v_mfma_f32_16x16x32_bf16 v[92:95], v[224:227], v[192:195], v[92:95]
	v_mfma_f32_16x16x32_bf16 v[88:91], v[232:235], v[192:195], v[88:91]
	v_mfma_f32_16x16x32_bf16 v[84:87], v[224:227], v[200:203], v[84:87]
	v_mfma_f32_16x16x32_bf16 v[80:83], v[232:235], v[200:203], v[80:83]
	v_mfma_f32_16x16x32_bf16 v[76:79], v[224:227], v[208:211], v[76:79]
	v_mfma_f32_16x16x32_bf16 v[72:75], v[232:235], v[208:211], v[72:75]
	v_mfma_f32_16x16x32_bf16 v[68:71], v[224:227], v[216:219], v[68:71]
	v_mfma_f32_16x16x32_bf16 v[64:67], v[232:235], v[216:219], v[64:67]
	v_mfma_f32_16x16x32_bf16 v[92:95], v[228:231], v[196:199], v[92:95]
	v_mfma_f32_16x16x32_bf16 v[88:91], v[236:239], v[196:199], v[88:91]
	v_mfma_f32_16x16x32_bf16 v[84:87], v[228:231], v[204:207], v[84:87]
	v_mfma_f32_16x16x32_bf16 v[80:83], v[236:239], v[204:207], v[80:83]
	v_mfma_f32_16x16x32_bf16 v[76:79], v[228:231], v[212:215], v[76:79]
	v_mfma_f32_16x16x32_bf16 v[72:75], v[236:239], v[212:215], v[72:75]
	v_mfma_f32_16x16x32_bf16 v[68:71], v[228:231], v[220:223], v[68:71]
	v_mfma_f32_16x16x32_bf16 v[64:67], v[236:239], v[220:223], v[64:67]
	s_mov_b32 m0, s12
	s_barrier
	ds_read_b128 v[192:195], v153 offset:16384
	ds_read_b128 v[196:199], v153 offset:17408
	ds_read_b128 v[200:203], v152 offset:16384
	ds_read_b128 v[204:207], v152 offset:17408
	ds_read_b128 v[208:211], v151 offset:16384
	ds_read_b128 v[212:215], v151 offset:17408
	ds_read_b128 v[216:219], v150 offset:16384
	ds_read_b128 v[220:223], v150 offset:17408
	global_load_lds_dwordx4 v159, s[72:73]
	s_add_u32 s72, s72, 0x100
	s_addc_u32 s73, s73, 0
	s_add_u32 m0, s12, 0x2000
	s_nop 0
	global_load_lds_dwordx4 v160, s[74:75]
	s_add_u32 s74, s74, 0x100
	s_addc_u32 s75, s75, 0
	s_barrier
	s_waitcnt lgkmcnt(0)
	v_mfma_f32_16x16x32_bf16 v[60:63], v[176:179], v[192:195], v[60:63]
	v_mfma_f32_16x16x32_bf16 v[56:59], v[184:187], v[192:195], v[56:59]
	v_mfma_f32_16x16x32_bf16 v[52:55], v[176:179], v[200:203], v[52:55]
	v_mfma_f32_16x16x32_bf16 v[48:51], v[184:187], v[200:203], v[48:51]
	v_mfma_f32_16x16x32_bf16 v[44:47], v[176:179], v[208:211], v[44:47]
	v_mfma_f32_16x16x32_bf16 v[40:43], v[184:187], v[208:211], v[40:43]
	v_mfma_f32_16x16x32_bf16 v[36:39], v[176:179], v[216:219], v[36:39]
	v_mfma_f32_16x16x32_bf16 v[32:35], v[184:187], v[216:219], v[32:35]
	v_mfma_f32_16x16x32_bf16 v[60:63], v[180:183], v[196:199], v[60:63]
	v_mfma_f32_16x16x32_bf16 v[56:59], v[188:191], v[196:199], v[56:59]
	v_mfma_f32_16x16x32_bf16 v[52:55], v[180:183], v[204:207], v[52:55]
	v_mfma_f32_16x16x32_bf16 v[48:51], v[188:191], v[204:207], v[48:51]
	v_mfma_f32_16x16x32_bf16 v[44:47], v[180:183], v[212:215], v[44:47]
	v_mfma_f32_16x16x32_bf16 v[40:43], v[188:191], v[212:215], v[40:43]
	v_mfma_f32_16x16x32_bf16 v[36:39], v[180:183], v[220:223], v[36:39]
	v_mfma_f32_16x16x32_bf16 v[32:35], v[188:191], v[220:223], v[32:35]
	s_barrier
	s_add_u32 m0, s12, s58
	s_nop 0
	global_load_lds_dwordx4 v162, s[76:77]
	s_add_u32 s76, s76, 0x100
	s_addc_u32 s77, s77, 0
	s_add_u32 m0, s12, 0x2000
	s_add_u32 m0, m0, s58
	s_nop 0
	global_load_lds_dwordx4 v163, s[78:79]
	s_add_u32 s78, s78, 0x100
	s_addc_u32 s79, s79, 0
	s_waitcnt vmcnt(6)
	s_barrier
	v_mfma_f32_16x16x32_bf16 v[28:31], v[224:227], v[192:195], v[28:31]
	v_mfma_f32_16x16x32_bf16 v[24:27], v[232:235], v[192:195], v[24:27]
	v_mfma_f32_16x16x32_bf16 v[20:23], v[224:227], v[200:203], v[20:23]
	v_mfma_f32_16x16x32_bf16 v[16:19], v[232:235], v[200:203], v[16:19]
	v_mfma_f32_16x16x32_bf16 v[12:15], v[224:227], v[208:211], v[12:15]
	v_mfma_f32_16x16x32_bf16 v[8:11], v[232:235], v[208:211], v[8:11]
	v_mfma_f32_16x16x32_bf16 v[4:7], v[224:227], v[216:219], v[4:7]
	v_mfma_f32_16x16x32_bf16 v[0:3], v[232:235], v[216:219], v[0:3]
	v_mfma_f32_16x16x32_bf16 v[28:31], v[228:231], v[196:199], v[28:31]
	v_mfma_f32_16x16x32_bf16 v[24:27], v[236:239], v[196:199], v[24:27]
	v_mfma_f32_16x16x32_bf16 v[20:23], v[228:231], v[204:207], v[20:23]
	v_mfma_f32_16x16x32_bf16 v[16:19], v[236:239], v[204:207], v[16:19]
	v_mfma_f32_16x16x32_bf16 v[12:15], v[228:231], v[212:215], v[12:15]
	v_mfma_f32_16x16x32_bf16 v[8:11], v[236:239], v[212:215], v[8:11]
	v_mfma_f32_16x16x32_bf16 v[4:7], v[228:231], v[220:223], v[4:7]
	v_mfma_f32_16x16x32_bf16 v[0:3], v[236:239], v[220:223], v[0:3]
	s_barrier
	ds_read_b128 v[176:179], v161
	ds_read_b128 v[180:183], v161 offset:1024
	ds_read_b128 v[184:187], v161 offset:2048
	ds_read_b128 v[188:191], v161 offset:3072
	s_add_u32 m0, s12, 0x4000
	ds_read_b128 v[192:195], v153 offset:32768
	ds_read_b128 v[196:199], v153 offset:33792
	ds_read_b128 v[200:203], v152 offset:32768
	ds_read_b128 v[204:207], v152 offset:33792
	ds_read_b128 v[208:211], v151 offset:32768
	ds_read_b128 v[212:215], v151 offset:33792
	ds_read_b128 v[216:219], v150 offset:32768
	ds_read_b128 v[220:223], v150 offset:33792
	global_load_lds_dwordx4 v159, s[80:81]
	s_add_u32 s80, s80, 0x100
	s_addc_u32 s81, s81, 0
	s_add_u32 m0, s12, 0x6000
	s_nop 0
	global_load_lds_dwordx4 v160, s[82:83]
	s_add_u32 s82, s82, 0x100
	s_addc_u32 s83, s83, 0
	s_waitcnt lgkmcnt(8)
	s_barrier
; #define WAIT_V(n) asm volatile("s_waitcnt vmcnt(" #n ")" ::: "memory")
; #define WAIT_L(n) asm volatile("s_waitcnt lgkmcnt(" #n ")" ::: "memory")
; #define BAR __builtin_amdgcn_s_barrier()
; #define SCHED __builtin_amdgcn_sched_barrier(0)
;     ...
;     WAIT_L(8); BAR; WAIT_L(0); MMA(0, 0, At, B0); BAR; SCHED;
;     LDB(B1, 1, 1); STAGE(SB(1, 0), Bt, bcol, t + 3);
;     BAR; WAIT_L(0); MMA(0, 1, At, B1); BAR;
;     LDA(At, 1, 1); STAGE(SA(1, 0), A, brow, t + 3);
;     BAR; WAIT_L(0); MMA(1, 0, At, B0); BAR; SCHED;
;     STAGE(SB(1, 1), Bt, bcol1, t + 3);
;     WAIT_V(6); BAR; MMA(1, 1, At, B1); BAR;
	s_waitcnt lgkmcnt(0)
	v_mfma_f32_16x16x32_bf16 v[124:127], v[176:179], v[192:195], v[124:127]
	v_mfma_f32_16x16x32_bf16 v[120:123], v[184:187], v[192:195], v[120:123]
	v_mfma_f32_16x16x32_bf16 v[116:119], v[176:179], v[200:203], v[116:119]
	v_mfma_f32_16x16x32_bf16 v[112:115], v[184:187], v[200:203], v[112:115]
	v_mfma_f32_16x16x32_bf16 v[108:111], v[176:179], v[208:211], v[108:111]
	v_mfma_f32_16x16x32_bf16 v[104:107], v[184:187], v[208:211], v[104:107]
	v_mfma_f32_16x16x32_bf16 v[100:103], v[176:179], v[216:219], v[100:103]
	v_mfma_f32_16x16x32_bf16 v[96:99], v[184:187], v[216:219], v[96:99]
	v_mfma_f32_16x16x32_bf16 v[124:127], v[180:183], v[196:199], v[124:127]
	v_mfma_f32_16x16x32_bf16 v[120:123], v[188:191], v[196:199], v[120:123]
	v_mfma_f32_16x16x32_bf16 v[116:119], v[180:183], v[204:207], v[116:119]
	v_mfma_f32_16x16x32_bf16 v[112:115], v[188:191], v[204:207], v[112:115]
	v_mfma_f32_16x16x32_bf16 v[108:111], v[180:183], v[212:215], v[108:111]
	v_mfma_f32_16x16x32_bf16 v[104:107], v[188:191], v[212:215], v[104:107]
	v_mfma_f32_16x16x32_bf16 v[100:103], v[180:183], v[220:223], v[100:103]
	v_mfma_f32_16x16x32_bf16 v[96:99], v[188:191], v[220:223], v[96:99]
	s_barrier
	s_add_u32 m0, s12, s59
	ds_read_b128 v[224:227], v156
	ds_read_b128 v[228:231], v156 offset:1024
	ds_read_b128 v[232:235], v156 offset:2048
	ds_read_b128 v[236:239], v156 offset:3072
	global_load_lds_dwordx4 v157, s[84:85]
	s_add_u32 s84, s84, 0x100
	s_addc_u32 s85, s85, 0
	s_add_u32 m0, s12, 0x2000
	s_add_u32 m0, m0, s59
	s_nop 0
	global_load_lds_dwordx4 v158, s[86:87]
	s_add_u32 s86, s86, 0x100
	s_addc_u32 s87, s87, 0
	s_barrier
	s_waitcnt lgkmcnt(0)
	v_mfma_f32_16x16x32_bf16 v[92:95], v[224:227], v[192:195], v[92:95]
	v_mfma_f32_16x16x32_bf16 v[88:91], v[232:235], v[192:195], v[88:91]
	v_mfma_f32_16x16x32_bf16 v[84:87], v[224:227], v[200:203], v[84:87]
	v_mfma_f32_16x16x32_bf16 v[80:83], v[232:235], v[200:203], v[80:83]
	v_mfma_f32_16x16x32_bf16 v[76:79], v[224:227], v[208:211], v[76:79]
	v_mfma_f32_16x16x32_bf16 v[72:75], v[232:235], v[208:211], v[72:75]
	v_mfma_f32_16x16x32_bf16 v[68:71], v[224:227], v[216:219], v[68:71]
	v_mfma_f32_16x16x32_bf16 v[64:67], v[232:235], v[216:219], v[64:67]
	v_mfma_f32_16x16x32_bf16 v[92:95], v[228:231], v[196:199], v[92:95]
	v_mfma_f32_16x16x32_bf16 v[88:91], v[236:239], v[196:199], v[88:91]
	v_mfma_f32_16x16x32_bf16 v[84:87], v[228:231], v[204:207], v[84:87]
	v_mfma_f32_16x16x32_bf16 v[80:83], v[236:239], v[204:207], v[80:83]
	v_mfma_f32_16x16x32_bf16 v[76:79], v[228:231], v[212:215], v[76:79]
	v_mfma_f32_16x16x32_bf16 v[72:75], v[236:239], v[212:215], v[72:75]
	v_mfma_f32_16x16x32_bf16 v[68:71], v[228:231], v[220:223], v[68:71]
	v_mfma_f32_16x16x32_bf16 v[64:67], v[236:239], v[220:223], v[64:67]
	s_add_u32 m0, s12, 0x8000
	s_barrier
	ds_read_b128 v[192:195], v153 offset:49152
	ds_read_b128 v[196:199], v153 offset:50176
	ds_read_b128 v[200:203], v152 offset:49152
	ds_read_b128 v[204:207], v152 offset:50176
	ds_read_b128 v[208:211], v151 offset:49152
	ds_read_b128 v[212:215], v151 offset:50176
	ds_read_b128 v[216:219], v150 offset:49152
	ds_read_b128 v[220:223], v150 offset:50176
	global_load_lds_dwordx4 v159, s[88:89]
	s_add_u32 s88, s88, 0x100
	s_addc_u32 s89, s89, 0
	s_add_u32 m0, s12, 0xa000
	s_nop 0
	global_load_lds_dwordx4 v160, s[90:91]
	s_add_u32 s90, s90, 0x100
	s_addc_u32 s91, s91, 0
	s_barrier
	s_waitcnt lgkmcnt(0)
	v_mfma_f32_16x16x32_bf16 v[60:63], v[176:179], v[192:195], v[60:63]
	v_mfma_f32_16x16x32_bf16 v[56:59], v[184:187], v[192:195], v[56:59]
	v_mfma_f32_16x16x32_bf16 v[52:55], v[176:179], v[200:203], v[52:55]
	v_mfma_f32_16x16x32_bf16 v[48:51], v[184:187], v[200:203], v[48:51]
	v_mfma_f32_16x16x32_bf16 v[44:47], v[176:179], v[208:211], v[44:47]
	v_mfma_f32_16x16x32_bf16 v[40:43], v[184:187], v[208:211], v[40:43]
	v_mfma_f32_16x16x32_bf16 v[36:39], v[176:179], v[216:219], v[36:39]
	v_mfma_f32_16x16x32_bf16 v[32:35], v[184:187], v[216:219], v[32:35]
	v_mfma_f32_16x16x32_bf16 v[60:63], v[180:183], v[196:199], v[60:63]
	v_mfma_f32_16x16x32_bf16 v[56:59], v[188:191], v[196:199], v[56:59]
	v_mfma_f32_16x16x32_bf16 v[52:55], v[180:183], v[204:207], v[52:55]
	v_mfma_f32_16x16x32_bf16 v[48:51], v[188:191], v[204:207], v[48:51]
	v_mfma_f32_16x16x32_bf16 v[44:47], v[180:183], v[212:215], v[44:47]
	v_mfma_f32_16x16x32_bf16 v[40:43], v[188:191], v[212:215], v[40:43]
	v_mfma_f32_16x16x32_bf16 v[36:39], v[180:183], v[220:223], v[36:39]
	v_mfma_f32_16x16x32_bf16 v[32:35], v[188:191], v[220:223], v[32:35]
	s_barrier
	s_add_u32 m0, s12, s60
	s_nop 0
	global_load_lds_dwordx4 v162, s[92:93]
	s_add_u32 s92, s92, 0x100
	s_addc_u32 s93, s93, 0
	s_add_u32 m0, s12, 0x2000
	s_add_u32 m0, m0, s60
	s_nop 0
	global_load_lds_dwordx4 v163, s[94:95]
	s_add_u32 s94, s94, 0x100
	s_addc_u32 s95, s95, 0
	s_waitcnt vmcnt(6)
	s_barrier
	v_mfma_f32_16x16x32_bf16 v[28:31], v[224:227], v[192:195], v[28:31]
	v_mfma_f32_16x16x32_bf16 v[24:27], v[232:235], v[192:195], v[24:27]
	v_mfma_f32_16x16x32_bf16 v[20:23], v[224:227], v[200:203], v[20:23]
	v_mfma_f32_16x16x32_bf16 v[16:19], v[232:235], v[200:203], v[16:19]
	v_mfma_f32_16x16x32_bf16 v[12:15], v[224:227], v[208:211], v[12:15]
	v_mfma_f32_16x16x32_bf16 v[8:11], v[232:235], v[208:211], v[8:11]
	v_mfma_f32_16x16x32_bf16 v[4:7], v[224:227], v[216:219], v[4:7]
	v_mfma_f32_16x16x32_bf16 v[0:3], v[232:235], v[216:219], v[0:3]
	v_mfma_f32_16x16x32_bf16 v[28:31], v[228:231], v[196:199], v[28:31]
	v_mfma_f32_16x16x32_bf16 v[24:27], v[236:239], v[196:199], v[24:27]
	v_mfma_f32_16x16x32_bf16 v[20:23], v[228:231], v[204:207], v[20:23]
	v_mfma_f32_16x16x32_bf16 v[16:19], v[236:239], v[204:207], v[16:19]
	v_mfma_f32_16x16x32_bf16 v[12:15], v[228:231], v[212:215], v[12:15]
	v_mfma_f32_16x16x32_bf16 v[8:11], v[236:239], v[212:215], v[8:11]
	v_mfma_f32_16x16x32_bf16 v[4:7], v[228:231], v[220:223], v[4:7]
	v_mfma_f32_16x16x32_bf16 v[0:3], v[236:239], v[220:223], v[0:3]
	s_add_i32 s7, s7, 2
	s_add_u32 s4, s4, 0x100
	s_addc_u32 s5, s5, 0
	s_cmp_lt_u32 s7, 60
	s_barrier
; #define WAIT_V(n) asm volatile("s_waitcnt vmcnt(" #n ")" ::: "memory")
; #define WAIT_L(n) asm volatile("s_waitcnt lgkmcnt(" #n ")" ::: "memory")
; #define BAR __builtin_amdgcn_s_barrier()
;     ...
;   { LDB(B0, 0, 0); LDA(At, 0, 0); STAGE(SA(1, 1), A, brow + HALF, nt - 1);
;     BAR; WAIT_L(0); MMA(0, 0, At, B0); BAR;
;     LDB(B1, 0, 1); BAR; WAIT_L(0); MMA(0, 1, At, B1); BAR;
;     LDA(At, 0, 1); WAIT_V(4); BAR; WAIT_L(0); MMA(1, 0, At, B0); MMA(1, 1, At, B1); BAR; }
	s_cbranch_scc1 .LBB0_1236
	v_readlane_b32 s64, v254, 0
	v_readlane_b32 s65, v254, 1
	v_readlane_b32 s66, v254, 2
	v_readlane_b32 s67, v254, 3
	v_readlane_b32 s68, v254, 4
	v_readlane_b32 s69, v254, 5
	v_readlane_b32 s70, v254, 6
	v_readlane_b32 s71, v254, 7
	v_readlane_b32 s72, v254, 8
	v_readlane_b32 s73, v254, 9
	v_readlane_b32 s74, v254, 10
	v_readlane_b32 s75, v254, 11
	v_readlane_b32 s76, v254, 12
	v_readlane_b32 s77, v254, 13
	v_readlane_b32 s78, v254, 14
	v_readlane_b32 s79, v254, 15
	v_readlane_b32 s80, v254, 16
	v_readlane_b32 s81, v254, 17
	v_readlane_b32 s82, v254, 18
	v_readlane_b32 s83, v254, 19
	v_readlane_b32 s84, v254, 20
	v_readlane_b32 s85, v254, 21
	v_readlane_b32 s86, v254, 22
	v_readlane_b32 s87, v254, 23
	v_readlane_b32 s88, v254, 24
	v_readlane_b32 s89, v254, 25
	v_readlane_b32 s90, v254, 26
	v_readlane_b32 s91, v254, 27
	v_readlane_b32 s92, v254, 28
	v_readlane_b32 s93, v254, 29
	v_readlane_b32 s94, v254, 30
	v_readlane_b32 s95, v254, 31
	s_nop 4
	s_add_u32 s4, s8, 0x1f80
	s_addc_u32 s5, s9, 0
	v_readfirstlane_b32 s7, v174
	v_lshl_add_u64 v[142:143], s[4:5], 0, v[148:149]
	s_mov_b32 m0, s7
	v_lshl_add_u64 v[128:129], s[4:5], 0, v[128:129]
	v_readfirstlane_b32 s4, v175
	ds_read_b128 v[130:133], v173
	ds_read_b128 v[134:137], v173 offset:1024
	ds_read_b128 v[138:141], v173 offset:2048
	ds_read_b128 v[162:165], v173 offset:3072
	ds_read_b128 v[176:179], v153
	ds_read_b128 v[180:183], v153 offset:1024
	ds_read_b128 v[184:187], v152
	ds_read_b128 v[188:191], v152 offset:1024
	ds_read_b128 v[192:195], v151
	ds_read_b128 v[196:199], v151 offset:1024
	ds_read_b128 v[200:203], v150
	ds_read_b128 v[204:207], v150 offset:1024
	global_load_lds_dwordx4 v[142:143], off
	s_mov_b32 m0, s4
	s_nop 0
	global_load_lds_dwordx4 v[128:129], off
	s_barrier
	s_waitcnt lgkmcnt(0)
	s_waitcnt lgkmcnt(0)
	v_mfma_f32_16x16x32_bf16 v[116:119], v[130:133], v[184:187], v[116:119]
	v_mfma_f32_16x16x32_bf16 v[108:111], v[130:133], v[192:195], v[108:111]
	v_mfma_f32_16x16x32_bf16 v[100:103], v[130:133], v[200:203], v[100:103]
	v_mfma_f32_16x16x32_bf16 v[96:99], v[138:141], v[200:203], v[96:99]
	v_mfma_f32_16x16x32_bf16 v[124:127], v[130:133], v[176:179], v[124:127]
	v_mfma_f32_16x16x32_bf16 v[120:123], v[138:141], v[176:179], v[120:123]
	v_mfma_f32_16x16x32_bf16 v[116:119], v[134:137], v[188:191], v[116:119]
	v_mfma_f32_16x16x32_bf16 v[112:115], v[138:141], v[184:187], v[112:115]
	v_mfma_f32_16x16x32_bf16 v[108:111], v[134:137], v[196:199], v[108:111]
	v_mfma_f32_16x16x32_bf16 v[104:107], v[138:141], v[192:195], v[104:107]
	v_mfma_f32_16x16x32_bf16 v[100:103], v[134:137], v[204:207], v[100:103]
	v_mfma_f32_16x16x32_bf16 v[96:99], v[162:165], v[204:207], v[96:99]
	v_mfma_f32_16x16x32_bf16 v[124:127], v[134:137], v[180:183], v[124:127]
	v_mfma_f32_16x16x32_bf16 v[208:211], v[162:165], v[180:183], v[120:123]
	v_mfma_f32_16x16x32_bf16 v[212:215], v[162:165], v[188:191], v[112:115]
	v_mfma_f32_16x16x32_bf16 v[216:219], v[162:165], v[196:199], v[104:107]
	s_barrier
	s_nop 0
	ds_read_b128 v[104:107], v172
	ds_read_b128 v[112:115], v172 offset:1024
	ds_read_b128 v[120:123], v172 offset:2048
	ds_read_b128 v[172:175], v172 offset:3072
	s_barrier
	s_waitcnt lgkmcnt(0)
	s_waitcnt lgkmcnt(0)
	v_mfma_f32_16x16x32_bf16 v[92:95], v[104:107], v[176:179], v[92:95]
	v_mfma_f32_16x16x32_bf16 v[84:87], v[104:107], v[184:187], v[84:87]
	v_mfma_f32_16x16x32_bf16 v[76:79], v[104:107], v[192:195], v[76:79]
	v_mfma_f32_16x16x32_bf16 v[64:67], v[120:123], v[200:203], v[64:67]
	v_mfma_f32_16x16x32_bf16 v[92:95], v[112:115], v[180:183], v[92:95]
	v_mfma_f32_16x16x32_bf16 v[88:91], v[120:123], v[176:179], v[88:91]
	v_mfma_f32_16x16x32_bf16 v[84:87], v[112:115], v[188:191], v[84:87]
	v_mfma_f32_16x16x32_bf16 v[80:83], v[120:123], v[184:187], v[80:83]
	v_mfma_f32_16x16x32_bf16 v[76:79], v[112:115], v[196:199], v[76:79]
	v_mfma_f32_16x16x32_bf16 v[72:75], v[120:123], v[192:195], v[72:75]
	v_mfma_f32_16x16x32_bf16 v[68:71], v[104:107], v[200:203], v[68:71]
	v_mfma_f32_16x16x32_bf16 v[64:67], v[172:175], v[204:207], v[64:67]
	v_mfma_f32_16x16x32_bf16 v[176:179], v[172:175], v[180:183], v[88:91]
	v_mfma_f32_16x16x32_bf16 v[180:183], v[172:175], v[188:191], v[80:83]
	v_mfma_f32_16x16x32_bf16 v[184:187], v[172:175], v[196:199], v[72:75]
	v_mfma_f32_16x16x32_bf16 v[188:191], v[112:115], v[204:207], v[68:71]
	s_barrier
	s_nop 0
	ds_read_b128 v[68:71], v153 offset:16384
	ds_read_b128 v[72:75], v153 offset:17408
	ds_read_b128 v[80:83], v152 offset:16384
	ds_read_b128 v[88:91], v152 offset:17408
	ds_read_b128 v[192:195], v151 offset:16384
	ds_read_b128 v[196:199], v151 offset:17408
	ds_read_b128 v[200:203], v150 offset:16384
	ds_read_b128 v[204:207], v150 offset:17408
	s_waitcnt vmcnt(4)
	s_barrier
; #define WAIT_V(n) asm volatile("s_waitcnt vmcnt(" #n ")" ::: "memory")
; #define WAIT_L(n) asm volatile("s_waitcnt lgkmcnt(" #n ")" ::: "memory")
; #define BAR __builtin_amdgcn_s_barrier()
;     ...
;     LDA(At, 0, 1); WAIT_V(4); BAR; WAIT_L(0); MMA(1, 0, At, B0); MMA(1, 1, At, B1); BAR; }
;   { LDB(B0, 1, 0); LDA(At, 1, 0); WAIT_V(2); BAR; WAIT_L(0); MMA(0, 0, At, B0); BAR;
	s_waitcnt lgkmcnt(0)
	s_waitcnt lgkmcnt(0)
	v_mfma_f32_16x16x32_bf16 v[60:63], v[130:133], v[68:71], v[60:63]
	v_mfma_f32_16x16x32_bf16 v[52:55], v[130:133], v[80:83], v[52:55]
	v_mfma_f32_16x16x32_bf16 v[44:47], v[130:133], v[192:195], v[44:47]
	v_mfma_f32_16x16x32_bf16 v[36:39], v[130:133], v[200:203], v[36:39]
	v_mfma_f32_16x16x32_bf16 v[32:35], v[138:141], v[200:203], v[32:35]
	v_mfma_f32_16x16x32_bf16 v[60:63], v[134:137], v[72:75], v[60:63]
	v_mfma_f32_16x16x32_bf16 v[56:59], v[138:141], v[68:71], v[56:59]
	v_mfma_f32_16x16x32_bf16 v[52:55], v[134:137], v[88:91], v[52:55]
	v_mfma_f32_16x16x32_bf16 v[48:51], v[138:141], v[80:83], v[48:51]
	v_mfma_f32_16x16x32_bf16 v[44:47], v[134:137], v[196:199], v[44:47]
	v_mfma_f32_16x16x32_bf16 v[40:43], v[138:141], v[192:195], v[40:43]
	v_mfma_f32_16x16x32_bf16 v[36:39], v[134:137], v[204:207], v[36:39]
	v_mfma_f32_16x16x32_bf16 v[32:35], v[162:165], v[204:207], v[32:35]
	v_mfma_f32_16x16x32_bf16 v[220:223], v[162:165], v[72:75], v[56:59]
	v_mfma_f32_16x16x32_bf16 v[224:227], v[162:165], v[88:91], v[48:51]
	v_mfma_f32_16x16x32_bf16 v[228:231], v[162:165], v[196:199], v[40:43]
	v_mfma_f32_16x16x32_bf16 v[28:31], v[104:107], v[68:71], v[28:31]
	v_mfma_f32_16x16x32_bf16 v[20:23], v[104:107], v[80:83], v[20:23]
	v_mfma_f32_16x16x32_bf16 v[12:15], v[104:107], v[192:195], v[12:15]
	v_mfma_f32_16x16x32_bf16 v[0:3], v[120:123], v[200:203], v[0:3]
	v_mfma_f32_16x16x32_bf16 v[28:31], v[112:115], v[72:75], v[28:31]
	v_mfma_f32_16x16x32_bf16 v[24:27], v[120:123], v[68:71], v[24:27]
	v_mfma_f32_16x16x32_bf16 v[20:23], v[112:115], v[88:91], v[20:23]
	v_mfma_f32_16x16x32_bf16 v[16:19], v[120:123], v[80:83], v[16:19]
	v_mfma_f32_16x16x32_bf16 v[12:15], v[112:115], v[196:199], v[12:15]
	v_mfma_f32_16x16x32_bf16 v[8:11], v[120:123], v[192:195], v[8:11]
	v_mfma_f32_16x16x32_bf16 v[4:7], v[104:107], v[200:203], v[4:7]
	v_mfma_f32_16x16x32_bf16 v[0:3], v[172:175], v[204:207], v[0:3]
	v_mfma_f32_16x16x32_bf16 v[128:131], v[172:175], v[72:75], v[24:27]
	v_mfma_f32_16x16x32_bf16 v[132:135], v[172:175], v[88:91], v[16:19]
	v_mfma_f32_16x16x32_bf16 v[136:139], v[172:175], v[196:199], v[8:11]
	v_mfma_f32_16x16x32_bf16 v[162:165], v[112:115], v[204:207], v[4:7]
	s_barrier
	s_nop 0
	ds_read_b128 v[4:7], v161
	ds_read_b128 v[172:175], v161 offset:1024
	ds_read_b128 v[192:195], v161 offset:2048
	ds_read_b128 v[158:161], v161 offset:3072
	ds_read_b128 v[8:11], v153 offset:32768
	ds_read_b128 v[16:19], v153 offset:33792
	ds_read_b128 v[24:27], v152 offset:32768
	ds_read_b128 v[40:43], v152 offset:33792
	ds_read_b128 v[48:51], v151 offset:32768
	ds_read_b128 v[56:59], v151 offset:33792
	ds_read_b128 v[196:199], v150 offset:32768
	ds_read_b128 v[200:203], v150 offset:33792
	s_waitcnt vmcnt(2)
	s_barrier
	s_waitcnt lgkmcnt(0)
	s_waitcnt lgkmcnt(0)
	v_mfma_f32_16x16x32_bf16 v[68:71], v[4:7], v[8:11], v[124:127]
	v_mfma_f32_16x16x32_bf16 v[120:123], v[172:175], v[16:19], v[68:71]
	v_mfma_f32_16x16x32_bf16 v[68:71], v[192:195], v[8:11], v[208:211]
	v_mfma_f32_16x16x32_bf16 v[88:91], v[158:161], v[16:19], v[68:71]
	v_mfma_f32_16x16x32_bf16 v[68:71], v[4:7], v[24:27], v[116:119]
	v_mfma_f32_16x16x32_bf16 v[112:115], v[172:175], v[40:43], v[68:71]
	v_mfma_f32_16x16x32_bf16 v[68:71], v[192:195], v[24:27], v[212:215]
	v_mfma_f32_16x16x32_bf16 v[80:83], v[158:161], v[40:43], v[68:71]
	v_mfma_f32_16x16x32_bf16 v[68:71], v[4:7], v[48:51], v[108:111]
	v_mfma_f32_16x16x32_bf16 v[104:107], v[172:175], v[56:59], v[68:71]
	v_mfma_f32_16x16x32_bf16 v[68:71], v[192:195], v[48:51], v[216:219]
	v_mfma_f32_16x16x32_bf16 v[72:75], v[158:161], v[56:59], v[68:71]
	v_mfma_f32_16x16x32_bf16 v[68:71], v[4:7], v[196:199], v[100:103]
	v_mfma_f32_16x16x32_bf16 v[100:103], v[172:175], v[200:203], v[68:71]
	v_mfma_f32_16x16x32_bf16 v[68:71], v[192:195], v[196:199], v[96:99]
	v_mfma_f32_16x16x32_bf16 v[68:71], v[158:161], v[200:203], v[68:71]
	s_barrier
; #define WAIT_V(n) asm volatile("s_waitcnt vmcnt(" #n ")" ::: "memory")
; #define WAIT_L(n) asm volatile("s_waitcnt lgkmcnt(" #n ")" ::: "memory")
; #define BAR __builtin_amdgcn_s_barrier()
;     ...
;   { LDB(B0, 1, 0); LDA(At, 1, 0); WAIT_V(2); BAR; WAIT_L(0); MMA(0, 0, At, B0); BAR;
;     LDB(B1, 1, 1); WAIT_V(0); BAR; WAIT_L(0); MMA(0, 1, At, B1); BAR;
;     LDA(At, 1, 1); BAR; WAIT_L(0); MMA(1, 0, At, B0); MMA(1, 1, At, B1); BAR; }
;   if (wr == 0) BAR;
	ds_read_b128 v[124:127], v156
	ds_read_b128 v[204:207], v156 offset:1024
	ds_read_b128 v[208:211], v156 offset:2048
	ds_read_b128 v[154:157], v156 offset:3072
	s_waitcnt vmcnt(0)
	s_barrier
	s_waitcnt lgkmcnt(0)
	s_waitcnt lgkmcnt(0)
	v_mfma_f32_16x16x32_bf16 v[92:95], v[124:127], v[8:11], v[92:95]
	v_mfma_f32_16x16x32_bf16 v[8:11], v[208:211], v[8:11], v[176:179]
	v_mfma_f32_16x16x32_bf16 v[140:143], v[204:207], v[16:19], v[92:95]
	v_mfma_f32_16x16x32_bf16 v[92:95], v[154:157], v[16:19], v[8:11]
	v_mfma_f32_16x16x32_bf16 v[8:11], v[124:127], v[24:27], v[84:87]
	v_mfma_f32_16x16x32_bf16 v[116:119], v[204:207], v[40:43], v[8:11]
	v_mfma_f32_16x16x32_bf16 v[8:11], v[208:211], v[24:27], v[180:183]
	v_mfma_f32_16x16x32_bf16 v[84:87], v[154:157], v[40:43], v[8:11]
	v_mfma_f32_16x16x32_bf16 v[8:11], v[124:127], v[48:51], v[76:79]
	v_mfma_f32_16x16x32_bf16 v[108:111], v[204:207], v[56:59], v[8:11]
	v_mfma_f32_16x16x32_bf16 v[8:11], v[208:211], v[48:51], v[184:187]
	v_mfma_f32_16x16x32_bf16 v[76:79], v[154:157], v[56:59], v[8:11]
	v_mfma_f32_16x16x32_bf16 v[8:11], v[124:127], v[196:199], v[188:191]
	v_mfma_f32_16x16x32_bf16 v[96:99], v[204:207], v[200:203], v[8:11]
	v_mfma_f32_16x16x32_bf16 v[8:11], v[208:211], v[196:199], v[64:67]
	v_mfma_f32_16x16x32_bf16 v[64:67], v[154:157], v[200:203], v[8:11]
	s_barrier
	ds_read_b128 v[176:179], v153 offset:49152
	ds_read_b128 v[180:183], v153 offset:50176
	ds_read_b128 v[184:187], v152 offset:49152
	ds_read_b128 v[188:191], v152 offset:50176
	ds_read_b128 v[196:199], v151 offset:49152
	ds_read_b128 v[200:203], v151 offset:50176
	ds_read_b128 v[212:215], v150 offset:49152
	ds_read_b128 v[150:153], v150 offset:50176
	s_barrier
	s_waitcnt lgkmcnt(0)
	s_waitcnt lgkmcnt(0)
	v_mfma_f32_16x16x32_bf16 v[8:11], v[4:7], v[176:179], v[60:63]
	v_mfma_f32_16x16x32_bf16 v[56:59], v[172:175], v[180:183], v[8:11]
	v_mfma_f32_16x16x32_bf16 v[8:11], v[192:195], v[176:179], v[220:223]
	v_mfma_f32_16x16x32_bf16 v[24:27], v[158:161], v[180:183], v[8:11]
	v_mfma_f32_16x16x32_bf16 v[8:11], v[4:7], v[184:187], v[52:55]
	v_mfma_f32_16x16x32_bf16 v[48:51], v[172:175], v[188:191], v[8:11]
	v_mfma_f32_16x16x32_bf16 v[8:11], v[192:195], v[184:187], v[224:227]
	v_mfma_f32_16x16x32_bf16 v[16:19], v[158:161], v[188:191], v[8:11]
	v_mfma_f32_16x16x32_bf16 v[8:11], v[4:7], v[196:199], v[44:47]
	v_mfma_f32_16x16x32_bf16 v[4:7], v[4:7], v[212:215], v[36:39]
	v_mfma_f32_16x16x32_bf16 v[40:43], v[172:175], v[200:203], v[8:11]
	v_mfma_f32_16x16x32_bf16 v[8:11], v[192:195], v[196:199], v[228:231]
	v_mfma_f32_16x16x32_bf16 v[36:39], v[172:175], v[150:153], v[4:7]
	v_mfma_f32_16x16x32_bf16 v[4:7], v[192:195], v[212:215], v[32:35]
	v_mfma_f32_16x16x32_bf16 v[8:11], v[158:161], v[200:203], v[8:11]
	v_mfma_f32_16x16x32_bf16 v[4:7], v[158:161], v[150:153], v[4:7]
	v_mfma_f32_16x16x32_bf16 v[28:31], v[124:127], v[176:179], v[28:31]
	v_mfma_f32_16x16x32_bf16 v[20:23], v[124:127], v[184:187], v[20:23]
	v_mfma_f32_16x16x32_bf16 v[12:15], v[124:127], v[196:199], v[12:15]
	v_mfma_f32_16x16x32_bf16 v[60:63], v[204:207], v[180:183], v[28:31]
	v_mfma_f32_16x16x32_bf16 v[28:31], v[208:211], v[176:179], v[128:131]
	v_mfma_f32_16x16x32_bf16 v[52:55], v[204:207], v[188:191], v[20:23]
	v_mfma_f32_16x16x32_bf16 v[20:23], v[208:211], v[184:187], v[132:135]
	v_mfma_f32_16x16x32_bf16 v[44:47], v[204:207], v[200:203], v[12:15]
	v_mfma_f32_16x16x32_bf16 v[12:15], v[208:211], v[196:199], v[136:139]
	v_mfma_f32_16x16x32_bf16 v[32:35], v[124:127], v[212:215], v[162:165]
	v_mfma_f32_16x16x32_bf16 v[0:3], v[208:211], v[212:215], v[0:3]
	v_mfma_f32_16x16x32_bf16 v[28:31], v[154:157], v[180:183], v[28:31]
	v_mfma_f32_16x16x32_bf16 v[20:23], v[154:157], v[188:191], v[20:23]
	v_mfma_f32_16x16x32_bf16 v[12:15], v[154:157], v[200:203], v[12:15]
	v_mfma_f32_16x16x32_bf16 v[32:35], v[204:207], v[150:153], v[32:35]
	v_mfma_f32_16x16x32_bf16 v[0:3], v[154:157], v[150:153], v[0:3]
	v_cmp_gt_u32_e64 s[4:5], s84, v145
	s_barrier
	s_and_saveexec_b64 s[8:9], s[4:5]
	s_cbranch_execz .LBB0_1239
	s_barrier

; #define WAIT_V(n) asm volatile("s_waitcnt vmcnt(" #n ")" ::: "memory")
; #define BAR __builtin_amdgcn_s_barrier()
;     ...
;   const int wid = tx >> 6, lane = tx & 63, wr = wid >> 2, wc = wid & 3, fr = lane & 15, fq = lane >> 4;
;   f32x4 acc[2][2][4][2] = {};
;   bf16x8 At[4][2], B0[2][2], B1[2][2];
;   const int nt = K / BK;
;   unsigned soff0, soff1;
;   { int _r, _c; stage_rc(tx * 16, _r, _c); soff0 = (unsigned)(_r * K + _c) * 2u;
;     stage_rc(tx * 16 + 8192, _r, _c); soff1 = (unsigned)(_r * K + _c) * 2u; }
;   STAGE(SB(0, 0), Bt, bcol, 0); STAGE(SA(0, 0), A, brow, 0);
;   STAGE(SB(0, 1), Bt, bcol1, 0); STAGE(SA(0, 1), A, brow + HALF, 0);
;   if (wr == 1) BAR;
;   WAIT_V(4); BAR;
;   STAGE(SB(1, 0), Bt, bcol, 1); STAGE(SA(1, 0), A, brow, 1); STAGE(SB(1, 1), Bt, bcol1, 1);
;   WAIT_V(6); BAR;
.LBB0_1334:
	s_or_b64 exec, exec, s[22:23]
	v_add_u32_e32 v162, s59, v15
	v_add_u32_e32 v163, 0x2000, v162
	v_readfirstlane_b32 s22, v162
	v_lshl_add_u64 v[6:7], v[6:7], 0, s[10:11]
	s_mov_b32 m0, s22
	v_readfirstlane_b32 s22, v163
	v_add_u32_e32 v164, 0x8000, v155
	s_waitcnt vmcnt(4)
	s_barrier
	global_load_lds_dwordx4 v[6:7], off
	v_lshl_add_u64 v[4:5], v[4:5], 0, s[10:11]
	s_mov_b32 m0, s22
	v_readfirstlane_b32 s22, v164
	v_add_u32_e32 v165, 0xa000, v155
	global_load_lds_dwordx4 v[4:5], off
	v_lshl_add_u64 v[2:3], v[2:3], 0, s[10:11]
	s_mov_b32 m0, s22
	v_readfirstlane_b32 s22, v165
	s_add_u32 s6, s6, 0x2b0080
	v_add_u32_e32 v166, s60, v15
	global_load_lds_dwordx4 v[2:3], off
	v_lshl_add_u64 v[0:1], v[0:1], 0, s[10:11]
	s_mov_b32 m0, s22
	s_addc_u32 s7, s7, 0
	v_readfirstlane_b32 s22, v166
	global_load_lds_dwordx4 v[0:1], off
	v_lshl_add_u64 v[0:1], s[6:7], 0, v[128:129]
	s_mov_b32 m0, s22
	v_add_u32_e32 v167, 0x2000, v166
	global_load_lds_dwordx4 v[0:1], off
	v_lshl_add_u64 v[0:1], s[6:7], 0, v[130:131]
	v_readfirstlane_b32 s6, v167
	s_mov_b32 m0, s6
	v_and_b32_e32 v142, 15, v140
	global_load_lds_dwordx4 v[0:1], off
	v_lshlrev_b32_e32 v2, 2, v140
	v_and_b32_e32 v0, 48, v140
	v_lshlrev_b32_e32 v1, 6, v142
	v_and_b32_e32 v2, 32, v2
	v_bitop3_b32 v1, v1, v2, v0 bitop3:0x36
	v_add_u32_e32 v5, s33, v1
	v_add_u32_e32 v6, s58, v1
	v_add_u32_e32 v7, s59, v1
	v_add_u32_e32 v15, s60, v1
	v_add_u32_e32 v18, 0, v1
	v_lshlrev_b32_e32 v1, 6, v140
	v_and_or_b32 v0, v1, s28, v0
	v_xad_u32 v19, v0, v2, 0
	v_lshrrev_b32_e32 v1, 1, v8
	v_mul_lo_u32 v0, v9, s27
	v_lshrrev_b32_e32 v3, 1, v12
	v_mul_lo_u32 v2, v13, s27
	v_mad_u64_u32 v[0:1], s[6:7], v1, s29, v[0:1]
	v_mad_u64_u32 v[2:3], s[22:23], v3, s29, v[2:3]
	v_or_b32_e32 v0, v0, v10
	s_add_u32 s6, s0, s37
	v_or_b32_e32 v2, v2, v14
	v_add_lshl_u32 v0, v0, v11, 1
	v_mov_b32_e32 v1, v129
	s_addc_u32 s7, s1, s38
	v_add_lshl_u32 v2, v2, v16, 1
	v_mov_b32_e32 v3, v129
	v_lshl_add_u64 v[132:133], s[6:7], 0, v[0:1]
	v_lshl_add_u64 v[134:135], s[6:7], 0, v[2:3]
	s_add_i32 s6, s35, s36
	s_mul_hi_i32 s7, s6, 0x5600
	s_mulk_i32 s6, 0x5600
	s_add_u32 s6, s2, s6
	v_bfe_u32 v141, v148, 6, 2
	s_waitcnt vmcnt(6)
	v_lshlrev_b32_e32 v143, 6, v17
	v_lshlrev_b32_e32 v17, 13, v17
	s_addc_u32 s7, s3, s7
	v_lshlrev_b32_e32 v4, 12, v141
	v_or_b32_e32 v20, 0x800, v17
	v_or_b32_e32 v21, 0x1000, v17
	v_or_b32_e32 v22, 0x1800, v17
	v_lshl_add_u64 v[136:137], s[6:7], 0, v[0:1]
	v_mov_b32_e32 v0, 0
	v_or_b32_e32 v149, v143, v142
	v_lshl_add_u64 v[138:139], s[6:7], 0, v[2:3]
	s_mov_b32 s22, -2
	s_mov_b64 s[6:7], 0
	v_add_u32_e32 v169, v5, v4
	v_add_u32_e32 v151, v18, v17
	v_add_u32_e32 v150, v19, v20
	v_add_u32_e32 v145, v19, v21
	v_add_u32_e32 v144, v19, v22
	v_add_u32_e32 v168, v6, v4
	v_add_u32_e32 v160, v7, v4
	v_add_u32_e32 v154, v15, v4
	v_mov_b32_e32 v1, v0
	v_mov_b32_e32 v2, v0
	v_mov_b32_e32 v3, v0
	v_mov_b32_e32 v4, v0
	v_mov_b32_e32 v5, v0
	v_mov_b32_e32 v6, v0
	v_mov_b32_e32 v7, v0
	v_mov_b32_e32 v8, v0
	v_mov_b32_e32 v9, v0
	v_mov_b32_e32 v10, v0
	v_mov_b32_e32 v11, v0
	v_mov_b32_e32 v12, v0
	v_mov_b32_e32 v13, v0
	v_mov_b32_e32 v14, v0
	v_mov_b32_e32 v15, v0
	v_mov_b32_e32 v16, v0
	v_mov_b32_e32 v17, v0
	v_mov_b32_e32 v18, v0
	v_mov_b32_e32 v19, v0
	v_mov_b32_e32 v20, v0
	v_mov_b32_e32 v21, v0
	v_mov_b32_e32 v22, v0
	v_mov_b32_e32 v23, v0
	v_mov_b32_e32 v24, v0
	v_mov_b32_e32 v25, v0
	v_mov_b32_e32 v26, v0
	v_mov_b32_e32 v27, v0
	v_mov_b32_e32 v28, v0
	v_mov_b32_e32 v29, v0
	v_mov_b32_e32 v30, v0
	v_mov_b32_e32 v31, v0
	v_mov_b32_e32 v32, v0
	v_mov_b32_e32 v33, v0
	v_mov_b32_e32 v34, v0
	v_mov_b32_e32 v35, v0
	v_mov_b32_e32 v36, v0
	v_mov_b32_e32 v37, v0
	v_mov_b32_e32 v38, v0
	v_mov_b32_e32 v39, v0
	v_mov_b32_e32 v40, v0
	v_mov_b32_e32 v41, v0
	v_mov_b32_e32 v42, v0
	v_mov_b32_e32 v43, v0
	v_mov_b32_e32 v44, v0
	v_mov_b32_e32 v45, v0
	v_mov_b32_e32 v46, v0
	v_mov_b32_e32 v47, v0
	v_mov_b32_e32 v48, v0
	v_mov_b32_e32 v49, v0
	v_mov_b32_e32 v50, v0
	v_mov_b32_e32 v51, v0
	v_mov_b32_e32 v52, v0
	v_mov_b32_e32 v53, v0
	v_mov_b32_e32 v54, v0
	v_mov_b32_e32 v55, v0
	v_mov_b32_e32 v56, v0
	v_mov_b32_e32 v57, v0
	v_mov_b32_e32 v58, v0
	v_mov_b32_e32 v59, v0
	v_mov_b32_e32 v60, v0
	v_mov_b32_e32 v61, v0
	v_mov_b32_e32 v62, v0
	v_mov_b32_e32 v63, v0
	v_mov_b32_e32 v64, v0
	v_mov_b32_e32 v65, v0
	v_mov_b32_e32 v66, v0
	v_mov_b32_e32 v67, v0
	v_mov_b32_e32 v68, v0
	v_mov_b32_e32 v69, v0
	v_mov_b32_e32 v70, v0
	v_mov_b32_e32 v71, v0
	v_mov_b32_e32 v72, v0
	v_mov_b32_e32 v73, v0
	v_mov_b32_e32 v74, v0
	v_mov_b32_e32 v75, v0
	v_mov_b32_e32 v76, v0
	v_mov_b32_e32 v77, v0
	v_mov_b32_e32 v78, v0
	v_mov_b32_e32 v79, v0
	v_mov_b32_e32 v80, v0
	v_mov_b32_e32 v81, v0
	v_mov_b32_e32 v82, v0
	v_mov_b32_e32 v83, v0
	v_mov_b32_e32 v84, v0
	v_mov_b32_e32 v85, v0
	v_mov_b32_e32 v86, v0
	v_mov_b32_e32 v87, v0
	v_mov_b32_e32 v88, v0
	v_mov_b32_e32 v89, v0
	v_mov_b32_e32 v90, v0
	v_mov_b32_e32 v91, v0
	v_mov_b32_e32 v92, v0
	v_mov_b32_e32 v93, v0
	v_mov_b32_e32 v94, v0
	v_mov_b32_e32 v95, v0
	v_mov_b32_e32 v96, v0
	v_mov_b32_e32 v97, v0
	v_mov_b32_e32 v98, v0
	v_mov_b32_e32 v99, v0
	v_mov_b32_e32 v100, v0
	v_mov_b32_e32 v101, v0
	v_mov_b32_e32 v102, v0
	v_mov_b32_e32 v103, v0
	v_mov_b32_e32 v104, v0
	v_mov_b32_e32 v105, v0
	v_mov_b32_e32 v106, v0
	v_mov_b32_e32 v107, v0
	v_mov_b32_e32 v108, v0
	v_mov_b32_e32 v109, v0
	v_mov_b32_e32 v110, v0
	v_mov_b32_e32 v111, v0
	v_mov_b32_e32 v112, v0
	v_mov_b32_e32 v113, v0
	v_mov_b32_e32 v114, v0
	v_mov_b32_e32 v115, v0
	v_mov_b32_e32 v116, v0
	v_mov_b32_e32 v117, v0
	v_mov_b32_e32 v118, v0
	v_mov_b32_e32 v119, v0
	v_mov_b32_e32 v120, v0
	v_mov_b32_e32 v121, v0
	v_mov_b32_e32 v122, v0
	v_mov_b32_e32 v123, v0
	v_mov_b32_e32 v124, v0
	v_mov_b32_e32 v125, v0
	v_mov_b32_e32 v126, v0
	v_mov_b32_e32 v127, v0
	s_barrier
; #define WAIT_L(n) asm volatile("s_waitcnt lgkmcnt(" #n ")" ::: "memory")
; #define BAR __builtin_amdgcn_s_barrier()
; #define SCHED __builtin_amdgcn_sched_barrier(0)
;     ...
;   for (int t = 0; t < nt - 2; t += 2) {
;     LDB(B0, 0, 0); SCHED; LDA(At, 0, 0); STAGE(SA(1, 1), A, brow + HALF, t + 1);
;     WAIT_L(8); BAR; WAIT_L(0); MMA(0, 0, At, B0); BAR; SCHED;
	v_readfirstlane_b32 s23, v155
	v_writelane_b32 v254, s64, 0
	v_writelane_b32 v254, s65, 1
	v_writelane_b32 v254, s66, 2
	v_writelane_b32 v254, s67, 3
	v_writelane_b32 v254, s68, 4
	v_writelane_b32 v254, s69, 5
	v_writelane_b32 v254, s70, 6
	v_writelane_b32 v254, s71, 7
	v_writelane_b32 v254, s72, 8
	v_writelane_b32 v254, s73, 9
	v_writelane_b32 v254, s74, 10
	v_writelane_b32 v254, s75, 11
	v_writelane_b32 v254, s76, 12
	v_writelane_b32 v254, s77, 13
	v_writelane_b32 v254, s78, 14
	v_writelane_b32 v254, s79, 15
	v_writelane_b32 v254, s80, 16
	v_writelane_b32 v254, s81, 17
	v_writelane_b32 v254, s82, 18
	v_writelane_b32 v254, s83, 19
	v_writelane_b32 v254, s84, 20
	v_writelane_b32 v254, s85, 21
	v_writelane_b32 v254, s86, 22
	v_writelane_b32 v254, s87, 23
	v_writelane_b32 v254, s88, 24
	v_writelane_b32 v254, s89, 25
	v_writelane_b32 v254, s90, 26
	v_writelane_b32 v254, s91, 27
	v_writelane_b32 v254, s92, 28
	v_writelane_b32 v254, s93, 29
	v_writelane_b32 v254, s94, 30
	v_writelane_b32 v254, s95, 31
	v_readfirstlane_b32 s64, v136
	v_readfirstlane_b32 s65, v137
	v_readfirstlane_b32 s66, v138
	v_readfirstlane_b32 s67, v139
	v_readfirstlane_b32 s68, v132
	v_readfirstlane_b32 s69, v133
	v_readfirstlane_b32 s70, v134
	v_readfirstlane_b32 s71, v135
	v_readfirstlane_b32 s72, v136
	v_readfirstlane_b32 s73, v137
	v_readfirstlane_b32 s74, v138
	v_readfirstlane_b32 s75, v139
	v_readfirstlane_b32 s76, v132
	v_readfirstlane_b32 s77, v133
	v_readfirstlane_b32 s78, v134
	v_readfirstlane_b32 s79, v135
	v_readfirstlane_b32 s80, v136
	v_readfirstlane_b32 s81, v137
	v_readfirstlane_b32 s82, v138
	v_readfirstlane_b32 s83, v139
	v_readfirstlane_b32 s84, v132
	v_readfirstlane_b32 s85, v133
	v_readfirstlane_b32 s86, v134
	v_readfirstlane_b32 s87, v135
	v_readfirstlane_b32 s88, v136
	v_readfirstlane_b32 s89, v137
	v_readfirstlane_b32 s90, v138
	v_readfirstlane_b32 s91, v139
	v_readfirstlane_b32 s92, v132
	v_readfirstlane_b32 s93, v133
	v_readfirstlane_b32 s94, v134
	v_readfirstlane_b32 s95, v135
	s_nop 3
	v_subrev_u32_e32 v158, s64, v136
	v_subrev_u32_e32 v159, s66, v138
	v_subrev_u32_e32 v156, s68, v132
	v_subrev_u32_e32 v157, s70, v134
	s_add_u32 s64, s64, s6
	s_addc_u32 s65, s65, s7
	s_add_u32 s64, s64, s12
	s_addc_u32 s65, s65, s13
	s_add_u32 s66, s66, s6
	s_addc_u32 s67, s67, s7
	s_add_u32 s66, s66, s12
	s_addc_u32 s67, s67, s13
	s_add_u32 s68, s68, s6
	s_addc_u32 s69, s69, s7
	s_add_u32 s68, s68, s14
	s_addc_u32 s69, s69, s15
	s_add_u32 s70, s70, s6
	s_addc_u32 s71, s71, s7
	s_add_u32 s70, s70, s14
	s_addc_u32 s71, s71, s15
	s_add_u32 s72, s72, s6
	s_addc_u32 s73, s73, s7
	s_add_u32 s72, s72, s14
	s_addc_u32 s73, s73, s15
	s_add_u32 s74, s74, s6
	s_addc_u32 s75, s75, s7
	s_add_u32 s74, s74, s14
	s_addc_u32 s75, s75, s15
	s_add_u32 s76, s76, s6
	s_addc_u32 s77, s77, s7
	s_add_u32 s76, s76, s16
	s_addc_u32 s77, s77, s17
	s_add_u32 s78, s78, s6
	s_addc_u32 s79, s79, s7
	s_add_u32 s78, s78, s16
	s_addc_u32 s79, s79, s17
	s_add_u32 s80, s80, s6
	s_addc_u32 s81, s81, s7
	s_add_u32 s80, s80, s16
	s_addc_u32 s81, s81, s17
	s_add_u32 s82, s82, s6
	s_addc_u32 s83, s83, s7
	s_add_u32 s82, s82, s16
	s_addc_u32 s83, s83, s17
	s_add_u32 s84, s84, s6
	s_addc_u32 s85, s85, s7
	s_add_u32 s84, s84, s18
	s_addc_u32 s85, s85, s19
	s_add_u32 s86, s86, s6
	s_addc_u32 s87, s87, s7
	s_add_u32 s86, s86, s18
	s_addc_u32 s87, s87, s19
	s_add_u32 s88, s88, s6
	s_addc_u32 s89, s89, s7
	s_add_u32 s88, s88, s18
	s_addc_u32 s89, s89, s19
	s_add_u32 s90, s90, s6
	s_addc_u32 s91, s91, s7
	s_add_u32 s90, s90, s18
	s_addc_u32 s91, s91, s19
	s_add_u32 s92, s92, s6
	s_addc_u32 s93, s93, s7
	s_add_u32 s92, s92, s20
	s_addc_u32 s93, s93, s21
	s_add_u32 s94, s94, s6
	s_addc_u32 s95, s95, s7
	s_add_u32 s94, s94, s20
	s_addc_u32 s95, s95, s21
	v_add_u32_e32 v170, 0xc000, v155
	v_add_u32_e32 v171, 0xe000, v155
.LBB0_1335:
	ds_read_b128 v[172:175], v169
	ds_read_b128 v[176:179], v169 offset:1024
	ds_read_b128 v[180:183], v169 offset:2048
	ds_read_b128 v[184:187], v169 offset:3072
	s_add_u32 m0, s23, 0xc000
	ds_read_b128 v[188:191], v151
	ds_read_b128 v[192:195], v151 offset:1024
	ds_read_b128 v[196:199], v150
	ds_read_b128 v[200:203], v150 offset:1024
	ds_read_b128 v[204:207], v145
	ds_read_b128 v[208:211], v145 offset:1024
	ds_read_b128 v[212:215], v144
	ds_read_b128 v[216:219], v144 offset:1024
	global_load_lds_dwordx4 v158, s[64:65]
	s_add_u32 s64, s64, 0x100
	s_addc_u32 s65, s65, 0
	s_add_u32 m0, s23, 0xe000
	s_nop 0
	global_load_lds_dwordx4 v159, s[66:67]
	s_add_u32 s66, s66, 0x100
	s_addc_u32 s67, s67, 0
	s_waitcnt lgkmcnt(8)
	s_barrier
	s_waitcnt lgkmcnt(0)
	v_mfma_f32_16x16x32_bf16 v[124:127], v[172:175], v[188:191], v[124:127]
	v_mfma_f32_16x16x32_bf16 v[120:123], v[180:183], v[188:191], v[120:123]
	v_mfma_f32_16x16x32_bf16 v[116:119], v[172:175], v[196:199], v[116:119]
	v_mfma_f32_16x16x32_bf16 v[112:115], v[180:183], v[196:199], v[112:115]
	v_mfma_f32_16x16x32_bf16 v[108:111], v[172:175], v[204:207], v[108:111]
	v_mfma_f32_16x16x32_bf16 v[104:107], v[180:183], v[204:207], v[104:107]
	v_mfma_f32_16x16x32_bf16 v[100:103], v[172:175], v[212:215], v[100:103]
	v_mfma_f32_16x16x32_bf16 v[96:99], v[180:183], v[212:215], v[96:99]
	v_mfma_f32_16x16x32_bf16 v[124:127], v[176:179], v[192:195], v[124:127]
	v_mfma_f32_16x16x32_bf16 v[120:123], v[184:187], v[192:195], v[120:123]
	v_mfma_f32_16x16x32_bf16 v[116:119], v[176:179], v[200:203], v[116:119]
	v_mfma_f32_16x16x32_bf16 v[112:115], v[184:187], v[200:203], v[112:115]
	v_mfma_f32_16x16x32_bf16 v[108:111], v[176:179], v[208:211], v[108:111]
	v_mfma_f32_16x16x32_bf16 v[104:107], v[184:187], v[208:211], v[104:107]
	v_mfma_f32_16x16x32_bf16 v[100:103], v[176:179], v[216:219], v[100:103]
	v_mfma_f32_16x16x32_bf16 v[96:99], v[184:187], v[216:219], v[96:99]
	s_barrier
; #define WAIT_V(n) asm volatile("s_waitcnt vmcnt(" #n ")" ::: "memory")
; #define WAIT_L(n) asm volatile("s_waitcnt lgkmcnt(" #n ")" ::: "memory")
; #define BAR __builtin_amdgcn_s_barrier()
; #define SCHED __builtin_amdgcn_sched_barrier(0)
;     ...
;     LDB(B1, 0, 1); STAGE(SB(0, 0), Bt, bcol, t + 2);
;     BAR; WAIT_L(0); MMA(0, 1, At, B1); BAR;
;     LDA(At, 0, 1); STAGE(SA(0, 0), A, brow, t + 2);
;     BAR; WAIT_L(0); MMA(1, 0, At, B0); BAR; SCHED;
;     STAGE(SB(0, 1), Bt, bcol1, t + 2);
;     WAIT_V(6); BAR; MMA(1, 1, At, B1); BAR;
;     LDB(B0, 1, 0); SCHED; LDA(At, 1, 0); STAGE(SA(0, 1), A, brow + HALF, t + 2);
;     WAIT_L(8); BAR; WAIT_L(0); MMA(0, 0, At, B0); BAR; SCHED;
	s_add_u32 m0, s23, s33
	ds_read_b128 v[220:223], v168
	ds_read_b128 v[224:227], v168 offset:1024
	ds_read_b128 v[228:231], v168 offset:2048
	ds_read_b128 v[232:235], v168 offset:3072
	global_load_lds_dwordx4 v156, s[68:69]
	s_add_u32 s68, s68, 0x100
	s_addc_u32 s69, s69, 0
	s_add_u32 m0, s23, 0x2000
	s_add_u32 m0, m0, s33
	s_nop 0
	global_load_lds_dwordx4 v157, s[70:71]
	s_add_u32 s70, s70, 0x100
	s_addc_u32 s71, s71, 0
	s_barrier
	s_waitcnt lgkmcnt(0)
	v_mfma_f32_16x16x32_bf16 v[92:95], v[220:223], v[188:191], v[92:95]
	v_mfma_f32_16x16x32_bf16 v[88:91], v[228:231], v[188:191], v[88:91]
	v_mfma_f32_16x16x32_bf16 v[84:87], v[220:223], v[196:199], v[84:87]
	v_mfma_f32_16x16x32_bf16 v[80:83], v[228:231], v[196:199], v[80:83]
	v_mfma_f32_16x16x32_bf16 v[76:79], v[220:223], v[204:207], v[76:79]
	v_mfma_f32_16x16x32_bf16 v[72:75], v[228:231], v[204:207], v[72:75]
	v_mfma_f32_16x16x32_bf16 v[68:71], v[220:223], v[212:215], v[68:71]
	v_mfma_f32_16x16x32_bf16 v[64:67], v[228:231], v[212:215], v[64:67]
	v_mfma_f32_16x16x32_bf16 v[92:95], v[224:227], v[192:195], v[92:95]
	v_mfma_f32_16x16x32_bf16 v[88:91], v[232:235], v[192:195], v[88:91]
	v_mfma_f32_16x16x32_bf16 v[84:87], v[224:227], v[200:203], v[84:87]
	v_mfma_f32_16x16x32_bf16 v[80:83], v[232:235], v[200:203], v[80:83]
	v_mfma_f32_16x16x32_bf16 v[76:79], v[224:227], v[208:211], v[76:79]
	v_mfma_f32_16x16x32_bf16 v[72:75], v[232:235], v[208:211], v[72:75]
	v_mfma_f32_16x16x32_bf16 v[68:71], v[224:227], v[216:219], v[68:71]
	v_mfma_f32_16x16x32_bf16 v[64:67], v[232:235], v[216:219], v[64:67]
	s_mov_b32 m0, s23
	s_barrier
	ds_read_b128 v[188:191], v151 offset:16384
	ds_read_b128 v[192:195], v151 offset:17408
	ds_read_b128 v[196:199], v150 offset:16384
	ds_read_b128 v[200:203], v150 offset:17408
	ds_read_b128 v[204:207], v145 offset:16384
	ds_read_b128 v[208:211], v145 offset:17408
	ds_read_b128 v[212:215], v144 offset:16384
	ds_read_b128 v[216:219], v144 offset:17408
	global_load_lds_dwordx4 v158, s[72:73]
	s_add_u32 s72, s72, 0x100
	s_addc_u32 s73, s73, 0
	s_add_u32 m0, s23, 0x2000
	s_nop 0
	global_load_lds_dwordx4 v159, s[74:75]
	s_add_u32 s74, s74, 0x100
	s_addc_u32 s75, s75, 0
	s_barrier
	s_waitcnt lgkmcnt(0)
	v_mfma_f32_16x16x32_bf16 v[60:63], v[172:175], v[188:191], v[60:63]
	v_mfma_f32_16x16x32_bf16 v[56:59], v[180:183], v[188:191], v[56:59]
	v_mfma_f32_16x16x32_bf16 v[52:55], v[172:175], v[196:199], v[52:55]
	v_mfma_f32_16x16x32_bf16 v[48:51], v[180:183], v[196:199], v[48:51]
	v_mfma_f32_16x16x32_bf16 v[44:47], v[172:175], v[204:207], v[44:47]
	v_mfma_f32_16x16x32_bf16 v[40:43], v[180:183], v[204:207], v[40:43]
	v_mfma_f32_16x16x32_bf16 v[36:39], v[172:175], v[212:215], v[36:39]
	v_mfma_f32_16x16x32_bf16 v[32:35], v[180:183], v[212:215], v[32:35]
	v_mfma_f32_16x16x32_bf16 v[60:63], v[176:179], v[192:195], v[60:63]
	v_mfma_f32_16x16x32_bf16 v[56:59], v[184:187], v[192:195], v[56:59]
	v_mfma_f32_16x16x32_bf16 v[52:55], v[176:179], v[200:203], v[52:55]
	v_mfma_f32_16x16x32_bf16 v[48:51], v[184:187], v[200:203], v[48:51]
	v_mfma_f32_16x16x32_bf16 v[44:47], v[176:179], v[208:211], v[44:47]
	v_mfma_f32_16x16x32_bf16 v[40:43], v[184:187], v[208:211], v[40:43]
	v_mfma_f32_16x16x32_bf16 v[36:39], v[176:179], v[216:219], v[36:39]
	v_mfma_f32_16x16x32_bf16 v[32:35], v[184:187], v[216:219], v[32:35]
	s_barrier
	s_add_u32 m0, s23, s58
	s_nop 0
	global_load_lds_dwordx4 v156, s[76:77]
	s_add_u32 s76, s76, 0x100
	s_addc_u32 s77, s77, 0
	s_add_u32 m0, s23, 0x2000
	s_add_u32 m0, m0, s58
	s_nop 0
	global_load_lds_dwordx4 v157, s[78:79]
	s_add_u32 s78, s78, 0x100
	s_addc_u32 s79, s79, 0
	s_waitcnt vmcnt(6)
	s_barrier
	v_mfma_f32_16x16x32_bf16 v[28:31], v[220:223], v[188:191], v[28:31]
	v_mfma_f32_16x16x32_bf16 v[24:27], v[228:231], v[188:191], v[24:27]
	v_mfma_f32_16x16x32_bf16 v[20:23], v[220:223], v[196:199], v[20:23]
	v_mfma_f32_16x16x32_bf16 v[16:19], v[228:231], v[196:199], v[16:19]
	v_mfma_f32_16x16x32_bf16 v[12:15], v[220:223], v[204:207], v[12:15]
	v_mfma_f32_16x16x32_bf16 v[8:11], v[228:231], v[204:207], v[8:11]
	v_mfma_f32_16x16x32_bf16 v[4:7], v[220:223], v[212:215], v[4:7]
	v_mfma_f32_16x16x32_bf16 v[0:3], v[228:231], v[212:215], v[0:3]
	v_mfma_f32_16x16x32_bf16 v[28:31], v[224:227], v[192:195], v[28:31]
	v_mfma_f32_16x16x32_bf16 v[24:27], v[232:235], v[192:195], v[24:27]
	v_mfma_f32_16x16x32_bf16 v[20:23], v[224:227], v[200:203], v[20:23]
	v_mfma_f32_16x16x32_bf16 v[16:19], v[232:235], v[200:203], v[16:19]
	v_mfma_f32_16x16x32_bf16 v[12:15], v[224:227], v[208:211], v[12:15]
	v_mfma_f32_16x16x32_bf16 v[8:11], v[232:235], v[208:211], v[8:11]
	v_mfma_f32_16x16x32_bf16 v[4:7], v[224:227], v[216:219], v[4:7]
	v_mfma_f32_16x16x32_bf16 v[0:3], v[232:235], v[216:219], v[0:3]
	s_barrier
	ds_read_b128 v[172:175], v160
	ds_read_b128 v[176:179], v160 offset:1024
	ds_read_b128 v[180:183], v160 offset:2048
	ds_read_b128 v[184:187], v160 offset:3072
	s_add_u32 m0, s23, 0x4000
	ds_read_b128 v[188:191], v151 offset:32768
	ds_read_b128 v[192:195], v151 offset:33792
	ds_read_b128 v[196:199], v150 offset:32768
	ds_read_b128 v[200:203], v150 offset:33792
	ds_read_b128 v[204:207], v145 offset:32768
	ds_read_b128 v[208:211], v145 offset:33792
	ds_read_b128 v[212:215], v144 offset:32768
	ds_read_b128 v[216:219], v144 offset:33792
	global_load_lds_dwordx4 v158, s[80:81]
	s_add_u32 s80, s80, 0x100
	s_addc_u32 s81, s81, 0
	s_add_u32 m0, s23, 0x6000
	s_nop 0
	global_load_lds_dwordx4 v159, s[82:83]
	s_add_u32 s82, s82, 0x100
	s_addc_u32 s83, s83, 0
	s_waitcnt lgkmcnt(8)
	s_barrier
; #define WAIT_V(n) asm volatile("s_waitcnt vmcnt(" #n ")" ::: "memory")
; #define WAIT_L(n) asm volatile("s_waitcnt lgkmcnt(" #n ")" ::: "memory")
; #define BAR __builtin_amdgcn_s_barrier()
; #define SCHED __builtin_amdgcn_sched_barrier(0)
;     ...
;     LDB(B0, 1, 0); SCHED; LDA(At, 1, 0); STAGE(SA(0, 1), A, brow + HALF, t + 2);
;     WAIT_L(8); BAR; WAIT_L(0); MMA(0, 0, At, B0); BAR; SCHED;
;     LDB(B1, 1, 1); STAGE(SB(1, 0), Bt, bcol, t + 3);
;     BAR; WAIT_L(0); MMA(0, 1, At, B1); BAR;
;     LDA(At, 1, 1); STAGE(SA(1, 0), A, brow, t + 3);
;     BAR; WAIT_L(0); MMA(1, 0, At, B0); BAR; SCHED;
;     STAGE(SB(1, 1), Bt, bcol1, t + 3);
;     WAIT_V(6); BAR; MMA(1, 1, At, B1); BAR;
	s_waitcnt lgkmcnt(0)
	v_mfma_f32_16x16x32_bf16 v[124:127], v[172:175], v[188:191], v[124:127]
	v_mfma_f32_16x16x32_bf16 v[120:123], v[180:183], v[188:191], v[120:123]
	v_mfma_f32_16x16x32_bf16 v[116:119], v[172:175], v[196:199], v[116:119]
	v_mfma_f32_16x16x32_bf16 v[112:115], v[180:183], v[196:199], v[112:115]
	v_mfma_f32_16x16x32_bf16 v[108:111], v[172:175], v[204:207], v[108:111]
	v_mfma_f32_16x16x32_bf16 v[104:107], v[180:183], v[204:207], v[104:107]
	v_mfma_f32_16x16x32_bf16 v[100:103], v[172:175], v[212:215], v[100:103]
	v_mfma_f32_16x16x32_bf16 v[96:99], v[180:183], v[212:215], v[96:99]
	v_mfma_f32_16x16x32_bf16 v[124:127], v[176:179], v[192:195], v[124:127]
	v_mfma_f32_16x16x32_bf16 v[120:123], v[184:187], v[192:195], v[120:123]
	v_mfma_f32_16x16x32_bf16 v[116:119], v[176:179], v[200:203], v[116:119]
	v_mfma_f32_16x16x32_bf16 v[112:115], v[184:187], v[200:203], v[112:115]
	v_mfma_f32_16x16x32_bf16 v[108:111], v[176:179], v[208:211], v[108:111]
	v_mfma_f32_16x16x32_bf16 v[104:107], v[184:187], v[208:211], v[104:107]
	v_mfma_f32_16x16x32_bf16 v[100:103], v[176:179], v[216:219], v[100:103]
	v_mfma_f32_16x16x32_bf16 v[96:99], v[184:187], v[216:219], v[96:99]
	s_barrier
	s_add_u32 m0, s23, s59
	ds_read_b128 v[220:223], v154
	ds_read_b128 v[224:227], v154 offset:1024
	ds_read_b128 v[228:231], v154 offset:2048
	ds_read_b128 v[232:235], v154 offset:3072
	global_load_lds_dwordx4 v156, s[84:85]
	s_add_u32 s84, s84, 0x100
	s_addc_u32 s85, s85, 0
	s_add_u32 m0, s23, 0x2000
	s_add_u32 m0, m0, s59
	s_nop 0
	global_load_lds_dwordx4 v157, s[86:87]
	s_add_u32 s86, s86, 0x100
	s_addc_u32 s87, s87, 0
	s_barrier
	s_waitcnt lgkmcnt(0)
	v_mfma_f32_16x16x32_bf16 v[92:95], v[220:223], v[188:191], v[92:95]
	v_mfma_f32_16x16x32_bf16 v[88:91], v[228:231], v[188:191], v[88:91]
	v_mfma_f32_16x16x32_bf16 v[84:87], v[220:223], v[196:199], v[84:87]
	v_mfma_f32_16x16x32_bf16 v[80:83], v[228:231], v[196:199], v[80:83]
	v_mfma_f32_16x16x32_bf16 v[76:79], v[220:223], v[204:207], v[76:79]
	v_mfma_f32_16x16x32_bf16 v[72:75], v[228:231], v[204:207], v[72:75]
	v_mfma_f32_16x16x32_bf16 v[68:71], v[220:223], v[212:215], v[68:71]
	v_mfma_f32_16x16x32_bf16 v[64:67], v[228:231], v[212:215], v[64:67]
	v_mfma_f32_16x16x32_bf16 v[92:95], v[224:227], v[192:195], v[92:95]
	v_mfma_f32_16x16x32_bf16 v[88:91], v[232:235], v[192:195], v[88:91]
	v_mfma_f32_16x16x32_bf16 v[84:87], v[224:227], v[200:203], v[84:87]
	v_mfma_f32_16x16x32_bf16 v[80:83], v[232:235], v[200:203], v[80:83]
	v_mfma_f32_16x16x32_bf16 v[76:79], v[224:227], v[208:211], v[76:79]
	v_mfma_f32_16x16x32_bf16 v[72:75], v[232:235], v[208:211], v[72:75]
	v_mfma_f32_16x16x32_bf16 v[68:71], v[224:227], v[216:219], v[68:71]
	v_mfma_f32_16x16x32_bf16 v[64:67], v[232:235], v[216:219], v[64:67]
	s_add_u32 m0, s23, 0x8000
	s_barrier
	ds_read_b128 v[188:191], v151 offset:49152
	ds_read_b128 v[192:195], v151 offset:50176
	ds_read_b128 v[196:199], v150 offset:49152
	ds_read_b128 v[200:203], v150 offset:50176
	ds_read_b128 v[204:207], v145 offset:49152
	ds_read_b128 v[208:211], v145 offset:50176
	ds_read_b128 v[212:215], v144 offset:49152
	ds_read_b128 v[216:219], v144 offset:50176
	global_load_lds_dwordx4 v158, s[88:89]
	s_add_u32 s88, s88, 0x100
	s_addc_u32 s89, s89, 0
	s_add_u32 m0, s23, 0xa000
	s_nop 0
	global_load_lds_dwordx4 v159, s[90:91]
	s_add_u32 s90, s90, 0x100
	s_addc_u32 s91, s91, 0
	s_barrier
	s_waitcnt lgkmcnt(0)
	v_mfma_f32_16x16x32_bf16 v[60:63], v[172:175], v[188:191], v[60:63]
	v_mfma_f32_16x16x32_bf16 v[56:59], v[180:183], v[188:191], v[56:59]
	v_mfma_f32_16x16x32_bf16 v[52:55], v[172:175], v[196:199], v[52:55]
	v_mfma_f32_16x16x32_bf16 v[48:51], v[180:183], v[196:199], v[48:51]
	v_mfma_f32_16x16x32_bf16 v[44:47], v[172:175], v[204:207], v[44:47]
	v_mfma_f32_16x16x32_bf16 v[40:43], v[180:183], v[204:207], v[40:43]
	v_mfma_f32_16x16x32_bf16 v[36:39], v[172:175], v[212:215], v[36:39]
	v_mfma_f32_16x16x32_bf16 v[32:35], v[180:183], v[212:215], v[32:35]
	v_mfma_f32_16x16x32_bf16 v[60:63], v[176:179], v[192:195], v[60:63]
	v_mfma_f32_16x16x32_bf16 v[56:59], v[184:187], v[192:195], v[56:59]
	v_mfma_f32_16x16x32_bf16 v[52:55], v[176:179], v[200:203], v[52:55]
	v_mfma_f32_16x16x32_bf16 v[48:51], v[184:187], v[200:203], v[48:51]
	v_mfma_f32_16x16x32_bf16 v[44:47], v[176:179], v[208:211], v[44:47]
	v_mfma_f32_16x16x32_bf16 v[40:43], v[184:187], v[208:211], v[40:43]
	v_mfma_f32_16x16x32_bf16 v[36:39], v[176:179], v[216:219], v[36:39]
	v_mfma_f32_16x16x32_bf16 v[32:35], v[184:187], v[216:219], v[32:35]
	s_barrier
	s_add_u32 m0, s23, s60
	s_nop 0
	global_load_lds_dwordx4 v156, s[92:93]
	s_add_u32 s92, s92, 0x100
	s_addc_u32 s93, s93, 0
	s_add_u32 m0, s23, 0x2000
	s_add_u32 m0, m0, s60
	s_nop 0
	global_load_lds_dwordx4 v157, s[94:95]
	s_add_u32 s94, s94, 0x100
	s_addc_u32 s95, s95, 0
	s_waitcnt vmcnt(6)
	s_barrier
	v_mfma_f32_16x16x32_bf16 v[28:31], v[220:223], v[188:191], v[28:31]
	v_mfma_f32_16x16x32_bf16 v[24:27], v[228:231], v[188:191], v[24:27]
	v_mfma_f32_16x16x32_bf16 v[20:23], v[220:223], v[196:199], v[20:23]
	v_mfma_f32_16x16x32_bf16 v[16:19], v[228:231], v[196:199], v[16:19]
	v_mfma_f32_16x16x32_bf16 v[12:15], v[220:223], v[204:207], v[12:15]
	v_mfma_f32_16x16x32_bf16 v[8:11], v[228:231], v[204:207], v[8:11]
	v_mfma_f32_16x16x32_bf16 v[4:7], v[220:223], v[212:215], v[4:7]
	v_mfma_f32_16x16x32_bf16 v[0:3], v[228:231], v[212:215], v[0:3]
	v_mfma_f32_16x16x32_bf16 v[28:31], v[224:227], v[192:195], v[28:31]
	v_mfma_f32_16x16x32_bf16 v[24:27], v[232:235], v[192:195], v[24:27]
	v_mfma_f32_16x16x32_bf16 v[20:23], v[224:227], v[200:203], v[20:23]
	v_mfma_f32_16x16x32_bf16 v[16:19], v[232:235], v[200:203], v[16:19]
	v_mfma_f32_16x16x32_bf16 v[12:15], v[224:227], v[208:211], v[12:15]
	v_mfma_f32_16x16x32_bf16 v[8:11], v[232:235], v[208:211], v[8:11]
	v_mfma_f32_16x16x32_bf16 v[4:7], v[224:227], v[216:219], v[4:7]
	v_mfma_f32_16x16x32_bf16 v[0:3], v[232:235], v[216:219], v[0:3]
	s_add_i32 s22, s22, 2
	s_add_u32 s6, s6, 0x100
	s_addc_u32 s7, s7, 0
	s_cmpk_lt_u32 s22, 0xa8
	s_barrier
; #define WAIT_V(n) asm volatile("s_waitcnt vmcnt(" #n ")" ::: "memory")
; #define WAIT_L(n) asm volatile("s_waitcnt lgkmcnt(" #n ")" ::: "memory")
; #define BAR __builtin_amdgcn_s_barrier()
;     ...
;   }
;   { LDB(B0, 0, 0); LDA(At, 0, 0); STAGE(SA(1, 1), A, brow + HALF, nt - 1);
;     BAR; WAIT_L(0); MMA(0, 0, At, B0); BAR;
;     LDB(B1, 0, 1); BAR; WAIT_L(0); MMA(0, 1, At, B1); BAR;
;     LDA(At, 0, 1); WAIT_V(4); BAR; WAIT_L(0); MMA(1, 0, At, B0); MMA(1, 1, At, B1); BAR; }
	s_cbranch_scc1 .LBB0_1335
	v_readlane_b32 s64, v254, 0
	v_readlane_b32 s65, v254, 1
	v_readlane_b32 s66, v254, 2
	v_readlane_b32 s67, v254, 3
	v_readlane_b32 s68, v254, 4
	v_readlane_b32 s69, v254, 5
	v_readlane_b32 s70, v254, 6
	v_readlane_b32 s71, v254, 7
	v_readlane_b32 s72, v254, 8
	v_readlane_b32 s73, v254, 9
	v_readlane_b32 s74, v254, 10
	v_readlane_b32 s75, v254, 11
	v_readlane_b32 s76, v254, 12
	v_readlane_b32 s77, v254, 13
	v_readlane_b32 s78, v254, 14
	v_readlane_b32 s79, v254, 15
	v_readlane_b32 s80, v254, 16
	v_readlane_b32 s81, v254, 17
	v_readlane_b32 s82, v254, 18
	v_readlane_b32 s83, v254, 19
	v_readlane_b32 s84, v254, 20
	v_readlane_b32 s85, v254, 21
	v_readlane_b32 s86, v254, 22
	v_readlane_b32 s87, v254, 23
	v_readlane_b32 s88, v254, 24
	v_readlane_b32 s89, v254, 25
	v_readlane_b32 s90, v254, 26
	v_readlane_b32 s91, v254, 27
	v_readlane_b32 s92, v254, 28
	v_readlane_b32 s93, v254, 29
	v_readlane_b32 s94, v254, 30
	v_readlane_b32 s95, v254, 31
	s_nop 4
	s_add_u32 s4, s4, 0x5580
	s_addc_u32 s5, s5, 0
	v_readfirstlane_b32 s6, v170
	v_lshl_add_u64 v[152:153], s[4:5], 0, v[128:129]
	s_mov_b32 m0, s6
	v_lshl_add_u64 v[130:131], s[4:5], 0, v[130:131]
	v_readfirstlane_b32 s4, v171
	ds_read_b128 v[132:135], v169
	ds_read_b128 v[136:139], v169 offset:1024
	ds_read_b128 v[156:159], v169 offset:2048
	ds_read_b128 v[162:165], v169 offset:3072
	ds_read_b128 v[172:175], v151
	ds_read_b128 v[176:179], v151 offset:1024
	ds_read_b128 v[180:183], v150
	ds_read_b128 v[184:187], v150 offset:1024
	ds_read_b128 v[188:191], v145
	ds_read_b128 v[192:195], v145 offset:1024
	ds_read_b128 v[196:199], v144
	ds_read_b128 v[200:203], v144 offset:1024
	global_load_lds_dwordx4 v[152:153], off
	s_mov_b32 m0, s4
	s_nop 0
	global_load_lds_dwordx4 v[130:131], off
	s_barrier
	s_waitcnt lgkmcnt(0)
	s_waitcnt lgkmcnt(0)
	v_mfma_f32_16x16x32_bf16 v[124:127], v[132:135], v[172:175], v[124:127]
	v_mfma_f32_16x16x32_bf16 v[120:123], v[156:159], v[172:175], v[120:123]
	v_mfma_f32_16x16x32_bf16 v[108:111], v[132:135], v[188:191], v[108:111]
	v_mfma_f32_16x16x32_bf16 v[104:107], v[156:159], v[188:191], v[104:107]
	v_mfma_f32_16x16x32_bf16 v[124:127], v[136:139], v[176:179], v[124:127]
	v_mfma_f32_16x16x32_bf16 v[120:123], v[162:165], v[176:179], v[120:123]
	v_mfma_f32_16x16x32_bf16 v[116:119], v[132:135], v[180:183], v[116:119]
	v_mfma_f32_16x16x32_bf16 v[112:115], v[156:159], v[180:183], v[112:115]
	v_mfma_f32_16x16x32_bf16 v[108:111], v[136:139], v[192:195], v[108:111]
	v_mfma_f32_16x16x32_bf16 v[104:107], v[162:165], v[192:195], v[104:107]
	v_mfma_f32_16x16x32_bf16 v[100:103], v[132:135], v[196:199], v[100:103]
	v_mfma_f32_16x16x32_bf16 v[96:99], v[156:159], v[196:199], v[96:99]
	v_mfma_f32_16x16x32_bf16 v[204:207], v[136:139], v[184:187], v[116:119]
	v_mfma_f32_16x16x32_bf16 v[208:211], v[162:165], v[184:187], v[112:115]
	v_mfma_f32_16x16x32_bf16 v[212:215], v[136:139], v[200:203], v[100:103]
	v_mfma_f32_16x16x32_bf16 v[216:219], v[162:165], v[200:203], v[96:99]
	s_barrier
	s_nop 1
	ds_read_b128 v[96:99], v168
	ds_read_b128 v[100:103], v168 offset:1024
	ds_read_b128 v[112:115], v168 offset:2048
	ds_read_b128 v[116:119], v168 offset:3072
	s_barrier
	s_waitcnt lgkmcnt(0)
	s_waitcnt lgkmcnt(0)
	v_mfma_f32_16x16x32_bf16 v[92:95], v[96:99], v[172:175], v[92:95]
	v_mfma_f32_16x16x32_bf16 v[88:91], v[112:115], v[172:175], v[88:91]
	v_mfma_f32_16x16x32_bf16 v[76:79], v[96:99], v[188:191], v[76:79]
	v_mfma_f32_16x16x32_bf16 v[72:75], v[112:115], v[188:191], v[72:75]
	v_mfma_f32_16x16x32_bf16 v[92:95], v[100:103], v[176:179], v[92:95]
	v_mfma_f32_16x16x32_bf16 v[88:91], v[116:119], v[176:179], v[88:91]
	v_mfma_f32_16x16x32_bf16 v[84:87], v[96:99], v[180:183], v[84:87]
	v_mfma_f32_16x16x32_bf16 v[80:83], v[112:115], v[180:183], v[80:83]
	v_mfma_f32_16x16x32_bf16 v[76:79], v[100:103], v[192:195], v[76:79]
	v_mfma_f32_16x16x32_bf16 v[72:75], v[116:119], v[192:195], v[72:75]
	v_mfma_f32_16x16x32_bf16 v[68:71], v[96:99], v[196:199], v[68:71]
	v_mfma_f32_16x16x32_bf16 v[64:67], v[112:115], v[196:199], v[64:67]
	v_mfma_f32_16x16x32_bf16 v[166:169], v[100:103], v[184:187], v[84:87]
	v_mfma_f32_16x16x32_bf16 v[170:173], v[116:119], v[184:187], v[80:83]
	v_mfma_f32_16x16x32_bf16 v[174:177], v[100:103], v[200:203], v[68:71]
	v_mfma_f32_16x16x32_bf16 v[178:181], v[116:119], v[200:203], v[64:67]
	s_barrier
	s_nop 1
	ds_read_b128 v[64:67], v151 offset:16384
	ds_read_b128 v[68:71], v151 offset:17408
	ds_read_b128 v[80:83], v150 offset:16384
	ds_read_b128 v[84:87], v150 offset:17408
	ds_read_b128 v[182:185], v145 offset:16384
	ds_read_b128 v[186:189], v145 offset:17408
	ds_read_b128 v[190:193], v144 offset:16384
	ds_read_b128 v[194:197], v144 offset:17408
	s_waitcnt vmcnt(4)
	s_barrier
; #define WAIT_V(n) asm volatile("s_waitcnt vmcnt(" #n ")" ::: "memory")
; #define WAIT_L(n) asm volatile("s_waitcnt lgkmcnt(" #n ")" ::: "memory")
; #define BAR __builtin_amdgcn_s_barrier()
;     ...
;     LDB(B1, 0, 1); BAR; WAIT_L(0); MMA(0, 1, At, B1); BAR;
;     LDA(At, 0, 1); WAIT_V(4); BAR; WAIT_L(0); MMA(1, 0, At, B0); MMA(1, 1, At, B1); BAR; }
;   { LDB(B0, 1, 0); LDA(At, 1, 0); WAIT_V(2); BAR; WAIT_L(0); MMA(0, 0, At, B0); BAR;
	s_waitcnt lgkmcnt(0)
	s_waitcnt lgkmcnt(0)
	v_mfma_f32_16x16x32_bf16 v[60:63], v[132:135], v[64:67], v[60:63]
	v_mfma_f32_16x16x32_bf16 v[56:59], v[156:159], v[64:67], v[56:59]
	v_mfma_f32_16x16x32_bf16 v[44:47], v[132:135], v[182:185], v[44:47]
	v_mfma_f32_16x16x32_bf16 v[40:43], v[156:159], v[182:185], v[40:43]
	v_mfma_f32_16x16x32_bf16 v[60:63], v[136:139], v[68:71], v[60:63]
	v_mfma_f32_16x16x32_bf16 v[56:59], v[162:165], v[68:71], v[56:59]
	v_mfma_f32_16x16x32_bf16 v[52:55], v[132:135], v[80:83], v[52:55]
	v_mfma_f32_16x16x32_bf16 v[48:51], v[156:159], v[80:83], v[48:51]
	v_mfma_f32_16x16x32_bf16 v[44:47], v[136:139], v[186:189], v[44:47]
	v_mfma_f32_16x16x32_bf16 v[40:43], v[162:165], v[186:189], v[40:43]
	v_mfma_f32_16x16x32_bf16 v[36:39], v[132:135], v[190:193], v[36:39]
	v_mfma_f32_16x16x32_bf16 v[32:35], v[156:159], v[190:193], v[32:35]
	v_mfma_f32_16x16x32_bf16 v[198:201], v[136:139], v[84:87], v[52:55]
	v_mfma_f32_16x16x32_bf16 v[220:223], v[162:165], v[84:87], v[48:51]
	v_mfma_f32_16x16x32_bf16 v[130:133], v[136:139], v[194:197], v[36:39]
	v_mfma_f32_16x16x32_bf16 v[134:137], v[162:165], v[194:197], v[32:35]
	v_mfma_f32_16x16x32_bf16 v[28:31], v[96:99], v[64:67], v[28:31]
	v_mfma_f32_16x16x32_bf16 v[24:27], v[112:115], v[64:67], v[24:27]
	v_mfma_f32_16x16x32_bf16 v[12:15], v[96:99], v[182:185], v[12:15]
	v_mfma_f32_16x16x32_bf16 v[8:11], v[112:115], v[182:185], v[8:11]
	v_mfma_f32_16x16x32_bf16 v[28:31], v[100:103], v[68:71], v[28:31]
	v_mfma_f32_16x16x32_bf16 v[24:27], v[116:119], v[68:71], v[24:27]
	v_mfma_f32_16x16x32_bf16 v[20:23], v[96:99], v[80:83], v[20:23]
	v_mfma_f32_16x16x32_bf16 v[16:19], v[112:115], v[80:83], v[16:19]
	v_mfma_f32_16x16x32_bf16 v[12:15], v[100:103], v[186:189], v[12:15]
	v_mfma_f32_16x16x32_bf16 v[8:11], v[116:119], v[186:189], v[8:11]
	v_mfma_f32_16x16x32_bf16 v[4:7], v[96:99], v[190:193], v[4:7]
	v_mfma_f32_16x16x32_bf16 v[0:3], v[112:115], v[190:193], v[0:3]
	v_mfma_f32_16x16x32_bf16 v[156:159], v[100:103], v[84:87], v[20:23]
	v_mfma_f32_16x16x32_bf16 v[162:165], v[116:119], v[84:87], v[16:19]
	v_mfma_f32_16x16x32_bf16 v[182:185], v[100:103], v[194:197], v[4:7]
	v_mfma_f32_16x16x32_bf16 v[186:189], v[116:119], v[194:197], v[0:3]
	s_barrier
	s_nop 1
	ds_read_b128 v[0:3], v160
	ds_read_b128 v[4:7], v160 offset:1024
	ds_read_b128 v[190:193], v160 offset:2048
	ds_read_b128 v[194:197], v160 offset:3072
	ds_read_b128 v[16:19], v151 offset:32768
	ds_read_b128 v[20:23], v151 offset:33792
	ds_read_b128 v[32:35], v150 offset:32768
	ds_read_b128 v[36:39], v150 offset:33792
	ds_read_b128 v[48:51], v145 offset:32768
	ds_read_b128 v[52:55], v145 offset:33792
	ds_read_b128 v[224:227], v144 offset:32768
	ds_read_b128 v[228:231], v144 offset:33792
	s_waitcnt vmcnt(2)
	s_barrier
	s_waitcnt lgkmcnt(0)
	s_waitcnt lgkmcnt(0)
	v_mfma_f32_16x16x32_bf16 v[64:67], v[0:3], v[16:19], v[124:127]
	v_mfma_f32_16x16x32_bf16 v[112:115], v[4:7], v[20:23], v[64:67]
	v_mfma_f32_16x16x32_bf16 v[64:67], v[190:193], v[16:19], v[120:123]
	v_mfma_f32_16x16x32_bf16 v[116:119], v[194:197], v[20:23], v[64:67]
	v_mfma_f32_16x16x32_bf16 v[64:67], v[0:3], v[32:35], v[204:207]
	v_mfma_f32_16x16x32_bf16 v[96:99], v[4:7], v[36:39], v[64:67]
	v_mfma_f32_16x16x32_bf16 v[64:67], v[190:193], v[32:35], v[208:211]
	v_mfma_f32_16x16x32_bf16 v[100:103], v[194:197], v[36:39], v[64:67]
	v_mfma_f32_16x16x32_bf16 v[64:67], v[0:3], v[48:51], v[108:111]
	v_mfma_f32_16x16x32_bf16 v[80:83], v[4:7], v[52:55], v[64:67]
	v_mfma_f32_16x16x32_bf16 v[64:67], v[190:193], v[48:51], v[104:107]
	v_mfma_f32_16x16x32_bf16 v[84:87], v[194:197], v[52:55], v[64:67]
	v_mfma_f32_16x16x32_bf16 v[64:67], v[0:3], v[224:227], v[212:215]
	v_mfma_f32_16x16x32_bf16 v[68:71], v[190:193], v[224:227], v[216:219]
	v_mfma_f32_16x16x32_bf16 v[64:67], v[4:7], v[228:231], v[64:67]
	v_mfma_f32_16x16x32_bf16 v[68:71], v[194:197], v[228:231], v[68:71]
	s_barrier
; #define WAIT_V(n) asm volatile("s_waitcnt vmcnt(" #n ")" ::: "memory")
; #define WAIT_L(n) asm volatile("s_waitcnt lgkmcnt(" #n ")" ::: "memory")
; #define BAR __builtin_amdgcn_s_barrier()
;     ...
;   { LDB(B0, 1, 0); LDA(At, 1, 0); WAIT_V(2); BAR; WAIT_L(0); MMA(0, 0, At, B0); BAR;
;     LDB(B1, 1, 1); WAIT_V(0); BAR; WAIT_L(0); MMA(0, 1, At, B1); BAR;
;     LDA(At, 1, 1); BAR; WAIT_L(0); MMA(1, 0, At, B0); MMA(1, 1, At, B1); BAR; }
;   if (wr == 0) BAR;
	ds_read_b128 v[202:205], v154
	ds_read_b128 v[206:209], v154 offset:1024
	ds_read_b128 v[210:213], v154 offset:2048
	ds_read_b128 v[152:155], v154 offset:3072
	s_waitcnt vmcnt(0)
	s_barrier
	s_waitcnt lgkmcnt(0)
	s_waitcnt lgkmcnt(0)
	v_mfma_f32_16x16x32_bf16 v[92:95], v[202:205], v[16:19], v[92:95]
	v_mfma_f32_16x16x32_bf16 v[16:19], v[210:213], v[16:19], v[88:91]
	v_mfma_f32_16x16x32_bf16 v[120:123], v[152:155], v[20:23], v[16:19]
	v_mfma_f32_16x16x32_bf16 v[16:19], v[202:205], v[32:35], v[166:169]
	v_mfma_f32_16x16x32_bf16 v[108:111], v[206:209], v[36:39], v[16:19]
	v_mfma_f32_16x16x32_bf16 v[16:19], v[210:213], v[32:35], v[170:173]
	v_mfma_f32_16x16x32_bf16 v[104:107], v[152:155], v[36:39], v[16:19]
	v_mfma_f32_16x16x32_bf16 v[16:19], v[202:205], v[48:51], v[76:79]
	v_mfma_f32_16x16x32_bf16 v[124:127], v[206:209], v[20:23], v[92:95]
	v_mfma_f32_16x16x32_bf16 v[92:95], v[206:209], v[52:55], v[16:19]
	v_mfma_f32_16x16x32_bf16 v[16:19], v[210:213], v[48:51], v[72:75]
	v_mfma_f32_16x16x32_bf16 v[88:91], v[152:155], v[52:55], v[16:19]
	v_mfma_f32_16x16x32_bf16 v[16:19], v[202:205], v[224:227], v[174:177]
	v_mfma_f32_16x16x32_bf16 v[76:79], v[206:209], v[228:231], v[16:19]
	v_mfma_f32_16x16x32_bf16 v[16:19], v[210:213], v[224:227], v[178:181]
	v_mfma_f32_16x16x32_bf16 v[72:75], v[152:155], v[228:231], v[16:19]
	s_barrier
	ds_read_b128 v[166:169], v151 offset:49152
	ds_read_b128 v[170:173], v151 offset:50176
	ds_read_b128 v[174:177], v150 offset:49152
	ds_read_b128 v[178:181], v150 offset:50176
	ds_read_b128 v[214:217], v145 offset:49152
	ds_read_b128 v[224:227], v145 offset:50176
	ds_read_b128 v[228:231], v144 offset:49152
	ds_read_b128 v[232:235], v144 offset:50176
	s_barrier
	s_waitcnt lgkmcnt(0)
	s_waitcnt lgkmcnt(0)
	v_mfma_f32_16x16x32_bf16 v[16:19], v[0:3], v[166:169], v[60:63]
	v_mfma_f32_16x16x32_bf16 v[48:51], v[4:7], v[170:173], v[16:19]
	v_mfma_f32_16x16x32_bf16 v[16:19], v[190:193], v[166:169], v[56:59]
	v_mfma_f32_16x16x32_bf16 v[52:55], v[194:197], v[170:173], v[16:19]
	v_mfma_f32_16x16x32_bf16 v[16:19], v[0:3], v[174:177], v[198:201]
	v_mfma_f32_16x16x32_bf16 v[32:35], v[4:7], v[178:181], v[16:19]
	v_mfma_f32_16x16x32_bf16 v[16:19], v[190:193], v[174:177], v[220:223]
	v_mfma_f32_16x16x32_bf16 v[36:39], v[194:197], v[178:181], v[16:19]
	v_mfma_f32_16x16x32_bf16 v[16:19], v[0:3], v[214:217], v[44:47]
	v_mfma_f32_16x16x32_bf16 v[0:3], v[0:3], v[228:231], v[130:133]
	v_mfma_f32_16x16x32_bf16 v[16:19], v[4:7], v[224:227], v[16:19]
	v_mfma_f32_16x16x32_bf16 v[20:23], v[190:193], v[214:217], v[40:43]
	v_mfma_f32_16x16x32_bf16 v[0:3], v[4:7], v[232:235], v[0:3]
	v_mfma_f32_16x16x32_bf16 v[4:7], v[190:193], v[228:231], v[134:137]
	v_mfma_f32_16x16x32_bf16 v[20:23], v[194:197], v[224:227], v[20:23]
	v_mfma_f32_16x16x32_bf16 v[4:7], v[194:197], v[232:235], v[4:7]
	v_mfma_f32_16x16x32_bf16 v[24:27], v[210:213], v[166:169], v[24:27]
	v_mfma_f32_16x16x32_bf16 v[56:59], v[152:155], v[170:173], v[24:27]
	v_mfma_f32_16x16x32_bf16 v[24:27], v[202:205], v[174:177], v[156:159]
	v_mfma_f32_16x16x32_bf16 v[44:47], v[206:209], v[178:181], v[24:27]
	v_mfma_f32_16x16x32_bf16 v[24:27], v[210:213], v[174:177], v[162:165]
	v_mfma_f32_16x16x32_bf16 v[8:11], v[210:213], v[214:217], v[8:11]
	v_mfma_f32_16x16x32_bf16 v[28:31], v[202:205], v[166:169], v[28:31]
	v_mfma_f32_16x16x32_bf16 v[40:43], v[152:155], v[178:181], v[24:27]
	v_mfma_f32_16x16x32_bf16 v[12:15], v[202:205], v[214:217], v[12:15]
	v_mfma_f32_16x16x32_bf16 v[24:27], v[152:155], v[224:227], v[8:11]
	v_mfma_f32_16x16x32_bf16 v[8:11], v[202:205], v[228:231], v[182:185]
	v_mfma_f32_16x16x32_bf16 v[60:63], v[206:209], v[170:173], v[28:31]
	v_mfma_f32_16x16x32_bf16 v[28:31], v[206:209], v[224:227], v[12:15]
	v_mfma_f32_16x16x32_bf16 v[12:15], v[206:209], v[232:235], v[8:11]
	v_mfma_f32_16x16x32_bf16 v[8:11], v[210:213], v[228:231], v[186:189]
	v_mfma_f32_16x16x32_bf16 v[8:11], v[152:155], v[232:235], v[8:11]
	v_cmp_gt_u32_e32 vcc, s30, v148
	s_barrier
	s_and_saveexec_b64 s[4:5], vcc
	s_cbranch_execz .LBB0_1338
	s_barrier
